# same as previous plus s_nop 0 restored where an m0 write became adjacent to its LDS-DMA load (hazard fix)
# baseline (speedup 1.0000x reference)
.LBB0_139:
	v_add_u32_e32 v253, 0x10000, v146
	ds_read_b128 v[140:143], v253
	ds_read_b128 v[150:153], v253 offset:1024
	ds_read_b128 v[154:157], v253 offset:2048
	ds_read_b128 v[158:161], v253 offset:3072
	s_add_u32 s10, s6, 0xfff80080
	s_addc_u32 s11, s7, -1
	s_cmp_eq_u32 s41, 28
	s_cselect_b32 s11, s63, s11
	s_cselect_b32 s10, s62, s10
	s_cselect_b32 s53, s61, s29
	s_cselect_b32 s52, s60, s28
	s_mov_b32 m0, s12
	ds_read_b128 v[162:165], v145
	ds_read_b128 v[166:169], v145 offset:1024
	ds_read_b128 v[170:173], v145 offset:2048
	ds_read_b128 v[174:177], v145 offset:3072
	ds_read_b128 v[178:181], v145 offset:4096
	ds_read_b128 v[182:185], v145 offset:5120
	ds_read_b128 v[186:189], v145 offset:6144
	ds_read_b128 v[190:193], v145 offset:7168
	global_load_lds_dwordx4 v136, s[6:7]
	s_mov_b32 m0, s78
	s_nop 0
	global_load_lds_dwordx4 v138, s[6:7]
	s_waitcnt lgkmcnt(8)
	s_setprio 1
	s_barrier
	s_waitcnt lgkmcnt(0)
	v_mfma_f32_16x16x32_bf16 v[126:129], v[140:143], v[162:165], v[126:129]
	v_mfma_f32_16x16x32_bf16 v[122:125], v[154:157], v[162:165], v[122:125]
	v_mfma_f32_16x16x32_bf16 v[118:121], v[140:143], v[170:173], v[118:121]
	v_mfma_f32_16x16x32_bf16 v[110:113], v[154:157], v[170:173], v[110:113]
	v_mfma_f32_16x16x32_bf16 v[102:105], v[140:143], v[178:181], v[102:105]
	v_mfma_f32_16x16x32_bf16 v[94:97], v[154:157], v[178:181], v[94:97]
	v_mfma_f32_16x16x32_bf16 v[86:89], v[140:143], v[186:189], v[86:89]
	v_mfma_f32_16x16x32_bf16 v[78:81], v[154:157], v[186:189], v[78:81]
	v_mfma_f32_16x16x32_bf16 v[126:129], v[150:153], v[166:169], v[126:129]
	v_mfma_f32_16x16x32_bf16 v[122:125], v[158:161], v[166:169], v[122:125]
	v_mfma_f32_16x16x32_bf16 v[118:121], v[150:153], v[174:177], v[118:121]
	v_mfma_f32_16x16x32_bf16 v[110:113], v[158:161], v[174:177], v[110:113]
	v_mfma_f32_16x16x32_bf16 v[102:105], v[150:153], v[182:185], v[102:105]
	v_mfma_f32_16x16x32_bf16 v[94:97], v[158:161], v[182:185], v[94:97]
	v_mfma_f32_16x16x32_bf16 v[86:89], v[150:153], v[190:193], v[86:89]
	v_mfma_f32_16x16x32_bf16 v[78:81], v[158:161], v[190:193], v[78:81]
	s_barrier
	s_setprio 0
	s_mov_b32 m0, s83
	ds_read_b128 v[206:209], v253 offset:16384
	ds_read_b128 v[210:213], v253 offset:17408
	v_lshl_add_u64 v[222:223], s[52:53], 0, v[194:195]
	ds_read_b128 v[214:217], v253 offset:18432
	ds_read_b128 v[218:221], v253 offset:19456
	global_load_lds_dwordx4 v[222:223], off
	v_lshl_add_u64 v[224:225], s[52:53], 0, v[134:135]
	s_mov_b32 m0, s54
	s_nop 0
	global_load_lds_dwordx4 v[224:225], off
	s_setprio 1
	s_barrier
	s_waitcnt lgkmcnt(0)
	v_mfma_f32_16x16x32_bf16 v[114:117], v[206:209], v[162:165], v[114:117]
	v_mfma_f32_16x16x32_bf16 v[106:109], v[214:217], v[162:165], v[106:109]
	v_mfma_f32_16x16x32_bf16 v[98:101], v[206:209], v[170:173], v[98:101]
	v_mfma_f32_16x16x32_bf16 v[90:93], v[214:217], v[170:173], v[90:93]
	v_mfma_f32_16x16x32_bf16 v[82:85], v[206:209], v[178:181], v[82:85]
	v_mfma_f32_16x16x32_bf16 v[74:77], v[214:217], v[178:181], v[74:77]
	v_mfma_f32_16x16x32_bf16 v[70:73], v[206:209], v[186:189], v[70:73]
	v_mfma_f32_16x16x32_bf16 v[66:69], v[214:217], v[186:189], v[66:69]
	v_mfma_f32_16x16x32_bf16 v[114:117], v[210:213], v[166:169], v[114:117]
	v_mfma_f32_16x16x32_bf16 v[106:109], v[218:221], v[166:169], v[106:109]
	v_mfma_f32_16x16x32_bf16 v[98:101], v[210:213], v[174:177], v[98:101]
	v_mfma_f32_16x16x32_bf16 v[90:93], v[218:221], v[174:177], v[90:93]
	v_mfma_f32_16x16x32_bf16 v[82:85], v[210:213], v[182:185], v[82:85]
	v_mfma_f32_16x16x32_bf16 v[74:77], v[218:221], v[182:185], v[74:77]
	s_mov_b32 m0, s55
	v_mfma_f32_16x16x32_bf16 v[70:73], v[210:213], v[190:193], v[70:73]
	v_lshl_add_u64 v[226:227], s[10:11], 0, v[130:131]
	v_mfma_f32_16x16x32_bf16 v[66:69], v[218:221], v[190:193], v[66:69]
	s_barrier
	s_setprio 0
	ds_read_b128 v[162:165], v145 offset:16384
	ds_read_b128 v[166:169], v145 offset:17408
	ds_read_b128 v[170:173], v145 offset:18432
	ds_read_b128 v[174:177], v145 offset:19456
	ds_read_b128 v[178:181], v145 offset:20480
	ds_read_b128 v[182:185], v145 offset:21504
	ds_read_b128 v[186:189], v145 offset:22528
	ds_read_b128 v[190:193], v145 offset:23552
	global_load_lds_dwordx4 v[226:227], off
	v_lshl_add_u64 v[228:229], s[10:11], 0, v[132:133]
	s_mov_b32 m0, s34
	s_nop 0
	global_load_lds_dwordx4 v[228:229], off
	s_setprio 1
	s_barrier
	s_waitcnt lgkmcnt(0)
	v_mfma_f32_16x16x32_bf16 v[62:65], v[140:143], v[162:165], v[62:65]
	v_mfma_f32_16x16x32_bf16 v[58:61], v[154:157], v[162:165], v[58:61]
	v_mfma_f32_16x16x32_bf16 v[54:57], v[140:143], v[170:173], v[54:57]
	v_mfma_f32_16x16x32_bf16 v[46:49], v[154:157], v[170:173], v[46:49]
	v_mfma_f32_16x16x32_bf16 v[38:41], v[140:143], v[178:181], v[38:41]
	v_mfma_f32_16x16x32_bf16 v[30:33], v[154:157], v[178:181], v[30:33]
	v_mfma_f32_16x16x32_bf16 v[22:25], v[140:143], v[186:189], v[22:25]
	v_mfma_f32_16x16x32_bf16 v[14:17], v[154:157], v[186:189], v[14:17]
	v_mfma_f32_16x16x32_bf16 v[62:65], v[150:153], v[166:169], v[62:65]
	v_mfma_f32_16x16x32_bf16 v[58:61], v[158:161], v[166:169], v[58:61]
	v_mfma_f32_16x16x32_bf16 v[54:57], v[150:153], v[174:177], v[54:57]
	v_mfma_f32_16x16x32_bf16 v[46:49], v[158:161], v[174:177], v[46:49]
	v_mfma_f32_16x16x32_bf16 v[38:41], v[150:153], v[182:185], v[38:41]
	v_mfma_f32_16x16x32_bf16 v[30:33], v[158:161], v[182:185], v[30:33]
	v_mfma_f32_16x16x32_bf16 v[22:25], v[150:153], v[190:193], v[22:25]
	v_mfma_f32_16x16x32_bf16 v[14:17], v[158:161], v[190:193], v[14:17]
	s_barrier
	s_setprio 0
	s_add_u32 s58, s52, 0x80000
	s_addc_u32 s59, s53, 0
	s_mov_b32 m0, s4
	s_nop 0
	global_load_lds_dwordx4 v194, s[58:59]
	s_mov_b32 m0, s5
	s_nop 0
	global_load_lds_dwordx4 v134, s[58:59]
	s_waitcnt vmcnt(6)
	s_setprio 1
	s_barrier
	v_mfma_f32_16x16x32_bf16 v[50:53], v[206:209], v[162:165], v[50:53]
	v_mfma_f32_16x16x32_bf16 v[42:45], v[214:217], v[162:165], v[42:45]
	v_mfma_f32_16x16x32_bf16 v[34:37], v[206:209], v[170:173], v[34:37]
	v_mfma_f32_16x16x32_bf16 v[26:29], v[214:217], v[170:173], v[26:29]
	v_mfma_f32_16x16x32_bf16 v[18:21], v[206:209], v[178:181], v[18:21]
	v_mfma_f32_16x16x32_bf16 v[10:13], v[214:217], v[178:181], v[10:13]
	v_mfma_f32_16x16x32_bf16 v[6:9], v[206:209], v[186:189], v[6:9]
	v_mfma_f32_16x16x32_bf16 v[2:5], v[214:217], v[186:189], v[2:5]
	v_mfma_f32_16x16x32_bf16 v[50:53], v[210:213], v[166:169], v[50:53]
	v_mfma_f32_16x16x32_bf16 v[42:45], v[218:221], v[166:169], v[42:45]
	v_mfma_f32_16x16x32_bf16 v[34:37], v[210:213], v[174:177], v[34:37]
	v_mfma_f32_16x16x32_bf16 v[26:29], v[218:221], v[174:177], v[26:29]
	v_mfma_f32_16x16x32_bf16 v[18:21], v[210:213], v[182:185], v[18:21]
	v_mfma_f32_16x16x32_bf16 v[10:13], v[218:221], v[182:185], v[10:13]
	v_mfma_f32_16x16x32_bf16 v[6:9], v[210:213], v[190:193], v[6:9]
	v_mfma_f32_16x16x32_bf16 v[2:5], v[218:221], v[190:193], v[2:5]
	s_barrier
	s_setprio 0
	ds_read_b128 v[140:143], v253 offset:32768
	ds_read_b128 v[150:153], v253 offset:33792
	ds_read_b128 v[154:157], v253 offset:34816
	ds_read_b128 v[158:161], v253 offset:35840
	s_add_u32 s10, s10, 0x80000
	s_addc_u32 s11, s11, 0
	s_mov_b32 m0, s56
	ds_read_b128 v[162:165], v145 offset:32768
	ds_read_b128 v[166:169], v145 offset:33792
	ds_read_b128 v[170:173], v145 offset:34816
	ds_read_b128 v[174:177], v145 offset:35840
	ds_read_b128 v[178:181], v145 offset:36864
	ds_read_b128 v[182:185], v145 offset:37888
	ds_read_b128 v[186:189], v145 offset:38912
	ds_read_b128 v[190:193], v145 offset:39936
	global_load_lds_dwordx4 v130, s[10:11]
	s_mov_b32 m0, s57
	s_nop 0
	global_load_lds_dwordx4 v132, s[10:11]
	s_waitcnt lgkmcnt(8)
	s_setprio 1
	s_barrier
	s_waitcnt lgkmcnt(0)
	v_mfma_f32_16x16x32_bf16 v[126:129], v[140:143], v[162:165], v[126:129]
	v_mfma_f32_16x16x32_bf16 v[122:125], v[154:157], v[162:165], v[122:125]
	v_mfma_f32_16x16x32_bf16 v[118:121], v[140:143], v[170:173], v[118:121]
	v_mfma_f32_16x16x32_bf16 v[110:113], v[154:157], v[170:173], v[110:113]
	v_mfma_f32_16x16x32_bf16 v[102:105], v[140:143], v[178:181], v[102:105]
	v_mfma_f32_16x16x32_bf16 v[94:97], v[154:157], v[178:181], v[94:97]
	v_mfma_f32_16x16x32_bf16 v[86:89], v[140:143], v[186:189], v[86:89]
	v_mfma_f32_16x16x32_bf16 v[78:81], v[154:157], v[186:189], v[78:81]
	v_mfma_f32_16x16x32_bf16 v[126:129], v[150:153], v[166:169], v[126:129]
	v_mfma_f32_16x16x32_bf16 v[122:125], v[158:161], v[166:169], v[122:125]
	v_mfma_f32_16x16x32_bf16 v[118:121], v[150:153], v[174:177], v[118:121]
	v_mfma_f32_16x16x32_bf16 v[110:113], v[158:161], v[174:177], v[110:113]
	v_mfma_f32_16x16x32_bf16 v[102:105], v[150:153], v[182:185], v[102:105]
	v_mfma_f32_16x16x32_bf16 v[94:97], v[158:161], v[182:185], v[94:97]
	v_mfma_f32_16x16x32_bf16 v[86:89], v[150:153], v[190:193], v[86:89]
	v_mfma_f32_16x16x32_bf16 v[78:81], v[158:161], v[190:193], v[78:81]
	s_barrier
	s_setprio 0
	s_mov_b32 m0, s70
	ds_read_b128 v[206:209], v253 offset:49152
	ds_read_b128 v[210:213], v253 offset:50176
	v_lshl_add_u64 v[222:223], v[222:223], 0, s[76:77]
	ds_read_b128 v[214:217], v253 offset:51200
	ds_read_b128 v[218:221], v253 offset:52224
	global_load_lds_dwordx4 v[222:223], off
	v_lshl_add_u64 v[222:223], v[224:225], 0, s[76:77]
	s_mov_b32 m0, s71
	s_nop 0
	global_load_lds_dwordx4 v[222:223], off
	s_setprio 1
	s_barrier
	s_waitcnt lgkmcnt(0)
	v_mfma_f32_16x16x32_bf16 v[114:117], v[206:209], v[162:165], v[114:117]
	v_mfma_f32_16x16x32_bf16 v[106:109], v[214:217], v[162:165], v[106:109]
	v_mfma_f32_16x16x32_bf16 v[98:101], v[206:209], v[170:173], v[98:101]
	v_mfma_f32_16x16x32_bf16 v[90:93], v[214:217], v[170:173], v[90:93]
	v_mfma_f32_16x16x32_bf16 v[82:85], v[206:209], v[178:181], v[82:85]
	v_mfma_f32_16x16x32_bf16 v[74:77], v[214:217], v[178:181], v[74:77]
	v_mfma_f32_16x16x32_bf16 v[70:73], v[206:209], v[186:189], v[70:73]
	v_mfma_f32_16x16x32_bf16 v[66:69], v[214:217], v[186:189], v[66:69]
	v_mfma_f32_16x16x32_bf16 v[114:117], v[210:213], v[166:169], v[114:117]
	v_mfma_f32_16x16x32_bf16 v[106:109], v[218:221], v[166:169], v[106:109]
	v_mfma_f32_16x16x32_bf16 v[98:101], v[210:213], v[174:177], v[98:101]
	v_mfma_f32_16x16x32_bf16 v[90:93], v[218:221], v[174:177], v[90:93]
	v_mfma_f32_16x16x32_bf16 v[82:85], v[210:213], v[182:185], v[82:85]
	v_mfma_f32_16x16x32_bf16 v[74:77], v[218:221], v[182:185], v[74:77]
	s_mov_b32 m0, s33
	v_mfma_f32_16x16x32_bf16 v[70:73], v[210:213], v[190:193], v[70:73]
	v_lshl_add_u64 v[222:223], v[226:227], 0, s[76:77]
	v_mfma_f32_16x16x32_bf16 v[66:69], v[218:221], v[190:193], v[66:69]
	s_barrier
	s_setprio 0
	ds_read_b128 v[162:165], v145 offset:49152
	ds_read_b128 v[166:169], v145 offset:50176
	ds_read_b128 v[170:173], v145 offset:51200
	ds_read_b128 v[174:177], v145 offset:52224
	ds_read_b128 v[178:181], v145 offset:53248
	ds_read_b128 v[182:185], v145 offset:54272
	ds_read_b128 v[186:189], v145 offset:55296
	ds_read_b128 v[190:193], v145 offset:56320
	global_load_lds_dwordx4 v[222:223], off
	v_lshl_add_u64 v[222:223], v[228:229], 0, s[76:77]
	s_mov_b32 m0, s35
	s_nop 0
	global_load_lds_dwordx4 v[222:223], off
	s_setprio 1
	s_barrier
	s_waitcnt lgkmcnt(0)
	v_mfma_f32_16x16x32_bf16 v[62:65], v[140:143], v[162:165], v[62:65]
	v_mfma_f32_16x16x32_bf16 v[58:61], v[154:157], v[162:165], v[58:61]
	v_mfma_f32_16x16x32_bf16 v[54:57], v[140:143], v[170:173], v[54:57]
	v_mfma_f32_16x16x32_bf16 v[46:49], v[154:157], v[170:173], v[46:49]
	v_mfma_f32_16x16x32_bf16 v[38:41], v[140:143], v[178:181], v[38:41]
	v_mfma_f32_16x16x32_bf16 v[30:33], v[154:157], v[178:181], v[30:33]
	v_mfma_f32_16x16x32_bf16 v[22:25], v[140:143], v[186:189], v[22:25]
	v_mfma_f32_16x16x32_bf16 v[14:17], v[154:157], v[186:189], v[14:17]
	v_mfma_f32_16x16x32_bf16 v[62:65], v[150:153], v[166:169], v[62:65]
	v_mfma_f32_16x16x32_bf16 v[58:61], v[158:161], v[166:169], v[58:61]
	v_mfma_f32_16x16x32_bf16 v[54:57], v[150:153], v[174:177], v[54:57]
	v_mfma_f32_16x16x32_bf16 v[46:49], v[158:161], v[174:177], v[46:49]
	v_mfma_f32_16x16x32_bf16 v[38:41], v[150:153], v[182:185], v[38:41]
	v_mfma_f32_16x16x32_bf16 v[30:33], v[158:161], v[182:185], v[30:33]
	v_mfma_f32_16x16x32_bf16 v[22:25], v[150:153], v[190:193], v[22:25]
	v_mfma_f32_16x16x32_bf16 v[14:17], v[158:161], v[190:193], v[14:17]
	s_barrier
	s_setprio 0
	s_add_u32 s10, s52, 0x80080
	s_addc_u32 s11, s53, 0
	s_mov_b32 m0, s67
	s_nop 0
	global_load_lds_dwordx4 v194, s[10:11]
	s_mov_b32 m0, s17
	s_nop 0
	global_load_lds_dwordx4 v134, s[10:11]
	s_waitcnt vmcnt(6)
	s_setprio 1
	s_barrier
	v_mfma_f32_16x16x32_bf16 v[50:53], v[206:209], v[162:165], v[50:53]
	v_mfma_f32_16x16x32_bf16 v[42:45], v[214:217], v[162:165], v[42:45]
	v_mfma_f32_16x16x32_bf16 v[34:37], v[206:209], v[170:173], v[34:37]
	v_mfma_f32_16x16x32_bf16 v[26:29], v[214:217], v[170:173], v[26:29]
	v_mfma_f32_16x16x32_bf16 v[18:21], v[206:209], v[178:181], v[18:21]
	v_mfma_f32_16x16x32_bf16 v[10:13], v[214:217], v[178:181], v[10:13]
	v_mfma_f32_16x16x32_bf16 v[6:9], v[206:209], v[186:189], v[6:9]
	v_mfma_f32_16x16x32_bf16 v[2:5], v[214:217], v[186:189], v[2:5]
	v_mfma_f32_16x16x32_bf16 v[50:53], v[210:213], v[166:169], v[50:53]
	v_mfma_f32_16x16x32_bf16 v[42:45], v[218:221], v[166:169], v[42:45]
	v_mfma_f32_16x16x32_bf16 v[34:37], v[210:213], v[174:177], v[34:37]
	v_mfma_f32_16x16x32_bf16 v[26:29], v[218:221], v[174:177], v[26:29]
	v_mfma_f32_16x16x32_bf16 v[18:21], v[210:213], v[182:185], v[18:21]
	v_mfma_f32_16x16x32_bf16 v[10:13], v[218:221], v[182:185], v[10:13]
	v_mfma_f32_16x16x32_bf16 v[6:9], v[210:213], v[190:193], v[6:9]
	v_mfma_f32_16x16x32_bf16 v[2:5], v[218:221], v[190:193], v[2:5]
	s_setprio 0
	s_add_i32 s41, s41, 2
	s_add_u32 s6, s6, 0x100
	s_addc_u32 s7, s7, 0
	s_add_u32 s28, s28, 0x100
	s_addc_u32 s29, s29, 0
	s_cmp_gt_u32 s41, 29
	s_barrier
	s_cbranch_scc0 .LBB0_139
	s_cmp_gt_i32 s79, 3
	s_mov_b64 s[6:7], -1
	s_cbranch_scc0 .LBB0_146
	s_lshl_b32 s10, s82, 8
	v_lshl_or_b32 v140, s80, 8, v149
	s_cmp_lg_u32 s79, 4
	v_ashrrev_i32_e32 v141, 31, v140
	s_cbranch_scc0 .LBB0_143
	v_readlane_b32 s6, v252, 55
	v_readlane_b32 s7, v252, 56
	v_add_u32_e32 v150, s10, v147
	s_nop 0
	v_mov_b64_e32 v[142:143], s[6:7]
	s_mov_b32 s6, 0x9000
	v_mad_i64_i32 v[142:143], s[6:7], v150, s6, v[142:143]
	v_lshl_add_u64 v[142:143], v[140:141], 1, v[142:143]
	v_cvt_pk_bf16_f32 v150, v126, v127
	v_cvt_pk_bf16_f32 v151, v128, v129
	v_cvt_pk_bf16_f32 v152, v122, v123
	v_cvt_pk_bf16_f32 v153, v124, v125
	global_store_dwordx4 v[142:143], v[150:153], off
	v_add_co_u32_e32 v154, vcc, s44, v142
	s_nop 0
	v_cvt_pk_bf16_f32 v150, v114, v115
	v_cvt_pk_bf16_f32 v151, v116, v117
	v_cvt_pk_bf16_f32 v152, v106, v107
	v_cvt_pk_bf16_f32 v153, v108, v109
	global_store_dwordx4 v[142:143], v[150:153], off offset:256
	v_addc_co_u32_e32 v155, vcc, 0, v143, vcc
	s_nop 0
	v_cvt_pk_bf16_f32 v150, v118, v119
	v_cvt_pk_bf16_f32 v151, v120, v121
	v_cvt_pk_bf16_f32 v152, v110, v111
	v_cvt_pk_bf16_f32 v153, v112, v113
	global_store_dwordx4 v[154:155], v[150:153], off
	s_mov_b64 s[6:7], 0
	s_nop 0
	v_cvt_pk_bf16_f32 v150, v98, v99
	v_cvt_pk_bf16_f32 v151, v100, v101
	v_cvt_pk_bf16_f32 v152, v90, v91
	v_cvt_pk_bf16_f32 v153, v92, v93
	global_store_dwordx4 v[154:155], v[150:153], off offset:256
	v_add_co_u32_e32 v154, vcc, s45, v142
	s_nop 0
	v_cvt_pk_bf16_f32 v150, v102, v103
	v_cvt_pk_bf16_f32 v151, v104, v105
	v_cvt_pk_bf16_f32 v152, v94, v95
	v_cvt_pk_bf16_f32 v153, v96, v97
	s_nop 0
	v_addc_co_u32_e32 v155, vcc, 0, v143, vcc
	global_store_dwordx4 v[154:155], v[150:153], off
	s_nop 1
	v_cvt_pk_bf16_f32 v150, v82, v83
	v_cvt_pk_bf16_f32 v151, v84, v85
	v_cvt_pk_bf16_f32 v152, v74, v75
	v_cvt_pk_bf16_f32 v153, v76, v77
	global_store_dwordx4 v[154:155], v[150:153], off offset:256
	v_add_co_u32_e32 v154, vcc, s90, v142
	s_nop 0
	v_cvt_pk_bf16_f32 v150, v86, v87
	v_cvt_pk_bf16_f32 v151, v88, v89
	v_cvt_pk_bf16_f32 v152, v78, v79
	v_cvt_pk_bf16_f32 v153, v80, v81
	s_nop 0
	v_addc_co_u32_e32 v155, vcc, 0, v143, vcc
	global_store_dwordx4 v[154:155], v[150:153], off
	s_nop 1
	v_cvt_pk_bf16_f32 v150, v70, v71
	v_cvt_pk_bf16_f32 v151, v72, v73
	v_cvt_pk_bf16_f32 v152, v66, v67
	v_cvt_pk_bf16_f32 v153, v68, v69
	global_store_dwordx4 v[154:155], v[150:153], off offset:256
	v_add_co_u32_e32 v154, vcc, s20, v142
	s_nop 0
	v_cvt_pk_bf16_f32 v150, v62, v63
	v_cvt_pk_bf16_f32 v151, v64, v65
	v_cvt_pk_bf16_f32 v152, v58, v59
	v_cvt_pk_bf16_f32 v153, v60, v61
	s_nop 0
	v_addc_co_u32_e32 v155, vcc, 0, v143, vcc
	global_store_dwordx4 v[154:155], v[150:153], off
	s_nop 1
	v_cvt_pk_bf16_f32 v150, v50, v51
	v_cvt_pk_bf16_f32 v151, v52, v53
	v_cvt_pk_bf16_f32 v152, v42, v43
	v_cvt_pk_bf16_f32 v153, v44, v45
	global_store_dwordx4 v[154:155], v[150:153], off offset:256
	v_add_co_u32_e32 v154, vcc, s21, v142
	s_nop 0
	v_cvt_pk_bf16_f32 v150, v54, v55
	v_cvt_pk_bf16_f32 v151, v56, v57
	v_cvt_pk_bf16_f32 v152, v46, v47
	v_cvt_pk_bf16_f32 v153, v48, v49
	s_nop 0
	v_addc_co_u32_e32 v155, vcc, 0, v143, vcc
	global_store_dwordx4 v[154:155], v[150:153], off
	s_nop 1
	v_cvt_pk_bf16_f32 v150, v34, v35
	v_cvt_pk_bf16_f32 v151, v36, v37
	v_cvt_pk_bf16_f32 v152, v26, v27
	v_cvt_pk_bf16_f32 v153, v28, v29
	global_store_dwordx4 v[154:155], v[150:153], off offset:256
	v_add_co_u32_e32 v154, vcc, s22, v142
	s_nop 0
	v_cvt_pk_bf16_f32 v150, v38, v39
	v_cvt_pk_bf16_f32 v151, v40, v41
	v_cvt_pk_bf16_f32 v152, v30, v31
	v_cvt_pk_bf16_f32 v153, v32, v33
	s_nop 0
	v_addc_co_u32_e32 v155, vcc, 0, v143, vcc
	global_store_dwordx4 v[154:155], v[150:153], off
	v_add_co_u32_e32 v142, vcc, s23, v142
	s_nop 0
	v_cvt_pk_bf16_f32 v150, v18, v19
	v_cvt_pk_bf16_f32 v151, v20, v21
	v_cvt_pk_bf16_f32 v152, v10, v11
	v_cvt_pk_bf16_f32 v153, v12, v13
	global_store_dwordx4 v[154:155], v[150:153], off offset:256
	v_addc_co_u32_e32 v143, vcc, 0, v143, vcc
	s_nop 0
	v_cvt_pk_bf16_f32 v150, v22, v23
	v_cvt_pk_bf16_f32 v151, v24, v25
	v_cvt_pk_bf16_f32 v152, v14, v15
	v_cvt_pk_bf16_f32 v153, v16, v17
	global_store_dwordx4 v[142:143], v[150:153], off
	s_nop 1
	v_cvt_pk_bf16_f32 v150, v6, v7
	v_cvt_pk_bf16_f32 v151, v8, v9
	v_cvt_pk_bf16_f32 v152, v2, v3
	v_cvt_pk_bf16_f32 v153, v4, v5
	global_store_dwordx4 v[142:143], v[150:153], off offset:256

.LBB0_204:
	s_add_u32 s80, s54, s62
	s_addc_u32 s81, s55, s63
	s_add_u32 s82, s80, 0x100
	s_addc_u32 s83, s81, 0
	s_and_b64 s[10:11], s[8:9], exec
	s_cselect_b32 s83, s1, s83
	s_cselect_b32 s82, s0, s82
	s_add_u32 s10, s52, s62
	s_addc_u32 s11, s53, s63
	s_add_u32 s10, s10, 0x100
	s_addc_u32 s11, s11, 0
	s_and_b64 s[8:9], s[8:9], exec
	s_cselect_b32 vcc_hi, s7, s11
	s_cselect_b32 vcc_lo, s6, s10
	s_add_u32 s10, s80, 0x10080
	v_add_u32_e32 v253, 0x10000, v142
	s_addc_u32 s11, s81, 0
	s_add_i32 m0, s5, 0xc000
	s_add_i32 s87, s5, 0xe000
	ds_read_b128 v[144:147], v253
	s_add_u32 s80, vcc_lo, 0x340000
	ds_read_b128 v[148:151], v253 offset:1024
	s_addc_u32 s81, vcc_hi, 0
	ds_read_b128 v[152:155], v253 offset:2048
	s_add_u32 s62, s82, 0x10000
	ds_read_b128 v[156:159], v253 offset:3072
	s_addc_u32 s63, s83, 0
	s_add_u32 s8, vcc_lo, 0x340080
	s_addc_u32 s9, vcc_hi, 0
	ds_read_b128 v[160:163], v141
	ds_read_b128 v[164:167], v141 offset:1024
	ds_read_b128 v[168:171], v141 offset:2048
	ds_read_b128 v[172:175], v141 offset:3072
	ds_read_b128 v[176:179], v141 offset:4096
	ds_read_b128 v[180:183], v141 offset:5120
	ds_read_b128 v[184:187], v141 offset:6144
	ds_read_b128 v[188:191], v141 offset:7168
	global_load_lds_dwordx4 v136, s[10:11]
	s_mov_b32 m0, s87
	s_nop 0
	global_load_lds_dwordx4 v132, s[10:11]
	s_waitcnt lgkmcnt(8)
	s_setprio 1
	s_barrier
	s_waitcnt lgkmcnt(0)
	v_mfma_f32_16x16x32_bf16 v[126:129], v[144:147], v[160:163], v[126:129]
	v_mfma_f32_16x16x32_bf16 v[122:125], v[152:155], v[160:163], v[122:125]
	v_mfma_f32_16x16x32_bf16 v[118:121], v[144:147], v[168:171], v[118:121]
	v_mfma_f32_16x16x32_bf16 v[110:113], v[152:155], v[168:171], v[110:113]
	v_mfma_f32_16x16x32_bf16 v[102:105], v[144:147], v[176:179], v[102:105]
	v_mfma_f32_16x16x32_bf16 v[94:97], v[152:155], v[176:179], v[94:97]
	v_mfma_f32_16x16x32_bf16 v[86:89], v[144:147], v[184:187], v[86:89]
	v_mfma_f32_16x16x32_bf16 v[78:81], v[152:155], v[184:187], v[78:81]
	v_mfma_f32_16x16x32_bf16 v[126:129], v[148:151], v[164:167], v[126:129]
	v_mfma_f32_16x16x32_bf16 v[122:125], v[156:159], v[164:167], v[122:125]
	v_mfma_f32_16x16x32_bf16 v[118:121], v[148:151], v[172:175], v[118:121]
	v_mfma_f32_16x16x32_bf16 v[110:113], v[156:159], v[172:175], v[110:113]
	v_mfma_f32_16x16x32_bf16 v[102:105], v[148:151], v[180:183], v[102:105]
	v_mfma_f32_16x16x32_bf16 v[94:97], v[156:159], v[180:183], v[94:97]
	v_mfma_f32_16x16x32_bf16 v[86:89], v[148:151], v[188:191], v[86:89]
	v_mfma_f32_16x16x32_bf16 v[78:81], v[156:159], v[188:191], v[78:81]
	s_barrier
	s_setprio 0
	ds_read_b128 v[206:209], v253 offset:16384
	ds_read_b128 v[210:213], v253 offset:17408
	s_mov_b32 m0, s12
	ds_read_b128 v[214:217], v253 offset:18432
	ds_read_b128 v[218:221], v253 offset:19456
	v_lshl_add_u64 v[138:139], vcc, 0, v[134:135]
	global_load_lds_dwordx4 v[138:139], off
	v_lshl_add_u64 v[192:193], vcc, 0, v[130:131]
	s_mov_b32 m0, s17
	s_nop 0
	global_load_lds_dwordx4 v[192:193], off
	s_setprio 1
	s_barrier
	s_waitcnt lgkmcnt(0)
	v_mfma_f32_16x16x32_bf16 v[114:117], v[206:209], v[160:163], v[114:117]
	v_mfma_f32_16x16x32_bf16 v[106:109], v[214:217], v[160:163], v[106:109]
	v_mfma_f32_16x16x32_bf16 v[98:101], v[206:209], v[168:171], v[98:101]
	v_mfma_f32_16x16x32_bf16 v[90:93], v[214:217], v[168:171], v[90:93]
	v_mfma_f32_16x16x32_bf16 v[82:85], v[206:209], v[176:179], v[82:85]
	v_mfma_f32_16x16x32_bf16 v[74:77], v[214:217], v[176:179], v[74:77]
	v_mfma_f32_16x16x32_bf16 v[70:73], v[206:209], v[184:187], v[70:73]
	v_mfma_f32_16x16x32_bf16 v[66:69], v[214:217], v[184:187], v[66:69]
	v_mfma_f32_16x16x32_bf16 v[114:117], v[210:213], v[164:167], v[114:117]
	v_mfma_f32_16x16x32_bf16 v[106:109], v[218:221], v[164:167], v[106:109]
	v_mfma_f32_16x16x32_bf16 v[98:101], v[210:213], v[172:175], v[98:101]
	v_mfma_f32_16x16x32_bf16 v[90:93], v[218:221], v[172:175], v[90:93]
	v_mfma_f32_16x16x32_bf16 v[82:85], v[210:213], v[180:183], v[82:85]
	v_mfma_f32_16x16x32_bf16 v[74:77], v[218:221], v[180:183], v[74:77]
	s_mov_b32 m0, s5
	v_mfma_f32_16x16x32_bf16 v[70:73], v[210:213], v[188:191], v[70:73]
	v_lshl_add_u64 v[222:223], s[82:83], 0, v[136:137]
	v_mfma_f32_16x16x32_bf16 v[66:69], v[218:221], v[188:191], v[66:69]
	s_barrier
	s_setprio 0
	ds_read_b128 v[160:163], v141 offset:16384
	ds_read_b128 v[164:167], v141 offset:17408
	ds_read_b128 v[168:171], v141 offset:18432
	ds_read_b128 v[172:175], v141 offset:19456
	ds_read_b128 v[176:179], v141 offset:20480
	ds_read_b128 v[180:183], v141 offset:21504
	ds_read_b128 v[184:187], v141 offset:22528
	ds_read_b128 v[188:191], v141 offset:23552
	global_load_lds_dwordx4 v[222:223], off
	v_lshl_add_u64 v[224:225], s[82:83], 0, v[132:133]
	s_mov_b32 m0, s26
	s_nop 0
	global_load_lds_dwordx4 v[224:225], off
	s_setprio 1
	s_barrier
	s_waitcnt lgkmcnt(0)
	v_mfma_f32_16x16x32_bf16 v[62:65], v[144:147], v[160:163], v[62:65]
	v_mfma_f32_16x16x32_bf16 v[58:61], v[152:155], v[160:163], v[58:61]
	v_mfma_f32_16x16x32_bf16 v[54:57], v[144:147], v[168:171], v[54:57]
	v_mfma_f32_16x16x32_bf16 v[46:49], v[152:155], v[168:171], v[46:49]
	v_mfma_f32_16x16x32_bf16 v[38:41], v[144:147], v[176:179], v[38:41]
	v_mfma_f32_16x16x32_bf16 v[30:33], v[152:155], v[176:179], v[30:33]
	v_mfma_f32_16x16x32_bf16 v[22:25], v[144:147], v[184:187], v[22:25]
	v_mfma_f32_16x16x32_bf16 v[14:17], v[152:155], v[184:187], v[14:17]
	v_mfma_f32_16x16x32_bf16 v[62:65], v[148:151], v[164:167], v[62:65]
	v_mfma_f32_16x16x32_bf16 v[58:61], v[156:159], v[164:167], v[58:61]
	v_mfma_f32_16x16x32_bf16 v[54:57], v[148:151], v[172:175], v[54:57]
	v_mfma_f32_16x16x32_bf16 v[46:49], v[156:159], v[172:175], v[46:49]
	v_mfma_f32_16x16x32_bf16 v[38:41], v[148:151], v[180:183], v[38:41]
	v_mfma_f32_16x16x32_bf16 v[30:33], v[156:159], v[180:183], v[30:33]
	v_mfma_f32_16x16x32_bf16 v[22:25], v[148:151], v[188:191], v[22:25]
	v_mfma_f32_16x16x32_bf16 v[14:17], v[156:159], v[188:191], v[14:17]
	s_barrier
	s_setprio 0
	s_mov_b32 m0, s34
	s_nop 0
	global_load_lds_dwordx4 v134, s[80:81]
	s_mov_b32 m0, s35
	s_nop 0
	global_load_lds_dwordx4 v130, s[80:81]
	s_waitcnt vmcnt(6)
	s_setprio 1
	s_barrier
	v_mfma_f32_16x16x32_bf16 v[50:53], v[206:209], v[160:163], v[50:53]
	v_mfma_f32_16x16x32_bf16 v[42:45], v[214:217], v[160:163], v[42:45]
	v_mfma_f32_16x16x32_bf16 v[34:37], v[206:209], v[168:171], v[34:37]
	v_mfma_f32_16x16x32_bf16 v[26:29], v[214:217], v[168:171], v[26:29]
	v_mfma_f32_16x16x32_bf16 v[18:21], v[206:209], v[176:179], v[18:21]
	v_mfma_f32_16x16x32_bf16 v[10:13], v[214:217], v[176:179], v[10:13]
	v_mfma_f32_16x16x32_bf16 v[6:9], v[206:209], v[184:187], v[6:9]
	v_mfma_f32_16x16x32_bf16 v[2:5], v[214:217], v[184:187], v[2:5]
	v_mfma_f32_16x16x32_bf16 v[50:53], v[210:213], v[164:167], v[50:53]
	v_mfma_f32_16x16x32_bf16 v[42:45], v[218:221], v[164:167], v[42:45]
	v_mfma_f32_16x16x32_bf16 v[34:37], v[210:213], v[172:175], v[34:37]
	v_mfma_f32_16x16x32_bf16 v[26:29], v[218:221], v[172:175], v[26:29]
	v_mfma_f32_16x16x32_bf16 v[18:21], v[210:213], v[180:183], v[18:21]
	v_mfma_f32_16x16x32_bf16 v[10:13], v[218:221], v[180:183], v[10:13]
	v_mfma_f32_16x16x32_bf16 v[6:9], v[210:213], v[188:191], v[6:9]
	v_mfma_f32_16x16x32_bf16 v[2:5], v[218:221], v[188:191], v[2:5]
	s_barrier
	s_setprio 0
	ds_read_b128 v[144:147], v253 offset:32768
	ds_read_b128 v[148:151], v253 offset:33792
	ds_read_b128 v[152:155], v253 offset:34816
	ds_read_b128 v[156:159], v253 offset:35840
	s_mov_b32 m0, s56
	ds_read_b128 v[160:163], v141 offset:32768
	ds_read_b128 v[164:167], v141 offset:33792
	ds_read_b128 v[168:171], v141 offset:34816
	ds_read_b128 v[172:175], v141 offset:35840
	ds_read_b128 v[176:179], v141 offset:36864
	ds_read_b128 v[180:183], v141 offset:37888
	ds_read_b128 v[184:187], v141 offset:38912
	ds_read_b128 v[188:191], v141 offset:39936
	global_load_lds_dwordx4 v136, s[62:63]
	s_mov_b32 m0, s57
	s_nop 0
	global_load_lds_dwordx4 v132, s[62:63]
	s_waitcnt lgkmcnt(8)
	s_setprio 1
	s_barrier
	s_waitcnt lgkmcnt(0)
	v_mfma_f32_16x16x32_bf16 v[126:129], v[144:147], v[160:163], v[126:129]
	v_mfma_f32_16x16x32_bf16 v[122:125], v[152:155], v[160:163], v[122:125]
	v_mfma_f32_16x16x32_bf16 v[118:121], v[144:147], v[168:171], v[118:121]
	v_mfma_f32_16x16x32_bf16 v[110:113], v[152:155], v[168:171], v[110:113]
	v_mfma_f32_16x16x32_bf16 v[102:105], v[144:147], v[176:179], v[102:105]
	v_mfma_f32_16x16x32_bf16 v[94:97], v[152:155], v[176:179], v[94:97]
	v_mfma_f32_16x16x32_bf16 v[86:89], v[144:147], v[184:187], v[86:89]
	v_mfma_f32_16x16x32_bf16 v[78:81], v[152:155], v[184:187], v[78:81]
	v_mfma_f32_16x16x32_bf16 v[126:129], v[148:151], v[164:167], v[126:129]
	v_mfma_f32_16x16x32_bf16 v[122:125], v[156:159], v[164:167], v[122:125]
	v_mfma_f32_16x16x32_bf16 v[118:121], v[148:151], v[172:175], v[118:121]
	v_mfma_f32_16x16x32_bf16 v[110:113], v[156:159], v[172:175], v[110:113]
	v_mfma_f32_16x16x32_bf16 v[102:105], v[148:151], v[180:183], v[102:105]
	v_mfma_f32_16x16x32_bf16 v[94:97], v[156:159], v[180:183], v[94:97]
	v_mfma_f32_16x16x32_bf16 v[86:89], v[148:151], v[188:191], v[86:89]
	v_mfma_f32_16x16x32_bf16 v[78:81], v[156:159], v[188:191], v[78:81]
	s_barrier
	s_setprio 0
	s_mov_b32 m0, s58
	ds_read_b128 v[206:209], v253 offset:49152
	ds_read_b128 v[210:213], v253 offset:50176
	v_lshl_add_u64 v[138:139], v[138:139], 0, s[76:77]
	ds_read_b128 v[214:217], v253 offset:51200
	ds_read_b128 v[218:221], v253 offset:52224
	global_load_lds_dwordx4 v[138:139], off
	v_lshl_add_u64 v[138:139], v[192:193], 0, s[76:77]
	s_mov_b32 m0, s59
	s_nop 0
	global_load_lds_dwordx4 v[138:139], off
	s_setprio 1
	s_barrier
	s_waitcnt lgkmcnt(0)
	v_mfma_f32_16x16x32_bf16 v[114:117], v[206:209], v[160:163], v[114:117]
	v_mfma_f32_16x16x32_bf16 v[106:109], v[214:217], v[160:163], v[106:109]
	v_mfma_f32_16x16x32_bf16 v[98:101], v[206:209], v[168:171], v[98:101]
	v_mfma_f32_16x16x32_bf16 v[90:93], v[214:217], v[168:171], v[90:93]
	v_mfma_f32_16x16x32_bf16 v[82:85], v[206:209], v[176:179], v[82:85]
	v_mfma_f32_16x16x32_bf16 v[74:77], v[214:217], v[176:179], v[74:77]
	v_mfma_f32_16x16x32_bf16 v[70:73], v[206:209], v[184:187], v[70:73]
	v_mfma_f32_16x16x32_bf16 v[66:69], v[214:217], v[184:187], v[66:69]
	v_mfma_f32_16x16x32_bf16 v[114:117], v[210:213], v[164:167], v[114:117]
	v_mfma_f32_16x16x32_bf16 v[106:109], v[218:221], v[164:167], v[106:109]
	v_mfma_f32_16x16x32_bf16 v[98:101], v[210:213], v[172:175], v[98:101]
	v_mfma_f32_16x16x32_bf16 v[90:93], v[218:221], v[172:175], v[90:93]
	v_mfma_f32_16x16x32_bf16 v[82:85], v[210:213], v[180:183], v[82:85]
	v_mfma_f32_16x16x32_bf16 v[74:77], v[218:221], v[180:183], v[74:77]
	s_mov_b32 m0, s67
	v_mfma_f32_16x16x32_bf16 v[70:73], v[210:213], v[188:191], v[70:73]
	v_lshl_add_u64 v[138:139], v[222:223], 0, s[76:77]
	v_mfma_f32_16x16x32_bf16 v[66:69], v[218:221], v[188:191], v[66:69]
	s_barrier
	s_setprio 0
	ds_read_b128 v[160:163], v141 offset:49152
	ds_read_b128 v[164:167], v141 offset:50176
	ds_read_b128 v[168:171], v141 offset:51200
	ds_read_b128 v[172:175], v141 offset:52224
	ds_read_b128 v[176:179], v141 offset:53248
	ds_read_b128 v[180:183], v141 offset:54272
	ds_read_b128 v[184:187], v141 offset:55296
	ds_read_b128 v[188:191], v141 offset:56320
	global_load_lds_dwordx4 v[138:139], off
	v_lshl_add_u64 v[138:139], v[224:225], 0, s[76:77]
	s_mov_b32 m0, s70
	s_nop 0
	global_load_lds_dwordx4 v[138:139], off
	s_setprio 1
	s_barrier
	s_waitcnt lgkmcnt(0)
	v_mfma_f32_16x16x32_bf16 v[62:65], v[144:147], v[160:163], v[62:65]
	v_mfma_f32_16x16x32_bf16 v[58:61], v[152:155], v[160:163], v[58:61]
	v_mfma_f32_16x16x32_bf16 v[54:57], v[144:147], v[168:171], v[54:57]
	v_mfma_f32_16x16x32_bf16 v[46:49], v[152:155], v[168:171], v[46:49]
	v_mfma_f32_16x16x32_bf16 v[38:41], v[144:147], v[176:179], v[38:41]
	v_mfma_f32_16x16x32_bf16 v[30:33], v[152:155], v[176:179], v[30:33]
	v_mfma_f32_16x16x32_bf16 v[22:25], v[144:147], v[184:187], v[22:25]
	v_mfma_f32_16x16x32_bf16 v[14:17], v[152:155], v[184:187], v[14:17]
	v_mfma_f32_16x16x32_bf16 v[62:65], v[148:151], v[164:167], v[62:65]
	v_mfma_f32_16x16x32_bf16 v[58:61], v[156:159], v[164:167], v[58:61]
	v_mfma_f32_16x16x32_bf16 v[54:57], v[148:151], v[172:175], v[54:57]
	v_mfma_f32_16x16x32_bf16 v[46:49], v[156:159], v[172:175], v[46:49]
	v_mfma_f32_16x16x32_bf16 v[38:41], v[148:151], v[180:183], v[38:41]
	v_mfma_f32_16x16x32_bf16 v[30:33], v[156:159], v[180:183], v[30:33]
	v_mfma_f32_16x16x32_bf16 v[22:25], v[148:151], v[188:191], v[22:25]
	v_mfma_f32_16x16x32_bf16 v[14:17], v[156:159], v[188:191], v[14:17]
	s_barrier
	s_setprio 0
	s_mov_b32 m0, s71
	s_nop 0
	global_load_lds_dwordx4 v134, s[8:9]
	s_mov_b32 m0, s78
	s_nop 0
	global_load_lds_dwordx4 v130, s[8:9]
	s_waitcnt vmcnt(6)
	s_setprio 1
	s_barrier
	v_mfma_f32_16x16x32_bf16 v[50:53], v[206:209], v[160:163], v[50:53]
	v_mfma_f32_16x16x32_bf16 v[42:45], v[214:217], v[160:163], v[42:45]
	v_mfma_f32_16x16x32_bf16 v[34:37], v[206:209], v[168:171], v[34:37]
	v_mfma_f32_16x16x32_bf16 v[26:29], v[214:217], v[168:171], v[26:29]
	v_mfma_f32_16x16x32_bf16 v[18:21], v[206:209], v[176:179], v[18:21]
	v_mfma_f32_16x16x32_bf16 v[10:13], v[214:217], v[176:179], v[10:13]
	v_mfma_f32_16x16x32_bf16 v[6:9], v[206:209], v[184:187], v[6:9]
	v_mfma_f32_16x16x32_bf16 v[2:5], v[214:217], v[184:187], v[2:5]
	v_mfma_f32_16x16x32_bf16 v[50:53], v[210:213], v[164:167], v[50:53]
	v_mfma_f32_16x16x32_bf16 v[42:45], v[218:221], v[164:167], v[42:45]
	v_mfma_f32_16x16x32_bf16 v[34:37], v[210:213], v[172:175], v[34:37]
	v_mfma_f32_16x16x32_bf16 v[26:29], v[218:221], v[172:175], v[26:29]
	v_mfma_f32_16x16x32_bf16 v[18:21], v[210:213], v[180:183], v[18:21]
	v_mfma_f32_16x16x32_bf16 v[10:13], v[218:221], v[180:183], v[10:13]
	v_mfma_f32_16x16x32_bf16 v[6:9], v[210:213], v[188:191], v[6:9]
	v_mfma_f32_16x16x32_bf16 v[2:5], v[218:221], v[188:191], v[2:5]
	s_setprio 0
	s_andn2_b64 vcc, exec, s[60:61]
	s_mov_b64 s[8:9], -1
	s_mov_b64 s[60:61], 0
	s_mov_b64 s[62:63], 0x100
	s_barrier
	s_cbranch_vccz .LBB0_204
	s_cmp_gt_i32 s29, 63
	s_cbranch_scc0 .LBB0_207
	s_lshl_b32 s8, s29, 10
	s_lshl_b32 s9, s94, 8
	s_add_i32 s9, s9, s8
	v_add_u32_e32 v138, s9, v143
	v_ashrrev_i32_e32 v139, 31, v138
	v_lshlrev_b64 v[138:139], 10, v[138:139]
	s_lshl_b32 s8, s42, 8
	v_lshl_add_u64 v[138:139], s[64:65], 0, v[138:139]
	s_ashr_i32 s9, s8, 31
	v_lshl_add_u64 v[138:139], s[8:9], 1, v[138:139]
	s_mov_b64 s[8:9], 0

.LBB0_255:
	v_add_u32_e32 v253, 0x10000, v182
	ds_read_b128 v[130:133], v253
	ds_read_b128 v[134:137], v253 offset:1024
	ds_read_b128 v[138:141], v253 offset:2048
	ds_read_b128 v[142:145], v253 offset:3072
	s_add_u32 s8, s6, 0xfff00080
	s_addc_u32 s9, s7, -1
	s_cmp_eq_u32 s79, 60
	s_cselect_b32 s11, s53, s9
	s_cselect_b32 s10, s52, s8
	s_cselect_b32 s9, s61, s78
	s_cselect_b32 s8, s60, s1
	s_add_i32 m0, s5, 0xc000
	ds_read_b128 v[146:149], v181
	ds_read_b128 v[150:153], v181 offset:1024
	ds_read_b128 v[154:157], v181 offset:2048
	ds_read_b128 v[170:173], v181 offset:3072
	ds_read_b128 v[174:177], v181 offset:4096
	ds_read_b128 v[184:187], v181 offset:5120
	ds_read_b128 v[188:191], v181 offset:6144
	ds_read_b128 v[206:209], v181 offset:7168
	global_load_lds_dwordx4 v166, s[6:7]
	s_add_i32 m0, s5, 0xe000
	s_nop 0
	global_load_lds_dwordx4 v168, s[6:7]
	s_waitcnt lgkmcnt(8)
	s_setprio 1
	s_barrier
	s_waitcnt lgkmcnt(0)
	v_mfma_f32_16x16x32_bf16 v[126:129], v[130:133], v[146:149], v[126:129]
	v_mfma_f32_16x16x32_bf16 v[122:125], v[138:141], v[146:149], v[122:125]
	v_mfma_f32_16x16x32_bf16 v[110:113], v[130:133], v[154:157], v[110:113]
	v_mfma_f32_16x16x32_bf16 v[106:109], v[138:141], v[154:157], v[106:109]
	v_mfma_f32_16x16x32_bf16 v[94:97], v[130:133], v[174:177], v[94:97]
	v_mfma_f32_16x16x32_bf16 v[90:93], v[138:141], v[174:177], v[90:93]
	v_mfma_f32_16x16x32_bf16 v[78:81], v[130:133], v[188:191], v[78:81]
	v_mfma_f32_16x16x32_bf16 v[74:77], v[138:141], v[188:191], v[74:77]
	v_mfma_f32_16x16x32_bf16 v[126:129], v[134:137], v[150:153], v[126:129]
	v_mfma_f32_16x16x32_bf16 v[122:125], v[142:145], v[150:153], v[122:125]
	v_mfma_f32_16x16x32_bf16 v[110:113], v[134:137], v[170:173], v[110:113]
	v_mfma_f32_16x16x32_bf16 v[106:109], v[142:145], v[170:173], v[106:109]
	v_mfma_f32_16x16x32_bf16 v[94:97], v[134:137], v[184:187], v[94:97]
	v_mfma_f32_16x16x32_bf16 v[90:93], v[142:145], v[184:187], v[90:93]
	v_mfma_f32_16x16x32_bf16 v[78:81], v[134:137], v[206:209], v[78:81]
	v_mfma_f32_16x16x32_bf16 v[74:77], v[142:145], v[206:209], v[74:77]
	s_barrier
	s_setprio 0
	ds_read_b128 v[210:213], v253 offset:16384
	ds_read_b128 v[214:217], v253 offset:17408
	s_mov_b32 m0, s12
	ds_read_b128 v[218:221], v253 offset:18432
	ds_read_b128 v[222:225], v253 offset:19456
	v_lshl_add_u64 v[178:179], s[8:9], 0, v[162:163]
	global_load_lds_dwordx4 v[178:179], off
	v_lshl_add_u64 v[192:193], s[8:9], 0, v[158:159]
	s_mov_b32 m0, s17
	s_nop 0
	global_load_lds_dwordx4 v[192:193], off
	s_setprio 1
	s_barrier
	s_waitcnt lgkmcnt(0)
	v_mfma_f32_16x16x32_bf16 v[118:121], v[210:213], v[146:149], v[118:121]
	v_mfma_f32_16x16x32_bf16 v[114:117], v[218:221], v[146:149], v[114:117]
	v_mfma_f32_16x16x32_bf16 v[102:105], v[210:213], v[154:157], v[102:105]
	v_mfma_f32_16x16x32_bf16 v[98:101], v[218:221], v[154:157], v[98:101]
	v_mfma_f32_16x16x32_bf16 v[86:89], v[210:213], v[174:177], v[86:89]
	v_mfma_f32_16x16x32_bf16 v[82:85], v[218:221], v[174:177], v[82:85]
	v_mfma_f32_16x16x32_bf16 v[70:73], v[210:213], v[188:191], v[70:73]
	v_mfma_f32_16x16x32_bf16 v[66:69], v[218:221], v[188:191], v[66:69]
	v_mfma_f32_16x16x32_bf16 v[118:121], v[214:217], v[150:153], v[118:121]
	v_mfma_f32_16x16x32_bf16 v[114:117], v[222:225], v[150:153], v[114:117]
	v_mfma_f32_16x16x32_bf16 v[102:105], v[214:217], v[170:173], v[102:105]
	v_mfma_f32_16x16x32_bf16 v[98:101], v[222:225], v[170:173], v[98:101]
	v_mfma_f32_16x16x32_bf16 v[86:89], v[214:217], v[184:187], v[86:89]
	v_mfma_f32_16x16x32_bf16 v[82:85], v[222:225], v[184:187], v[82:85]
	s_mov_b32 m0, s5
	v_mfma_f32_16x16x32_bf16 v[70:73], v[214:217], v[206:209], v[70:73]
	v_lshl_add_u64 v[226:227], s[10:11], 0, v[164:165]
	v_mfma_f32_16x16x32_bf16 v[66:69], v[222:225], v[206:209], v[66:69]
	s_barrier
	s_setprio 0
	ds_read_b128 v[146:149], v181 offset:16384
	ds_read_b128 v[150:153], v181 offset:17408
	ds_read_b128 v[154:157], v181 offset:18432
	ds_read_b128 v[170:173], v181 offset:19456
	ds_read_b128 v[174:177], v181 offset:20480
	ds_read_b128 v[184:187], v181 offset:21504
	ds_read_b128 v[188:191], v181 offset:22528
	ds_read_b128 v[206:209], v181 offset:23552
	global_load_lds_dwordx4 v[226:227], off
	v_lshl_add_u64 v[228:229], s[10:11], 0, v[160:161]
	s_mov_b32 m0, s26
	s_nop 0
	global_load_lds_dwordx4 v[228:229], off
	s_setprio 1
	s_barrier
	s_waitcnt lgkmcnt(0)
	v_mfma_f32_16x16x32_bf16 v[62:65], v[130:133], v[146:149], v[62:65]
	v_mfma_f32_16x16x32_bf16 v[58:61], v[138:141], v[146:149], v[58:61]
	v_mfma_f32_16x16x32_bf16 v[46:49], v[130:133], v[154:157], v[46:49]
	v_mfma_f32_16x16x32_bf16 v[42:45], v[138:141], v[154:157], v[42:45]
	v_mfma_f32_16x16x32_bf16 v[30:33], v[130:133], v[174:177], v[30:33]
	v_mfma_f32_16x16x32_bf16 v[26:29], v[138:141], v[174:177], v[26:29]
	v_mfma_f32_16x16x32_bf16 v[14:17], v[130:133], v[188:191], v[14:17]
	v_mfma_f32_16x16x32_bf16 v[10:13], v[138:141], v[188:191], v[10:13]
	v_mfma_f32_16x16x32_bf16 v[62:65], v[134:137], v[150:153], v[62:65]
	v_mfma_f32_16x16x32_bf16 v[58:61], v[142:145], v[150:153], v[58:61]
	v_mfma_f32_16x16x32_bf16 v[46:49], v[134:137], v[170:173], v[46:49]
	v_mfma_f32_16x16x32_bf16 v[42:45], v[142:145], v[170:173], v[42:45]
	v_mfma_f32_16x16x32_bf16 v[30:33], v[134:137], v[184:187], v[30:33]
	v_mfma_f32_16x16x32_bf16 v[26:29], v[142:145], v[184:187], v[26:29]
	v_mfma_f32_16x16x32_bf16 v[14:17], v[134:137], v[206:209], v[14:17]
	v_mfma_f32_16x16x32_bf16 v[10:13], v[142:145], v[206:209], v[10:13]
	s_barrier
	s_setprio 0
	s_add_u32 s80, s8, 0x100000
	s_addc_u32 s81, s9, 0
	s_mov_b32 m0, s34
	s_nop 0
	global_load_lds_dwordx4 v162, s[80:81]
	s_mov_b32 m0, s35
	s_nop 0
	global_load_lds_dwordx4 v158, s[80:81]
	s_waitcnt vmcnt(6)
	s_setprio 1
	s_barrier
	v_mfma_f32_16x16x32_bf16 v[54:57], v[210:213], v[146:149], v[54:57]
	v_mfma_f32_16x16x32_bf16 v[50:53], v[218:221], v[146:149], v[50:53]
	v_mfma_f32_16x16x32_bf16 v[38:41], v[210:213], v[154:157], v[38:41]
	v_mfma_f32_16x16x32_bf16 v[34:37], v[218:221], v[154:157], v[34:37]
	v_mfma_f32_16x16x32_bf16 v[22:25], v[210:213], v[174:177], v[22:25]
	v_mfma_f32_16x16x32_bf16 v[18:21], v[218:221], v[174:177], v[18:21]
	v_mfma_f32_16x16x32_bf16 v[6:9], v[210:213], v[188:191], v[6:9]
	v_mfma_f32_16x16x32_bf16 v[2:5], v[218:221], v[188:191], v[2:5]
	v_mfma_f32_16x16x32_bf16 v[54:57], v[214:217], v[150:153], v[54:57]
	v_mfma_f32_16x16x32_bf16 v[50:53], v[222:225], v[150:153], v[50:53]
	v_mfma_f32_16x16x32_bf16 v[38:41], v[214:217], v[170:173], v[38:41]
	v_mfma_f32_16x16x32_bf16 v[34:37], v[222:225], v[170:173], v[34:37]
	v_mfma_f32_16x16x32_bf16 v[22:25], v[214:217], v[184:187], v[22:25]
	v_mfma_f32_16x16x32_bf16 v[18:21], v[222:225], v[184:187], v[18:21]
	v_mfma_f32_16x16x32_bf16 v[6:9], v[214:217], v[206:209], v[6:9]
	v_mfma_f32_16x16x32_bf16 v[2:5], v[222:225], v[206:209], v[2:5]
	s_barrier
	s_setprio 0
	ds_read_b128 v[130:133], v253 offset:32768
	ds_read_b128 v[134:137], v253 offset:33792
	ds_read_b128 v[138:141], v253 offset:34816
	ds_read_b128 v[142:145], v253 offset:35840
	s_add_u32 s10, s10, 0x100000
	s_addc_u32 s11, s11, 0
	s_mov_b32 m0, s42
	ds_read_b128 v[146:149], v181 offset:32768
	ds_read_b128 v[150:153], v181 offset:33792
	ds_read_b128 v[154:157], v181 offset:34816
	ds_read_b128 v[170:173], v181 offset:35840
	ds_read_b128 v[174:177], v181 offset:36864
	ds_read_b128 v[184:187], v181 offset:37888
	ds_read_b128 v[188:191], v181 offset:38912
	ds_read_b128 v[206:209], v181 offset:39936
	global_load_lds_dwordx4 v164, s[10:11]
	s_mov_b32 m0, s54
	s_nop 0
	global_load_lds_dwordx4 v160, s[10:11]
	s_waitcnt lgkmcnt(8)
	s_setprio 1
	s_barrier
	s_waitcnt lgkmcnt(0)
	v_mfma_f32_16x16x32_bf16 v[126:129], v[130:133], v[146:149], v[126:129]
	v_mfma_f32_16x16x32_bf16 v[122:125], v[138:141], v[146:149], v[122:125]
	v_mfma_f32_16x16x32_bf16 v[110:113], v[130:133], v[154:157], v[110:113]
	v_mfma_f32_16x16x32_bf16 v[106:109], v[138:141], v[154:157], v[106:109]
	v_mfma_f32_16x16x32_bf16 v[94:97], v[130:133], v[174:177], v[94:97]
	v_mfma_f32_16x16x32_bf16 v[90:93], v[138:141], v[174:177], v[90:93]
	v_mfma_f32_16x16x32_bf16 v[78:81], v[130:133], v[188:191], v[78:81]
	v_mfma_f32_16x16x32_bf16 v[74:77], v[138:141], v[188:191], v[74:77]
	v_mfma_f32_16x16x32_bf16 v[126:129], v[134:137], v[150:153], v[126:129]
	v_mfma_f32_16x16x32_bf16 v[122:125], v[142:145], v[150:153], v[122:125]
	v_mfma_f32_16x16x32_bf16 v[110:113], v[134:137], v[170:173], v[110:113]
	v_mfma_f32_16x16x32_bf16 v[106:109], v[142:145], v[170:173], v[106:109]
	v_mfma_f32_16x16x32_bf16 v[94:97], v[134:137], v[184:187], v[94:97]
	v_mfma_f32_16x16x32_bf16 v[90:93], v[142:145], v[184:187], v[90:93]
	v_mfma_f32_16x16x32_bf16 v[78:81], v[134:137], v[206:209], v[78:81]
	v_mfma_f32_16x16x32_bf16 v[74:77], v[142:145], v[206:209], v[74:77]
	s_barrier
	s_setprio 0
	s_mov_b32 m0, s55
	ds_read_b128 v[210:213], v253 offset:49152
	ds_read_b128 v[214:217], v253 offset:50176
	v_lshl_add_u64 v[178:179], v[178:179], 0, s[76:77]
	ds_read_b128 v[218:221], v253 offset:51200
	ds_read_b128 v[222:225], v253 offset:52224
	global_load_lds_dwordx4 v[178:179], off
	v_lshl_add_u64 v[178:179], v[192:193], 0, s[76:77]
	s_mov_b32 m0, s56
	s_nop 0
	global_load_lds_dwordx4 v[178:179], off
	s_setprio 1
	s_barrier
	s_waitcnt lgkmcnt(0)
	v_mfma_f32_16x16x32_bf16 v[118:121], v[210:213], v[146:149], v[118:121]
	v_mfma_f32_16x16x32_bf16 v[114:117], v[218:221], v[146:149], v[114:117]
	v_mfma_f32_16x16x32_bf16 v[102:105], v[210:213], v[154:157], v[102:105]
	v_mfma_f32_16x16x32_bf16 v[98:101], v[218:221], v[154:157], v[98:101]
	v_mfma_f32_16x16x32_bf16 v[86:89], v[210:213], v[174:177], v[86:89]
	v_mfma_f32_16x16x32_bf16 v[82:85], v[218:221], v[174:177], v[82:85]
	v_mfma_f32_16x16x32_bf16 v[70:73], v[210:213], v[188:191], v[70:73]
	v_mfma_f32_16x16x32_bf16 v[66:69], v[218:221], v[188:191], v[66:69]
	v_mfma_f32_16x16x32_bf16 v[118:121], v[214:217], v[150:153], v[118:121]
	v_mfma_f32_16x16x32_bf16 v[114:117], v[222:225], v[150:153], v[114:117]
	v_mfma_f32_16x16x32_bf16 v[102:105], v[214:217], v[170:173], v[102:105]
	v_mfma_f32_16x16x32_bf16 v[98:101], v[222:225], v[170:173], v[98:101]
	v_mfma_f32_16x16x32_bf16 v[86:89], v[214:217], v[184:187], v[86:89]
	v_mfma_f32_16x16x32_bf16 v[82:85], v[222:225], v[184:187], v[82:85]
	s_mov_b32 m0, s57
	v_mfma_f32_16x16x32_bf16 v[70:73], v[214:217], v[206:209], v[70:73]
	v_lshl_add_u64 v[178:179], v[226:227], 0, s[76:77]
	v_mfma_f32_16x16x32_bf16 v[66:69], v[222:225], v[206:209], v[66:69]
	s_barrier
	s_setprio 0
	ds_read_b128 v[146:149], v181 offset:49152
	ds_read_b128 v[150:153], v181 offset:50176
	ds_read_b128 v[154:157], v181 offset:51200
	ds_read_b128 v[170:173], v181 offset:52224
	ds_read_b128 v[174:177], v181 offset:53248
	ds_read_b128 v[184:187], v181 offset:54272
	ds_read_b128 v[188:191], v181 offset:55296
	ds_read_b128 v[206:209], v181 offset:56320
	global_load_lds_dwordx4 v[178:179], off
	v_lshl_add_u64 v[178:179], v[228:229], 0, s[76:77]
	s_mov_b32 m0, s58
	s_nop 0
	global_load_lds_dwordx4 v[178:179], off
	s_setprio 1
	s_barrier
	s_waitcnt lgkmcnt(0)
	v_mfma_f32_16x16x32_bf16 v[62:65], v[130:133], v[146:149], v[62:65]
	v_mfma_f32_16x16x32_bf16 v[58:61], v[138:141], v[146:149], v[58:61]
	v_mfma_f32_16x16x32_bf16 v[46:49], v[130:133], v[154:157], v[46:49]
	v_mfma_f32_16x16x32_bf16 v[42:45], v[138:141], v[154:157], v[42:45]
	v_mfma_f32_16x16x32_bf16 v[30:33], v[130:133], v[174:177], v[30:33]
	v_mfma_f32_16x16x32_bf16 v[26:29], v[138:141], v[174:177], v[26:29]
	v_mfma_f32_16x16x32_bf16 v[14:17], v[130:133], v[188:191], v[14:17]
	v_mfma_f32_16x16x32_bf16 v[10:13], v[138:141], v[188:191], v[10:13]
	v_mfma_f32_16x16x32_bf16 v[62:65], v[134:137], v[150:153], v[62:65]
	v_mfma_f32_16x16x32_bf16 v[58:61], v[142:145], v[150:153], v[58:61]
	v_mfma_f32_16x16x32_bf16 v[46:49], v[134:137], v[170:173], v[46:49]
	v_mfma_f32_16x16x32_bf16 v[42:45], v[142:145], v[170:173], v[42:45]
	v_mfma_f32_16x16x32_bf16 v[30:33], v[134:137], v[184:187], v[30:33]
	v_mfma_f32_16x16x32_bf16 v[26:29], v[142:145], v[184:187], v[26:29]
	v_mfma_f32_16x16x32_bf16 v[14:17], v[134:137], v[206:209], v[14:17]
	v_mfma_f32_16x16x32_bf16 v[10:13], v[142:145], v[206:209], v[10:13]
	s_barrier
	s_setprio 0
	s_add_u32 s8, s8, 0x100080
	s_addc_u32 s9, s9, 0
	s_mov_b32 m0, s59
	s_nop 0
	global_load_lds_dwordx4 v162, s[8:9]
	s_mov_b32 m0, s67
	s_nop 0
	global_load_lds_dwordx4 v158, s[8:9]
	s_waitcnt vmcnt(6)
	s_setprio 1
	s_barrier
	v_mfma_f32_16x16x32_bf16 v[54:57], v[210:213], v[146:149], v[54:57]
	v_mfma_f32_16x16x32_bf16 v[50:53], v[218:221], v[146:149], v[50:53]
	v_mfma_f32_16x16x32_bf16 v[38:41], v[210:213], v[154:157], v[38:41]
	v_mfma_f32_16x16x32_bf16 v[34:37], v[218:221], v[154:157], v[34:37]
	v_mfma_f32_16x16x32_bf16 v[22:25], v[210:213], v[174:177], v[22:25]
	v_mfma_f32_16x16x32_bf16 v[18:21], v[218:221], v[174:177], v[18:21]
	v_mfma_f32_16x16x32_bf16 v[6:9], v[210:213], v[188:191], v[6:9]
	v_mfma_f32_16x16x32_bf16 v[2:5], v[218:221], v[188:191], v[2:5]
	v_mfma_f32_16x16x32_bf16 v[54:57], v[214:217], v[150:153], v[54:57]
	v_mfma_f32_16x16x32_bf16 v[50:53], v[222:225], v[150:153], v[50:53]
	v_mfma_f32_16x16x32_bf16 v[38:41], v[214:217], v[170:173], v[38:41]
	v_mfma_f32_16x16x32_bf16 v[34:37], v[222:225], v[170:173], v[34:37]
	v_mfma_f32_16x16x32_bf16 v[22:25], v[214:217], v[184:187], v[22:25]
	v_mfma_f32_16x16x32_bf16 v[18:21], v[222:225], v[184:187], v[18:21]
	v_mfma_f32_16x16x32_bf16 v[6:9], v[214:217], v[206:209], v[6:9]
	v_mfma_f32_16x16x32_bf16 v[2:5], v[222:225], v[206:209], v[2:5]
	s_setprio 0
	s_add_i32 s79, s79, 2
	s_add_u32 s6, s6, 0x100
	s_addc_u32 s7, s7, 0
	s_add_u32 s1, s1, 0x100
	s_addc_u32 s78, s78, 0
	s_cmp_gt_u32 s79, 61
	s_barrier
	s_cbranch_scc0 .LBB0_255
	s_lshl_b32 s1, s28, 9
	s_and_b32 s1, s1, 0xfffff800
	s_lshl_b32 s6, s29, 8
	s_add_i32 s1, s1, s6
	v_add_u32_e32 v172, s1, v180
	s_lshl_b32 s1, s28, 8
	s_and_b32 s1, s1, 0x300
	v_or_b32_e32 v132, s1, v183
	v_mov_b64_e32 v[170:171], s[50:51]
	v_mad_i64_i32 v[130:131], s[6:7], v172, s37, v[170:171]
	v_lshlrev_b32_e32 v194, 1, v132
	v_lshl_add_u64 v[130:131], v[130:131], 0, v[194:195]
	v_lshl_add_u64 v[132:133], v[130:131], 0, s[84:85]
	v_add_co_u32_e32 v130, vcc, s16, v130
	v_or_b32_e32 v178, 16, v172
	s_nop 0
	v_addc_co_u32_e32 v131, vcc, 0, v131, vcc
	global_load_dwordx4 v[184:187], v[130:131], off offset:2048
	global_load_dwordx4 v[154:157], v[132:133], off offset:256
	v_mad_i64_i32 v[130:131], s[6:7], v178, s37, v[170:171]
	v_lshl_add_u64 v[130:131], v[130:131], 0, v[194:195]
	v_lshl_add_u64 v[132:133], v[130:131], 0, s[84:85]
	v_add_co_u32_e32 v130, vcc, s16, v130
	v_or_b32_e32 v176, 32, v172
	s_nop 0
	v_addc_co_u32_e32 v131, vcc, 0, v131, vcc
	global_load_dwordx4 v[150:153], v[130:131], off offset:2048
	global_load_dwordx4 v[146:149], v[132:133], off offset:256
	v_mad_i64_i32 v[130:131], s[6:7], v176, s37, v[170:171]
	v_lshl_add_u64 v[130:131], v[130:131], 0, v[194:195]
	v_lshl_add_u64 v[132:133], v[130:131], 0, s[84:85]
	v_add_co_u32_e32 v130, vcc, s16, v130
	v_or_b32_e32 v174, 48, v172
	s_nop 0
	v_addc_co_u32_e32 v131, vcc, 0, v131, vcc
	global_load_dwordx4 v[142:145], v[130:131], off offset:2048
	global_load_dwordx4 v[138:141], v[132:133], off offset:256
	v_mad_i64_i32 v[130:131], s[6:7], v174, s37, v[170:171]
	v_lshl_add_u64 v[130:131], v[130:131], 0, v[194:195]
	v_lshl_add_u64 v[132:133], v[130:131], 0, s[84:85]
	v_add_co_u32_e32 v130, vcc, s16, v130
	v_pk_mul_f32 v[126:127], v[126:127], s[72:73] op_sel_hi:[1,0]
	s_nop 0
	v_addc_co_u32_e32 v131, vcc, 0, v131, vcc
	global_load_dwordx4 v[134:137], v[130:131], off offset:2048
	s_nop 0
	global_load_dwordx4 v[130:133], v[132:133], off offset:256
	v_pk_mul_f32 v[190:191], v[124:125], s[72:73] op_sel_hi:[1,0]
	v_pk_mul_f32 v[128:129], v[128:129], s[72:73] op_sel_hi:[1,0]
	v_pk_mul_f32 v[122:123], v[122:123], s[72:73] op_sel_hi:[1,0]
	v_ashrrev_i32_e32 v173, 31, v172
	v_lshlrev_b64 v[188:189], 11, v[172:173]
	v_pk_mul_f32 v[118:119], v[118:119], s[72:73] op_sel_hi:[1,0]
	v_pk_mul_f32 v[120:121], v[120:121], s[72:73] op_sel_hi:[1,0]
	v_pk_mul_f32 v[110:111], v[110:111], s[72:73] op_sel_hi:[1,0]
	v_pk_mul_f32 v[112:113], v[112:113], s[72:73] op_sel_hi:[1,0]
	v_ashrrev_i32_e32 v179, 31, v178
	v_pk_mul_f32 v[102:103], v[102:103], s[72:73] op_sel_hi:[1,0]
	v_pk_mul_f32 v[104:105], v[104:105], s[72:73] op_sel_hi:[1,0]
	v_pk_mul_f32 v[94:95], v[94:95], s[72:73] op_sel_hi:[1,0]
	v_pk_mul_f32 v[96:97], v[96:97], s[72:73] op_sel_hi:[1,0]
	v_ashrrev_i32_e32 v177, 31, v176
	v_pk_mul_f32 v[86:87], v[86:87], s[72:73] op_sel_hi:[1,0]
	v_pk_mul_f32 v[88:89], v[88:89], s[72:73] op_sel_hi:[1,0]
	v_pk_mul_f32 v[78:79], v[78:79], s[72:73] op_sel_hi:[1,0]
	v_pk_mul_f32 v[80:81], v[80:81], s[72:73] op_sel_hi:[1,0]
	v_ashrrev_i32_e32 v175, 31, v174
	v_pk_mul_f32 v[70:71], v[70:71], s[72:73] op_sel_hi:[1,0]
	v_pk_mul_f32 v[72:73], v[72:73], s[72:73] op_sel_hi:[1,0]
	s_waitcnt vmcnt(0)
	v_lshlrev_b32_e32 v124, 16, v184
	v_and_b32_e32 v125, 0xffff0000, v184
	v_mul_f32_e32 v124, v126, v124
	v_mul_f32_e32 v125, v127, v125
	v_cvt_pk_bf16_f32 v124, v124, v125
	v_lshlrev_b32_e32 v125, 16, v185
	v_and_b32_e32 v126, 0xffff0000, v185
	v_mul_f32_e32 v125, v128, v125
	v_mul_f32_e32 v126, v129, v126
	v_cvt_pk_bf16_f32 v125, v125, v126
	v_lshlrev_b32_e32 v126, 16, v186
	v_mul_f32_e32 v122, v122, v126
	v_and_b32_e32 v126, 0xffff0000, v186
	v_mul_f32_e32 v123, v123, v126
	v_cvt_pk_bf16_f32 v126, v122, v123
	v_lshlrev_b32_e32 v122, 16, v187
	v_and_b32_e32 v123, 0xffff0000, v187
	v_mul_f32_e32 v122, v190, v122
	v_mul_f32_e32 v123, v191, v123
	v_cvt_pk_bf16_f32 v127, v122, v123
	v_lshl_add_u64 v[122:123], s[74:75], 0, v[188:189]
	v_lshl_add_u64 v[122:123], v[122:123], 0, v[194:195]
	global_store_dwordx4 v[122:123], v[124:127], off
	s_nop 1
	v_pk_mul_f32 v[124:125], v[116:117], s[72:73] op_sel_hi:[1,0]
	v_pk_mul_f32 v[116:117], v[114:115], s[72:73] op_sel_hi:[1,0]
	v_lshlrev_b32_e32 v114, 16, v154
	v_and_b32_e32 v115, 0xffff0000, v154
	v_mul_f32_e32 v114, v118, v114
	v_mul_f32_e32 v115, v119, v115
	v_cvt_pk_bf16_f32 v114, v114, v115
	v_lshlrev_b32_e32 v115, 16, v155
	v_and_b32_e32 v118, 0xffff0000, v155
	v_mul_f32_e32 v115, v120, v115
	v_mul_f32_e32 v118, v121, v118
	v_cvt_pk_bf16_f32 v115, v115, v118
	v_lshlrev_b32_e32 v118, 16, v156
	v_mul_f32_e32 v116, v116, v118
	v_and_b32_e32 v118, 0xffff0000, v156
	v_mul_f32_e32 v117, v117, v118
	v_cvt_pk_bf16_f32 v116, v116, v117
	v_lshlrev_b32_e32 v117, 16, v157
	v_mul_f32_e32 v117, v124, v117
	v_and_b32_e32 v118, 0xffff0000, v157
	v_mul_f32_e32 v118, v125, v118
	v_cvt_pk_bf16_f32 v117, v117, v118
	global_store_dwordx4 v[122:123], v[114:117], off offset:256
	s_nop 1
	v_pk_mul_f32 v[116:117], v[108:109], s[72:73] op_sel_hi:[1,0]
	v_pk_mul_f32 v[108:109], v[106:107], s[72:73] op_sel_hi:[1,0]
	v_lshlrev_b32_e32 v106, 16, v150
	v_and_b32_e32 v107, 0xffff0000, v150
	v_mul_f32_e32 v106, v110, v106
	v_mul_f32_e32 v107, v111, v107
	v_cvt_pk_bf16_f32 v106, v106, v107
	v_lshlrev_b32_e32 v107, 16, v151
	v_and_b32_e32 v110, 0xffff0000, v151
	v_mul_f32_e32 v107, v112, v107
	v_mul_f32_e32 v110, v113, v110
	v_cvt_pk_bf16_f32 v107, v107, v110
	v_lshlrev_b32_e32 v110, 16, v152
	v_mul_f32_e32 v108, v108, v110
	v_and_b32_e32 v110, 0xffff0000, v152
	v_mul_f32_e32 v109, v109, v110
	v_cvt_pk_bf16_f32 v108, v108, v109
	v_lshlrev_b32_e32 v109, 16, v153
	v_and_b32_e32 v110, 0xffff0000, v153
	v_lshlrev_b64 v[114:115], 11, v[178:179]
	v_mul_f32_e32 v109, v116, v109
	v_mul_f32_e32 v110, v117, v110
	v_cvt_pk_bf16_f32 v109, v109, v110
	v_lshl_add_u64 v[110:111], s[74:75], 0, v[114:115]
	v_lshl_add_u64 v[110:111], v[110:111], 0, v[194:195]
	global_store_dwordx4 v[110:111], v[106:109], off
	s_nop 1
	v_pk_mul_f32 v[106:107], v[100:101], s[72:73] op_sel_hi:[1,0]
	v_pk_mul_f32 v[100:101], v[98:99], s[72:73] op_sel_hi:[1,0]
	v_lshlrev_b32_e32 v98, 16, v146
	v_and_b32_e32 v99, 0xffff0000, v146
	v_mul_f32_e32 v98, v102, v98
	v_mul_f32_e32 v99, v103, v99
	v_cvt_pk_bf16_f32 v98, v98, v99
	v_lshlrev_b32_e32 v99, 16, v147
	v_and_b32_e32 v102, 0xffff0000, v147
	v_mul_f32_e32 v99, v104, v99
	v_mul_f32_e32 v102, v105, v102
	v_cvt_pk_bf16_f32 v99, v99, v102
	v_lshlrev_b32_e32 v102, 16, v148
	v_mul_f32_e32 v100, v100, v102
	v_and_b32_e32 v102, 0xffff0000, v148
	v_mul_f32_e32 v101, v101, v102
	v_cvt_pk_bf16_f32 v100, v100, v101
	v_lshlrev_b32_e32 v101, 16, v149
	v_mul_f32_e32 v101, v106, v101
	v_and_b32_e32 v102, 0xffff0000, v149
	v_mul_f32_e32 v102, v107, v102
	v_cvt_pk_bf16_f32 v101, v101, v102
	global_store_dwordx4 v[110:111], v[98:101], off offset:256
	s_nop 1
	v_pk_mul_f32 v[100:101], v[92:93], s[72:73] op_sel_hi:[1,0]
	v_pk_mul_f32 v[92:93], v[90:91], s[72:73] op_sel_hi:[1,0]
	v_lshlrev_b32_e32 v90, 16, v142
	v_and_b32_e32 v91, 0xffff0000, v142
	v_mul_f32_e32 v90, v94, v90
	v_mul_f32_e32 v91, v95, v91
	v_cvt_pk_bf16_f32 v90, v90, v91
	v_lshlrev_b32_e32 v91, 16, v143
	v_and_b32_e32 v94, 0xffff0000, v143
	v_mul_f32_e32 v91, v96, v91
	v_mul_f32_e32 v94, v97, v94
	v_cvt_pk_bf16_f32 v91, v91, v94
	v_lshlrev_b32_e32 v94, 16, v144
	v_mul_f32_e32 v92, v92, v94
	v_and_b32_e32 v94, 0xffff0000, v144
	v_mul_f32_e32 v93, v93, v94
	v_cvt_pk_bf16_f32 v92, v92, v93
	v_lshlrev_b32_e32 v93, 16, v145
	v_and_b32_e32 v94, 0xffff0000, v145
	v_lshlrev_b64 v[98:99], 11, v[176:177]
	v_mul_f32_e32 v93, v100, v93
	v_mul_f32_e32 v94, v101, v94
	v_cvt_pk_bf16_f32 v93, v93, v94
	v_lshl_add_u64 v[94:95], s[74:75], 0, v[98:99]
	v_lshl_add_u64 v[94:95], v[94:95], 0, v[194:195]
	global_store_dwordx4 v[94:95], v[90:93], off
	s_nop 1
	v_pk_mul_f32 v[90:91], v[84:85], s[72:73] op_sel_hi:[1,0]
	v_pk_mul_f32 v[84:85], v[82:83], s[72:73] op_sel_hi:[1,0]
	v_lshlrev_b32_e32 v82, 16, v138
	v_and_b32_e32 v83, 0xffff0000, v138
	v_mul_f32_e32 v82, v86, v82
	v_mul_f32_e32 v83, v87, v83
	v_cvt_pk_bf16_f32 v82, v82, v83
	v_lshlrev_b32_e32 v83, 16, v139
	v_and_b32_e32 v86, 0xffff0000, v139
	v_mul_f32_e32 v83, v88, v83
	v_mul_f32_e32 v86, v89, v86
	v_cvt_pk_bf16_f32 v83, v83, v86
	v_lshlrev_b32_e32 v86, 16, v140
	v_mul_f32_e32 v84, v84, v86
	v_and_b32_e32 v86, 0xffff0000, v140
	v_mul_f32_e32 v85, v85, v86
	v_cvt_pk_bf16_f32 v84, v84, v85
	v_lshlrev_b32_e32 v85, 16, v141
	v_mul_f32_e32 v85, v90, v85
	v_and_b32_e32 v86, 0xffff0000, v141
	v_mul_f32_e32 v86, v91, v86
	v_cvt_pk_bf16_f32 v85, v85, v86
	global_store_dwordx4 v[94:95], v[82:85], off offset:256
	s_nop 1
	v_pk_mul_f32 v[84:85], v[76:77], s[72:73] op_sel_hi:[1,0]
	v_pk_mul_f32 v[76:77], v[74:75], s[72:73] op_sel_hi:[1,0]
	v_lshlrev_b32_e32 v74, 16, v134
	v_and_b32_e32 v75, 0xffff0000, v134
	v_mul_f32_e32 v74, v78, v74
	v_mul_f32_e32 v75, v79, v75
	v_cvt_pk_bf16_f32 v74, v74, v75
	v_lshlrev_b32_e32 v75, 16, v135
	v_and_b32_e32 v78, 0xffff0000, v135
	v_mul_f32_e32 v75, v80, v75
	v_mul_f32_e32 v78, v81, v78
	v_cvt_pk_bf16_f32 v75, v75, v78
	v_lshlrev_b32_e32 v78, 16, v136
	v_mul_f32_e32 v76, v76, v78
	v_and_b32_e32 v78, 0xffff0000, v136
	v_mul_f32_e32 v77, v77, v78
	v_cvt_pk_bf16_f32 v76, v76, v77
	v_lshlrev_b32_e32 v77, 16, v137
	v_and_b32_e32 v78, 0xffff0000, v137
	v_lshlrev_b64 v[82:83], 11, v[174:175]
	v_mul_f32_e32 v77, v84, v77
	v_mul_f32_e32 v78, v85, v78
	v_cvt_pk_bf16_f32 v77, v77, v78
	v_lshl_add_u64 v[78:79], s[74:75], 0, v[82:83]
	v_lshl_add_u64 v[78:79], v[78:79], 0, v[194:195]
	global_store_dwordx4 v[78:79], v[74:77], off
	s_nop 1
	v_pk_mul_f32 v[74:75], v[68:69], s[72:73] op_sel_hi:[1,0]
	v_pk_mul_f32 v[68:69], v[66:67], s[72:73] op_sel_hi:[1,0]
	v_lshlrev_b32_e32 v66, 16, v130
	v_and_b32_e32 v67, 0xffff0000, v130
	v_mul_f32_e32 v66, v70, v66
	v_mul_f32_e32 v67, v71, v67
	v_cvt_pk_bf16_f32 v66, v66, v67
	v_lshlrev_b32_e32 v67, 16, v131
	v_and_b32_e32 v70, 0xffff0000, v131
	v_mul_f32_e32 v67, v72, v67
	v_mul_f32_e32 v70, v73, v70
	v_cvt_pk_bf16_f32 v67, v67, v70
	v_lshlrev_b32_e32 v70, 16, v132
	v_mul_f32_e32 v68, v68, v70
	v_and_b32_e32 v70, 0xffff0000, v132
	v_mul_f32_e32 v69, v69, v70
	v_cvt_pk_bf16_f32 v68, v68, v69
	v_lshlrev_b32_e32 v69, 16, v133
	v_mul_f32_e32 v69, v74, v69
	v_and_b32_e32 v70, 0xffff0000, v133
	v_mul_f32_e32 v70, v75, v70
	v_cvt_pk_bf16_f32 v69, v69, v70
	global_store_dwordx4 v[78:79], v[66:69], off offset:256
	v_add_u32_e32 v78, 0x80, v172
	s_nop 0
	v_mad_i64_i32 v[66:67], s[6:7], v78, s37, v[170:171]
	v_lshl_add_u64 v[66:67], v[66:67], 0, v[194:195]
	v_add_co_u32_e32 v68, vcc, s16, v66
	v_add_u32_e32 v86, 0x90, v172
	s_nop 0
	v_addc_co_u32_e32 v69, vcc, 0, v67, vcc
	global_load_dwordx4 v[70:73], v[68:69], off offset:2048
	v_lshl_add_u64 v[66:67], v[66:67], 0, s[84:85]
	global_load_dwordx4 v[74:77], v[66:67], off offset:256
	v_pk_mul_f32 v[96:97], v[56:57], s[72:73] op_sel_hi:[1,0]
	v_mad_i64_i32 v[56:57], s[6:7], v86, s37, v[170:171]
	v_lshl_add_u64 v[56:57], v[56:57], 0, v[194:195]
	v_pk_mul_f32 v[94:95], v[58:59], s[72:73] op_sel_hi:[1,0]
	v_add_co_u32_e32 v58, vcc, s16, v56
	v_pk_mul_f32 v[92:93], v[60:61], s[72:73] op_sel_hi:[1,0]
	s_nop 0
	v_addc_co_u32_e32 v59, vcc, 0, v57, vcc
	global_load_dwordx4 v[58:61], v[58:59], off offset:2048
	v_add_u32_e32 v68, 0xa0, v172
	v_pk_mul_f32 v[102:103], v[50:51], s[72:73] op_sel_hi:[1,0]
	v_mad_i64_i32 v[50:51], s[6:7], v68, s37, v[170:171]
	v_add_u32_e32 v66, 0xb0, v172
	v_lshl_add_u64 v[50:51], v[50:51], 0, v[194:195]
	v_pk_mul_f32 v[100:101], v[52:53], s[72:73] op_sel_hi:[1,0]
	v_mad_i64_i32 v[52:53], s[6:7], v66, s37, v[170:171]
	v_lshl_add_u64 v[82:83], v[50:51], 0, s[84:85]
	v_add_co_u32_e32 v50, vcc, s16, v50
	v_lshl_add_u64 v[52:53], v[52:53], 0, v[194:195]
	s_nop 0
	v_addc_co_u32_e32 v51, vcc, 0, v51, vcc
	v_ashrrev_i32_e32 v79, 31, v78
	v_lshl_add_u64 v[104:105], v[52:53], 0, s[84:85]
	v_add_co_u32_e32 v52, vcc, s16, v52
	v_pk_mul_f32 v[98:99], v[54:55], s[72:73] op_sel_hi:[1,0]
	v_lshlrev_b64 v[54:55], 11, v[78:79]
	v_lshl_add_u64 v[56:57], v[56:57], 0, s[84:85]
	v_addc_co_u32_e32 v53, vcc, 0, v53, vcc
	v_pk_mul_f32 v[88:89], v[64:65], s[72:73] op_sel_hi:[1,0]
	v_pk_mul_f32 v[90:91], v[62:63], s[72:73] op_sel_hi:[1,0]
	v_lshl_add_u64 v[106:107], s[74:75], 0, v[54:55]
	global_load_dwordx4 v[62:65], v[56:57], off offset:256
	global_load_dwordx4 v[78:81], v[50:51], off offset:2048
	s_nop 0
	global_load_dwordx4 v[82:85], v[82:83], off offset:256
	s_nop 0
	global_load_dwordx4 v[54:57], v[52:53], off offset:2048
	s_nop 0
	global_load_dwordx4 v[50:53], v[104:105], off offset:256
	v_lshl_add_u64 v[104:105], v[106:107], 0, v[194:195]
	v_pk_mul_f32 v[46:47], v[46:47], s[72:73] op_sel_hi:[1,0]
	v_pk_mul_f32 v[48:49], v[48:49], s[72:73] op_sel_hi:[1,0]
	v_ashrrev_i32_e32 v87, 31, v86
	v_pk_mul_f32 v[38:39], v[38:39], s[72:73] op_sel_hi:[1,0]
	v_pk_mul_f32 v[40:41], v[40:41], s[72:73] op_sel_hi:[1,0]
	v_pk_mul_f32 v[30:31], v[30:31], s[72:73] op_sel_hi:[1,0]
	v_pk_mul_f32 v[32:33], v[32:33], s[72:73] op_sel_hi:[1,0]
	v_ashrrev_i32_e32 v69, 31, v68
	v_pk_mul_f32 v[22:23], v[22:23], s[72:73] op_sel_hi:[1,0]
	v_pk_mul_f32 v[24:25], v[24:25], s[72:73] op_sel_hi:[1,0]
	v_pk_mul_f32 v[14:15], v[14:15], s[72:73] op_sel_hi:[1,0]
	v_pk_mul_f32 v[16:17], v[16:17], s[72:73] op_sel_hi:[1,0]
	v_ashrrev_i32_e32 v67, 31, v66
	v_pk_mul_f32 v[6:7], v[6:7], s[72:73] op_sel_hi:[1,0]
	v_pk_mul_f32 v[8:9], v[8:9], s[72:73] op_sel_hi:[1,0]
	s_waitcnt vmcnt(0)
	v_lshlrev_b32_e32 v106, 16, v70
	v_and_b32_e32 v70, 0xffff0000, v70
	v_lshlrev_b32_e32 v107, 16, v71
	v_and_b32_e32 v71, 0xffff0000, v71
	v_lshlrev_b32_e32 v108, 16, v72
	v_and_b32_e32 v72, 0xffff0000, v72
	v_lshlrev_b32_e32 v109, 16, v73
	v_and_b32_e32 v73, 0xffff0000, v73
	v_mul_f32_e32 v70, v91, v70
	v_mul_f32_e32 v71, v89, v71
	v_mul_f32_e32 v72, v95, v72
	v_mul_f32_e32 v73, v93, v73
	v_mul_f32_e32 v90, v90, v106
	v_mul_f32_e32 v88, v88, v107
	v_mul_f32_e32 v89, v94, v108
	v_mul_f32_e32 v91, v92, v109
	v_cvt_pk_bf16_f32 v70, v90, v70
	v_cvt_pk_bf16_f32 v71, v88, v71
	v_cvt_pk_bf16_f32 v72, v89, v72
	v_cvt_pk_bf16_f32 v73, v91, v73
	v_lshlrev_b32_e32 v111, 16, v75
	v_and_b32_e32 v75, 0xffff0000, v75
	global_store_dwordx4 v[104:105], v[70:73], off
	v_lshlrev_b32_e32 v110, 16, v74
	v_and_b32_e32 v74, 0xffff0000, v74
	v_lshlrev_b32_e32 v72, 16, v76
	v_and_b32_e32 v73, 0xffff0000, v76
	v_mul_f32_e32 v71, v97, v75
	v_mul_f32_e32 v72, v102, v72
	v_mul_f32_e32 v73, v103, v73
	v_mul_f32_e32 v92, v98, v110
	v_mul_f32_e32 v74, v99, v74
	v_mul_f32_e32 v93, v96, v111
	v_cvt_pk_bf16_f32 v70, v92, v74
	v_cvt_pk_bf16_f32 v71, v93, v71
	v_cvt_pk_bf16_f32 v72, v72, v73
	v_lshlrev_b32_e32 v73, 16, v77
	v_mul_f32_e32 v73, v100, v73
	v_and_b32_e32 v74, 0xffff0000, v77
	v_mul_f32_e32 v74, v101, v74
	v_cvt_pk_bf16_f32 v73, v73, v74
	global_store_dwordx4 v[104:105], v[70:73], off offset:256
	s_nop 1
	v_pk_mul_f32 v[72:73], v[44:45], s[72:73] op_sel_hi:[1,0]
	v_pk_mul_f32 v[44:45], v[42:43], s[72:73] op_sel_hi:[1,0]
	v_lshlrev_b32_e32 v42, 16, v58
	v_and_b32_e32 v43, 0xffff0000, v58
	v_mul_f32_e32 v42, v46, v42
	v_mul_f32_e32 v43, v47, v43
	v_cvt_pk_bf16_f32 v42, v42, v43
	v_lshlrev_b32_e32 v43, 16, v59
	v_and_b32_e32 v46, 0xffff0000, v59
	v_mul_f32_e32 v43, v48, v43
	v_mul_f32_e32 v46, v49, v46
	v_cvt_pk_bf16_f32 v43, v43, v46
	v_lshlrev_b32_e32 v46, 16, v60
	v_mul_f32_e32 v44, v44, v46
	v_and_b32_e32 v46, 0xffff0000, v60
	v_mul_f32_e32 v45, v45, v46
	v_cvt_pk_bf16_f32 v44, v44, v45
	v_lshlrev_b32_e32 v45, 16, v61
	v_and_b32_e32 v46, 0xffff0000, v61
	v_lshlrev_b64 v[70:71], 11, v[86:87]
	v_mul_f32_e32 v45, v72, v45
	v_mul_f32_e32 v46, v73, v46
	v_cvt_pk_bf16_f32 v45, v45, v46
	v_lshl_add_u64 v[46:47], s[74:75], 0, v[70:71]
	v_lshl_add_u64 v[46:47], v[46:47], 0, v[194:195]
	global_store_dwordx4 v[46:47], v[42:45], off
	s_nop 1
	v_pk_mul_f32 v[42:43], v[36:37], s[72:73] op_sel_hi:[1,0]
	v_pk_mul_f32 v[36:37], v[34:35], s[72:73] op_sel_hi:[1,0]
	v_lshlrev_b32_e32 v34, 16, v62
	v_and_b32_e32 v35, 0xffff0000, v62
	v_mul_f32_e32 v34, v38, v34
	v_mul_f32_e32 v35, v39, v35
	v_cvt_pk_bf16_f32 v34, v34, v35
	v_lshlrev_b32_e32 v35, 16, v63
	v_and_b32_e32 v38, 0xffff0000, v63
	v_mul_f32_e32 v35, v40, v35
	v_mul_f32_e32 v38, v41, v38
	v_cvt_pk_bf16_f32 v35, v35, v38
	v_lshlrev_b32_e32 v38, 16, v64
	v_mul_f32_e32 v36, v36, v38
	v_and_b32_e32 v38, 0xffff0000, v64
	v_mul_f32_e32 v37, v37, v38
	v_cvt_pk_bf16_f32 v36, v36, v37
	v_lshlrev_b32_e32 v37, 16, v65
	v_mul_f32_e32 v37, v42, v37
	v_and_b32_e32 v38, 0xffff0000, v65
	v_mul_f32_e32 v38, v43, v38
	v_cvt_pk_bf16_f32 v37, v37, v38
	global_store_dwordx4 v[46:47], v[34:37], off offset:256
	s_nop 1
	v_pk_mul_f32 v[36:37], v[28:29], s[72:73] op_sel_hi:[1,0]
	v_pk_mul_f32 v[28:29], v[26:27], s[72:73] op_sel_hi:[1,0]
	v_lshlrev_b32_e32 v26, 16, v78
	v_and_b32_e32 v27, 0xffff0000, v78
	v_mul_f32_e32 v26, v30, v26
	v_mul_f32_e32 v27, v31, v27
	v_cvt_pk_bf16_f32 v26, v26, v27
	v_lshlrev_b32_e32 v27, 16, v79
	v_and_b32_e32 v30, 0xffff0000, v79
	v_mul_f32_e32 v27, v32, v27
	v_mul_f32_e32 v30, v33, v30
	v_cvt_pk_bf16_f32 v27, v27, v30
	v_lshlrev_b32_e32 v30, 16, v80
	v_mul_f32_e32 v28, v28, v30
	v_and_b32_e32 v30, 0xffff0000, v80
	v_mul_f32_e32 v29, v29, v30
	v_cvt_pk_bf16_f32 v28, v28, v29
	v_lshlrev_b32_e32 v29, 16, v81
	v_and_b32_e32 v30, 0xffff0000, v81
	v_lshlrev_b64 v[34:35], 11, v[68:69]
	v_mul_f32_e32 v29, v36, v29
	v_mul_f32_e32 v30, v37, v30
	v_cvt_pk_bf16_f32 v29, v29, v30
	v_lshl_add_u64 v[30:31], s[74:75], 0, v[34:35]
	v_lshl_add_u64 v[30:31], v[30:31], 0, v[194:195]
	global_store_dwordx4 v[30:31], v[26:29], off
	s_nop 1
	v_pk_mul_f32 v[26:27], v[20:21], s[72:73] op_sel_hi:[1,0]
	v_pk_mul_f32 v[20:21], v[18:19], s[72:73] op_sel_hi:[1,0]
	v_lshlrev_b32_e32 v18, 16, v82
	v_and_b32_e32 v19, 0xffff0000, v82
	v_mul_f32_e32 v18, v22, v18
	v_mul_f32_e32 v19, v23, v19
	v_cvt_pk_bf16_f32 v18, v18, v19
	v_lshlrev_b32_e32 v19, 16, v83
	v_and_b32_e32 v22, 0xffff0000, v83
	v_mul_f32_e32 v19, v24, v19
	v_mul_f32_e32 v22, v25, v22
	v_cvt_pk_bf16_f32 v19, v19, v22
	v_lshlrev_b32_e32 v22, 16, v84
	v_mul_f32_e32 v20, v20, v22
	v_and_b32_e32 v22, 0xffff0000, v84
	v_mul_f32_e32 v21, v21, v22
	v_cvt_pk_bf16_f32 v20, v20, v21
	v_lshlrev_b32_e32 v21, 16, v85
	v_mul_f32_e32 v21, v26, v21
	v_and_b32_e32 v22, 0xffff0000, v85
	v_mul_f32_e32 v22, v27, v22
	v_cvt_pk_bf16_f32 v21, v21, v22
	global_store_dwordx4 v[30:31], v[18:21], off offset:256
	s_nop 1
	v_pk_mul_f32 v[20:21], v[12:13], s[72:73] op_sel_hi:[1,0]
	v_pk_mul_f32 v[12:13], v[10:11], s[72:73] op_sel_hi:[1,0]
	v_lshlrev_b32_e32 v10, 16, v54
	v_and_b32_e32 v11, 0xffff0000, v54
	v_mul_f32_e32 v10, v14, v10
	v_mul_f32_e32 v11, v15, v11
	v_cvt_pk_bf16_f32 v10, v10, v11
	v_lshlrev_b32_e32 v11, 16, v55
	v_and_b32_e32 v14, 0xffff0000, v55
	v_mul_f32_e32 v11, v16, v11
	v_mul_f32_e32 v14, v17, v14
	v_cvt_pk_bf16_f32 v11, v11, v14
	v_lshlrev_b32_e32 v14, 16, v56
	v_mul_f32_e32 v12, v12, v14
	v_and_b32_e32 v14, 0xffff0000, v56
	v_mul_f32_e32 v13, v13, v14
	v_cvt_pk_bf16_f32 v12, v12, v13
	v_lshlrev_b32_e32 v13, 16, v57
	v_and_b32_e32 v14, 0xffff0000, v57
	v_lshlrev_b64 v[18:19], 11, v[66:67]
	v_mul_f32_e32 v13, v20, v13
	v_mul_f32_e32 v14, v21, v14
	v_cvt_pk_bf16_f32 v13, v13, v14
	v_lshl_add_u64 v[14:15], s[74:75], 0, v[18:19]
	v_lshl_add_u64 v[14:15], v[14:15], 0, v[194:195]
	global_store_dwordx4 v[14:15], v[10:13], off
	s_nop 1
	v_pk_mul_f32 v[10:11], v[4:5], s[72:73] op_sel_hi:[1,0]
	v_pk_mul_f32 v[4:5], v[2:3], s[72:73] op_sel_hi:[1,0]
	v_lshlrev_b32_e32 v2, 16, v50
	v_and_b32_e32 v3, 0xffff0000, v50
	v_mul_f32_e32 v2, v6, v2
	v_mul_f32_e32 v3, v7, v3
	v_cvt_pk_bf16_f32 v2, v2, v3
	v_lshlrev_b32_e32 v3, 16, v51
	v_and_b32_e32 v6, 0xffff0000, v51
	v_mul_f32_e32 v3, v8, v3
	v_mul_f32_e32 v6, v9, v6
	v_cvt_pk_bf16_f32 v3, v3, v6
	v_lshlrev_b32_e32 v6, 16, v52
	v_mul_f32_e32 v4, v4, v6
	v_and_b32_e32 v6, 0xffff0000, v52
	v_mul_f32_e32 v5, v5, v6
	v_cvt_pk_bf16_f32 v4, v4, v5
	v_lshlrev_b32_e32 v5, 16, v53
	v_mul_f32_e32 v5, v10, v5
	v_and_b32_e32 v6, 0xffff0000, v53
	v_mul_f32_e32 v6, v11, v6
	v_cvt_pk_bf16_f32 v5, v5, v6
	global_store_dwordx4 v[14:15], v[2:5], off offset:256
	s_and_b64 vcc, exec, s[62:63]
	s_mov_b32 s29, s71
	s_mov_b32 s28, s0
	s_mov_b64 s[8:9], s[60:61]
	s_mov_b64 s[6:7], s[52:53]
	s_cbranch_vccz .LBB0_252
	s_waitcnt vmcnt(0)
	v_readlane_b32 s28, v250, 12
	s_cmpk_gt_u32 s4, 0xff
	v_readlane_b32 s29, v250, 13
	s_mov_b32 s70, 0x800000
	s_cbranch_scc1 .LBB0_259
	s_barrier

.LBB0_266:
	s_add_u32 s8, s6, 0x100
	s_addc_u32 s9, s7, 0
	v_add_u32_e32 v253, 0x10000, v147
	s_add_u32 s10, s71, s6
	ds_read_b128 v[142:145], v253
	ds_read_b128 v[150:153], v253 offset:1024
	ds_read_b128 v[154:157], v253 offset:2048
	ds_read_b128 v[158:161], v253 offset:3072
	s_addc_u32 s11, s78, s7
	s_cmp_eq_u32 s79, 4
	s_cselect_b32 s81, 0, s8
	s_cselect_b32 s80, 0, s9
	s_cselect_b32 s54, s29, s10
	s_cselect_b32 s55, s5, s11
	s_add_u32 s10, s18, s81
	s_addc_u32 s11, s19, s80
	v_lshl_add_u64 v[206:207], v[138:139], 0, s[6:7]
	s_add_i32 m0, s17, 0xc000
	ds_read_b128 v[162:165], v146
	ds_read_b128 v[166:169], v146 offset:1024
	ds_read_b128 v[170:173], v146 offset:2048
	ds_read_b128 v[174:177], v146 offset:3072
	ds_read_b128 v[178:181], v146 offset:4096
	ds_read_b128 v[182:185], v146 offset:5120
	ds_read_b128 v[186:189], v146 offset:6144
	ds_read_b128 v[190:193], v146 offset:7168
	global_load_lds_dwordx4 v[206:207], off
	v_lshl_add_u64 v[206:207], v[140:141], 0, s[6:7]
	s_add_i32 m0, s17, 0xe000
	s_nop 0
	global_load_lds_dwordx4 v[206:207], off
	s_waitcnt lgkmcnt(8)
	s_setprio 1
	s_barrier
	s_waitcnt lgkmcnt(0)
	v_mfma_f32_16x16x32_bf16 v[126:129], v[142:145], v[162:165], v[126:129]
	v_mfma_f32_16x16x32_bf16 v[122:125], v[154:157], v[162:165], v[122:125]
	v_mfma_f32_16x16x32_bf16 v[110:113], v[142:145], v[170:173], v[110:113]
	v_mfma_f32_16x16x32_bf16 v[106:109], v[154:157], v[170:173], v[106:109]
	v_mfma_f32_16x16x32_bf16 v[94:97], v[142:145], v[178:181], v[94:97]
	v_mfma_f32_16x16x32_bf16 v[90:93], v[154:157], v[178:181], v[90:93]
	v_mfma_f32_16x16x32_bf16 v[78:81], v[142:145], v[186:189], v[78:81]
	v_mfma_f32_16x16x32_bf16 v[74:77], v[154:157], v[186:189], v[74:77]
	v_mfma_f32_16x16x32_bf16 v[126:129], v[150:153], v[166:169], v[126:129]
	v_mfma_f32_16x16x32_bf16 v[122:125], v[158:161], v[166:169], v[122:125]
	v_mfma_f32_16x16x32_bf16 v[110:113], v[150:153], v[174:177], v[110:113]
	v_mfma_f32_16x16x32_bf16 v[106:109], v[158:161], v[174:177], v[106:109]
	v_mfma_f32_16x16x32_bf16 v[94:97], v[150:153], v[182:185], v[94:97]
	v_mfma_f32_16x16x32_bf16 v[90:93], v[158:161], v[182:185], v[90:93]
	v_mfma_f32_16x16x32_bf16 v[78:81], v[150:153], v[190:193], v[78:81]
	v_mfma_f32_16x16x32_bf16 v[74:77], v[158:161], v[190:193], v[74:77]
	s_barrier
	s_setprio 0
	s_mov_b32 m0, s26
	ds_read_b128 v[206:209], v253 offset:16384
	ds_read_b128 v[210:213], v253 offset:17408
	v_lshl_add_u64 v[222:223], s[54:55], 0, v[134:135]
	ds_read_b128 v[214:217], v253 offset:18432
	ds_read_b128 v[218:221], v253 offset:19456
	global_load_lds_dwordx4 v[222:223], off
	v_lshl_add_u64 v[224:225], s[54:55], 0, v[130:131]
	s_mov_b32 m0, s34
	s_nop 0
	global_load_lds_dwordx4 v[224:225], off
	s_setprio 1
	s_barrier
	s_waitcnt lgkmcnt(0)
	v_mfma_f32_16x16x32_bf16 v[118:121], v[206:209], v[162:165], v[118:121]
	v_mfma_f32_16x16x32_bf16 v[114:117], v[214:217], v[162:165], v[114:117]
	v_mfma_f32_16x16x32_bf16 v[102:105], v[206:209], v[170:173], v[102:105]
	v_mfma_f32_16x16x32_bf16 v[98:101], v[214:217], v[170:173], v[98:101]
	v_mfma_f32_16x16x32_bf16 v[86:89], v[206:209], v[178:181], v[86:89]
	v_mfma_f32_16x16x32_bf16 v[82:85], v[214:217], v[178:181], v[82:85]
	v_mfma_f32_16x16x32_bf16 v[70:73], v[206:209], v[186:189], v[70:73]
	v_mfma_f32_16x16x32_bf16 v[66:69], v[214:217], v[186:189], v[66:69]
	v_mfma_f32_16x16x32_bf16 v[118:121], v[210:213], v[166:169], v[118:121]
	v_mfma_f32_16x16x32_bf16 v[114:117], v[218:221], v[166:169], v[114:117]
	v_mfma_f32_16x16x32_bf16 v[102:105], v[210:213], v[174:177], v[102:105]
	v_mfma_f32_16x16x32_bf16 v[98:101], v[218:221], v[174:177], v[98:101]
	v_mfma_f32_16x16x32_bf16 v[86:89], v[210:213], v[182:185], v[86:89]
	v_mfma_f32_16x16x32_bf16 v[82:85], v[218:221], v[182:185], v[82:85]
	s_mov_b32 m0, s17
	v_mfma_f32_16x16x32_bf16 v[70:73], v[210:213], v[190:193], v[70:73]
	v_lshl_add_u64 v[226:227], s[10:11], 0, v[136:137]
	v_mfma_f32_16x16x32_bf16 v[66:69], v[218:221], v[190:193], v[66:69]
	s_barrier
	s_setprio 0
	ds_read_b128 v[162:165], v146 offset:16384
	ds_read_b128 v[166:169], v146 offset:17408
	ds_read_b128 v[170:173], v146 offset:18432
	ds_read_b128 v[174:177], v146 offset:19456
	ds_read_b128 v[178:181], v146 offset:20480
	ds_read_b128 v[182:185], v146 offset:21504
	ds_read_b128 v[186:189], v146 offset:22528
	ds_read_b128 v[190:193], v146 offset:23552
	global_load_lds_dwordx4 v[226:227], off
	v_lshl_add_u64 v[228:229], s[10:11], 0, v[132:133]
	s_mov_b32 m0, s35
	s_nop 0
	global_load_lds_dwordx4 v[228:229], off
	s_setprio 1
	s_barrier
	s_waitcnt lgkmcnt(0)
	v_mfma_f32_16x16x32_bf16 v[62:65], v[142:145], v[162:165], v[62:65]
	v_mfma_f32_16x16x32_bf16 v[58:61], v[154:157], v[162:165], v[58:61]
	v_mfma_f32_16x16x32_bf16 v[46:49], v[142:145], v[170:173], v[46:49]
	v_mfma_f32_16x16x32_bf16 v[42:45], v[154:157], v[170:173], v[42:45]
	v_mfma_f32_16x16x32_bf16 v[30:33], v[142:145], v[178:181], v[30:33]
	v_mfma_f32_16x16x32_bf16 v[26:29], v[154:157], v[178:181], v[26:29]
	v_mfma_f32_16x16x32_bf16 v[14:17], v[142:145], v[186:189], v[14:17]
	v_mfma_f32_16x16x32_bf16 v[10:13], v[154:157], v[186:189], v[10:13]
	v_mfma_f32_16x16x32_bf16 v[62:65], v[150:153], v[166:169], v[62:65]
	v_mfma_f32_16x16x32_bf16 v[58:61], v[158:161], v[166:169], v[58:61]
	v_mfma_f32_16x16x32_bf16 v[46:49], v[150:153], v[174:177], v[46:49]
	v_mfma_f32_16x16x32_bf16 v[42:45], v[158:161], v[174:177], v[42:45]
	v_mfma_f32_16x16x32_bf16 v[30:33], v[150:153], v[182:185], v[30:33]
	v_mfma_f32_16x16x32_bf16 v[26:29], v[158:161], v[182:185], v[26:29]
	v_mfma_f32_16x16x32_bf16 v[14:17], v[150:153], v[190:193], v[14:17]
	v_mfma_f32_16x16x32_bf16 v[10:13], v[158:161], v[190:193], v[10:13]
	s_barrier
	s_setprio 0
	s_add_u32 s6, s54, 0x20000
	s_addc_u32 s7, s55, 0
	s_mov_b32 m0, s42
	s_nop 0
	global_load_lds_dwordx4 v134, s[6:7]
	s_mov_b32 m0, s56
	s_nop 0
	global_load_lds_dwordx4 v130, s[6:7]
	s_waitcnt vmcnt(6)
	s_setprio 1
	s_barrier
	v_mfma_f32_16x16x32_bf16 v[54:57], v[206:209], v[162:165], v[54:57]
	v_mfma_f32_16x16x32_bf16 v[50:53], v[214:217], v[162:165], v[50:53]
	v_mfma_f32_16x16x32_bf16 v[38:41], v[206:209], v[170:173], v[38:41]
	v_mfma_f32_16x16x32_bf16 v[34:37], v[214:217], v[170:173], v[34:37]
	v_mfma_f32_16x16x32_bf16 v[22:25], v[206:209], v[178:181], v[22:25]
	v_mfma_f32_16x16x32_bf16 v[18:21], v[214:217], v[178:181], v[18:21]
	v_mfma_f32_16x16x32_bf16 v[6:9], v[206:209], v[186:189], v[6:9]
	v_mfma_f32_16x16x32_bf16 v[2:5], v[214:217], v[186:189], v[2:5]
	v_mfma_f32_16x16x32_bf16 v[54:57], v[210:213], v[166:169], v[54:57]
	v_mfma_f32_16x16x32_bf16 v[50:53], v[218:221], v[166:169], v[50:53]
	v_mfma_f32_16x16x32_bf16 v[38:41], v[210:213], v[174:177], v[38:41]
	v_mfma_f32_16x16x32_bf16 v[34:37], v[218:221], v[174:177], v[34:37]
	v_mfma_f32_16x16x32_bf16 v[22:25], v[210:213], v[182:185], v[22:25]
	v_mfma_f32_16x16x32_bf16 v[18:21], v[218:221], v[182:185], v[18:21]
	v_mfma_f32_16x16x32_bf16 v[6:9], v[210:213], v[190:193], v[6:9]
	v_mfma_f32_16x16x32_bf16 v[2:5], v[218:221], v[190:193], v[2:5]
	s_barrier
	s_setprio 0
	ds_read_b128 v[142:145], v253 offset:32768
	ds_read_b128 v[150:153], v253 offset:33792
	ds_read_b128 v[154:157], v253 offset:34816
	ds_read_b128 v[158:161], v253 offset:35840
	s_add_u32 s6, s10, 0x20000
	s_addc_u32 s7, s11, 0
	s_mov_b32 m0, s57
	ds_read_b128 v[162:165], v146 offset:32768
	ds_read_b128 v[166:169], v146 offset:33792
	ds_read_b128 v[170:173], v146 offset:34816
	ds_read_b128 v[174:177], v146 offset:35840
	ds_read_b128 v[178:181], v146 offset:36864
	ds_read_b128 v[182:185], v146 offset:37888
	ds_read_b128 v[186:189], v146 offset:38912
	ds_read_b128 v[190:193], v146 offset:39936
	global_load_lds_dwordx4 v136, s[6:7]
	s_mov_b32 m0, s58
	s_nop 0
	global_load_lds_dwordx4 v132, s[6:7]
	s_waitcnt lgkmcnt(8)
	s_setprio 1
	s_barrier
	s_waitcnt lgkmcnt(0)
	v_mfma_f32_16x16x32_bf16 v[126:129], v[142:145], v[162:165], v[126:129]
	v_mfma_f32_16x16x32_bf16 v[122:125], v[154:157], v[162:165], v[122:125]
	v_mfma_f32_16x16x32_bf16 v[110:113], v[142:145], v[170:173], v[110:113]
	v_mfma_f32_16x16x32_bf16 v[106:109], v[154:157], v[170:173], v[106:109]
	v_mfma_f32_16x16x32_bf16 v[94:97], v[142:145], v[178:181], v[94:97]
	v_mfma_f32_16x16x32_bf16 v[90:93], v[154:157], v[178:181], v[90:93]
	v_mfma_f32_16x16x32_bf16 v[78:81], v[142:145], v[186:189], v[78:81]
	v_mfma_f32_16x16x32_bf16 v[74:77], v[154:157], v[186:189], v[74:77]
	v_mfma_f32_16x16x32_bf16 v[126:129], v[150:153], v[166:169], v[126:129]
	v_mfma_f32_16x16x32_bf16 v[122:125], v[158:161], v[166:169], v[122:125]
	v_mfma_f32_16x16x32_bf16 v[110:113], v[150:153], v[174:177], v[110:113]
	v_mfma_f32_16x16x32_bf16 v[106:109], v[158:161], v[174:177], v[106:109]
	v_mfma_f32_16x16x32_bf16 v[94:97], v[150:153], v[182:185], v[94:97]
	v_mfma_f32_16x16x32_bf16 v[90:93], v[158:161], v[182:185], v[90:93]
	v_mfma_f32_16x16x32_bf16 v[78:81], v[150:153], v[190:193], v[78:81]
	v_mfma_f32_16x16x32_bf16 v[74:77], v[158:161], v[190:193], v[74:77]
	s_barrier
	s_setprio 0
	s_mov_b32 m0, s59
	ds_read_b128 v[206:209], v253 offset:49152
	ds_read_b128 v[210:213], v253 offset:50176
	v_lshl_add_u64 v[222:223], v[222:223], 0, s[76:77]
	ds_read_b128 v[214:217], v253 offset:51200
	ds_read_b128 v[218:221], v253 offset:52224
	global_load_lds_dwordx4 v[222:223], off
	v_lshl_add_u64 v[222:223], v[224:225], 0, s[76:77]
	s_mov_b32 m0, s60
	s_nop 0
	global_load_lds_dwordx4 v[222:223], off
	s_setprio 1
	s_barrier
	s_waitcnt lgkmcnt(0)
	v_mfma_f32_16x16x32_bf16 v[118:121], v[206:209], v[162:165], v[118:121]
	v_mfma_f32_16x16x32_bf16 v[114:117], v[214:217], v[162:165], v[114:117]
	v_mfma_f32_16x16x32_bf16 v[102:105], v[206:209], v[170:173], v[102:105]
	v_mfma_f32_16x16x32_bf16 v[98:101], v[214:217], v[170:173], v[98:101]
	v_mfma_f32_16x16x32_bf16 v[86:89], v[206:209], v[178:181], v[86:89]
	v_mfma_f32_16x16x32_bf16 v[82:85], v[214:217], v[178:181], v[82:85]
	v_mfma_f32_16x16x32_bf16 v[70:73], v[206:209], v[186:189], v[70:73]
	v_mfma_f32_16x16x32_bf16 v[66:69], v[214:217], v[186:189], v[66:69]
	v_mfma_f32_16x16x32_bf16 v[118:121], v[210:213], v[166:169], v[118:121]
	v_mfma_f32_16x16x32_bf16 v[114:117], v[218:221], v[166:169], v[114:117]
	v_mfma_f32_16x16x32_bf16 v[102:105], v[210:213], v[174:177], v[102:105]
	v_mfma_f32_16x16x32_bf16 v[98:101], v[218:221], v[174:177], v[98:101]
	v_mfma_f32_16x16x32_bf16 v[86:89], v[210:213], v[182:185], v[86:89]
	v_mfma_f32_16x16x32_bf16 v[82:85], v[218:221], v[182:185], v[82:85]
	s_mov_b32 m0, s61
	v_mfma_f32_16x16x32_bf16 v[70:73], v[210:213], v[190:193], v[70:73]
	v_lshl_add_u64 v[222:223], v[226:227], 0, s[76:77]
	v_mfma_f32_16x16x32_bf16 v[66:69], v[218:221], v[190:193], v[66:69]
	s_barrier
	s_setprio 0
	ds_read_b128 v[162:165], v146 offset:49152
	ds_read_b128 v[166:169], v146 offset:50176
	ds_read_b128 v[170:173], v146 offset:51200
	ds_read_b128 v[174:177], v146 offset:52224
	ds_read_b128 v[178:181], v146 offset:53248
	ds_read_b128 v[182:185], v146 offset:54272
	ds_read_b128 v[186:189], v146 offset:55296
	ds_read_b128 v[190:193], v146 offset:56320
	global_load_lds_dwordx4 v[222:223], off
	v_lshl_add_u64 v[222:223], v[228:229], 0, s[76:77]
	s_mov_b32 m0, s62
	s_nop 0
	global_load_lds_dwordx4 v[222:223], off
	s_setprio 1
	s_barrier
	s_waitcnt lgkmcnt(0)
	v_mfma_f32_16x16x32_bf16 v[62:65], v[142:145], v[162:165], v[62:65]
	v_mfma_f32_16x16x32_bf16 v[58:61], v[154:157], v[162:165], v[58:61]
	v_mfma_f32_16x16x32_bf16 v[46:49], v[142:145], v[170:173], v[46:49]
	v_mfma_f32_16x16x32_bf16 v[42:45], v[154:157], v[170:173], v[42:45]
	v_mfma_f32_16x16x32_bf16 v[30:33], v[142:145], v[178:181], v[30:33]
	v_mfma_f32_16x16x32_bf16 v[26:29], v[154:157], v[178:181], v[26:29]
	v_mfma_f32_16x16x32_bf16 v[14:17], v[142:145], v[186:189], v[14:17]
	v_mfma_f32_16x16x32_bf16 v[10:13], v[154:157], v[186:189], v[10:13]
	v_mfma_f32_16x16x32_bf16 v[62:65], v[150:153], v[166:169], v[62:65]
	v_mfma_f32_16x16x32_bf16 v[58:61], v[158:161], v[166:169], v[58:61]
	v_mfma_f32_16x16x32_bf16 v[46:49], v[150:153], v[174:177], v[46:49]
	v_mfma_f32_16x16x32_bf16 v[42:45], v[158:161], v[174:177], v[42:45]
	v_mfma_f32_16x16x32_bf16 v[30:33], v[150:153], v[182:185], v[30:33]
	v_mfma_f32_16x16x32_bf16 v[26:29], v[158:161], v[182:185], v[26:29]
	v_mfma_f32_16x16x32_bf16 v[14:17], v[150:153], v[190:193], v[14:17]
	v_mfma_f32_16x16x32_bf16 v[10:13], v[158:161], v[190:193], v[10:13]
	s_barrier
	s_setprio 0
	s_add_u32 s6, s54, 0x20080
	s_addc_u32 s7, s55, 0
	s_mov_b32 m0, s63
	s_nop 0
	global_load_lds_dwordx4 v134, s[6:7]
	s_mov_b32 m0, s67
	s_nop 0
	global_load_lds_dwordx4 v130, s[6:7]
	s_waitcnt vmcnt(6)
	s_setprio 1
	s_barrier
	v_mfma_f32_16x16x32_bf16 v[54:57], v[206:209], v[162:165], v[54:57]
	v_mfma_f32_16x16x32_bf16 v[50:53], v[214:217], v[162:165], v[50:53]
	v_mfma_f32_16x16x32_bf16 v[38:41], v[206:209], v[170:173], v[38:41]
	v_mfma_f32_16x16x32_bf16 v[34:37], v[214:217], v[170:173], v[34:37]
	v_mfma_f32_16x16x32_bf16 v[22:25], v[206:209], v[178:181], v[22:25]
	v_mfma_f32_16x16x32_bf16 v[18:21], v[214:217], v[178:181], v[18:21]
	v_mfma_f32_16x16x32_bf16 v[6:9], v[206:209], v[186:189], v[6:9]
	v_mfma_f32_16x16x32_bf16 v[2:5], v[214:217], v[186:189], v[2:5]
	v_mfma_f32_16x16x32_bf16 v[54:57], v[210:213], v[166:169], v[54:57]
	v_mfma_f32_16x16x32_bf16 v[50:53], v[218:221], v[166:169], v[50:53]
	v_mfma_f32_16x16x32_bf16 v[38:41], v[210:213], v[174:177], v[38:41]
	v_mfma_f32_16x16x32_bf16 v[34:37], v[218:221], v[174:177], v[34:37]
	v_mfma_f32_16x16x32_bf16 v[22:25], v[210:213], v[182:185], v[22:25]
	v_mfma_f32_16x16x32_bf16 v[18:21], v[218:221], v[182:185], v[18:21]
	v_mfma_f32_16x16x32_bf16 v[6:9], v[210:213], v[190:193], v[6:9]
	v_mfma_f32_16x16x32_bf16 v[2:5], v[218:221], v[190:193], v[2:5]
	s_setprio 0
	s_add_i32 s79, s79, 2
	s_cmp_gt_u32 s79, 5
	s_mov_b64 s[6:7], s[8:9]
	s_barrier
	s_cbranch_scc0 .LBB0_266
	s_lshl_b32 s5, s28, 6
	s_and_b32 s5, s5, 0xffffff00
	v_add_u32_e32 v144, s5, v148
	s_lshl_b32 s5, s28, 8
	s_and_b32 s5, s5, 0x300
	v_or_b32_e32 v145, s5, v149
	v_mov_b64_e32 v[142:143], s[50:51]
	v_mad_i64_i32 v[150:151], s[6:7], v144, s37, v[142:143]
	v_lshlrev_b32_e32 v194, 1, v145
	v_lshl_add_u64 v[154:155], v[150:151], 0, v[194:195]
	v_add_co_u32_e32 v150, vcc, 0x1000, v154
	v_or_b32_e32 v184, 16, v144
	s_nop 0
	v_addc_co_u32_e32 v151, vcc, 0, v155, vcc
	global_load_dwordx4 v[150:153], v[150:151], off offset:2048
	v_lshl_add_u64 v[154:155], v[154:155], 0, s[84:85]
	global_load_dwordx4 v[154:157], v[154:155], off offset:256
	v_pk_mul_f32 v[182:183], v[114:115], s[36:37] op_sel_hi:[1,0]
	v_mad_i64_i32 v[114:115], s[6:7], v184, s37, v[142:143]
	v_lshl_add_u64 v[114:115], v[114:115], 0, v[194:195]
	v_pk_mul_f32 v[180:181], v[116:117], s[36:37] op_sel_hi:[1,0]
	v_add_co_u32_e32 v116, vcc, 0x1000, v114
	v_pk_mul_f32 v[170:171], v[126:127], s[36:37] op_sel_hi:[1,0]
	s_nop 0
	v_addc_co_u32_e32 v117, vcc, 0, v115, vcc
	v_pk_mul_f32 v[172:173], v[124:125], s[36:37] op_sel_hi:[1,0]
	global_load_dwordx4 v[124:127], v[116:117], off offset:2048
	v_lshl_add_u64 v[114:115], v[114:115], 0, s[84:85]
	global_load_dwordx4 v[158:161], v[114:115], off offset:256
	v_or_b32_e32 v186, 32, v144
	v_mad_i64_i32 v[116:117], s[6:7], v186, s37, v[142:143]
	v_lshl_add_u64 v[116:117], v[116:117], 0, v[194:195]
	v_lshl_add_u64 v[166:167], v[116:117], 0, s[84:85]
	v_add_co_u32_e32 v116, vcc, 0x1000, v116
	v_pk_mul_f32 v[174:175], v[122:123], s[36:37] op_sel_hi:[1,0]
	s_nop 0
	v_addc_co_u32_e32 v117, vcc, 0, v117, vcc
	global_load_dwordx4 v[162:165], v[116:117], off offset:2048
	s_nop 0
	global_load_dwordx4 v[166:169], v[166:167], off offset:256
	v_or_b32_e32 v122, 48, v144
	v_pk_mul_f32 v[178:179], v[118:119], s[36:37] op_sel_hi:[1,0]
	v_mad_i64_i32 v[118:119], s[6:7], v122, s37, v[142:143]
	v_ashrrev_i32_e32 v145, 31, v144
	v_lshl_add_u64 v[118:119], v[118:119], 0, v[194:195]
	v_pk_mul_f32 v[176:177], v[120:121], s[36:37] op_sel_hi:[1,0]
	v_lshlrev_b64 v[120:121], 11, v[144:145]
	v_add_co_u32_e32 v114, vcc, 0x1000, v118
	v_lshl_add_u64 v[120:121], s[74:75], 0, v[120:121]
	s_nop 0
	v_addc_co_u32_e32 v115, vcc, 0, v119, vcc
	v_lshl_add_u64 v[188:189], v[118:119], 0, s[84:85]
	v_lshl_add_u64 v[190:191], v[120:121], 0, v[194:195]
	global_load_dwordx4 v[118:121], v[114:115], off offset:2048
	s_nop 0
	global_load_dwordx4 v[114:117], v[188:189], off offset:256
	v_pk_mul_f32 v[128:129], v[128:129], s[36:37] op_sel_hi:[1,0]
	v_pk_mul_f32 v[110:111], v[110:111], s[36:37] op_sel_hi:[1,0]
	v_pk_mul_f32 v[112:113], v[112:113], s[36:37] op_sel_hi:[1,0]
	v_ashrrev_i32_e32 v185, 31, v184
	v_pk_mul_f32 v[102:103], v[102:103], s[36:37] op_sel_hi:[1,0]
	v_pk_mul_f32 v[104:105], v[104:105], s[36:37] op_sel_hi:[1,0]
	v_pk_mul_f32 v[94:95], v[94:95], s[36:37] op_sel_hi:[1,0]
	v_pk_mul_f32 v[96:97], v[96:97], s[36:37] op_sel_hi:[1,0]
	v_ashrrev_i32_e32 v187, 31, v186
	v_pk_mul_f32 v[86:87], v[86:87], s[36:37] op_sel_hi:[1,0]
	v_pk_mul_f32 v[88:89], v[88:89], s[36:37] op_sel_hi:[1,0]
	v_pk_mul_f32 v[78:79], v[78:79], s[36:37] op_sel_hi:[1,0]
	v_pk_mul_f32 v[80:81], v[80:81], s[36:37] op_sel_hi:[1,0]
	v_ashrrev_i32_e32 v123, 31, v122
	v_pk_mul_f32 v[70:71], v[70:71], s[36:37] op_sel_hi:[1,0]
	v_pk_mul_f32 v[72:73], v[72:73], s[36:37] op_sel_hi:[1,0]
	s_waitcnt vmcnt(0)
	v_lshlrev_b32_e32 v145, 16, v150
	v_and_b32_e32 v150, 0xffff0000, v150
	v_lshlrev_b32_e32 v188, 16, v151
	v_and_b32_e32 v151, 0xffff0000, v151
	v_mul_f32_e32 v150, v171, v150
	v_mul_f32_e32 v128, v128, v188
	v_mul_f32_e32 v129, v129, v151
	v_lshlrev_b32_e32 v189, 16, v152
	v_and_b32_e32 v152, 0xffff0000, v152
	v_lshlrev_b32_e32 v192, 16, v153
	v_and_b32_e32 v153, 0xffff0000, v153
	v_mul_f32_e32 v145, v170, v145
	v_cvt_pk_bf16_f32 v150, v145, v150
	v_cvt_pk_bf16_f32 v151, v128, v129
	v_lshlrev_b32_e32 v128, 16, v154
	v_and_b32_e32 v129, 0xffff0000, v154
	v_mul_f32_e32 v152, v175, v152
	v_mul_f32_e32 v153, v173, v153
	v_mul_f32_e32 v128, v178, v128
	v_mul_f32_e32 v129, v179, v129
	v_mul_f32_e32 v170, v174, v189
	v_mul_f32_e32 v171, v172, v192
	v_cvt_pk_bf16_f32 v152, v170, v152
	v_cvt_pk_bf16_f32 v153, v171, v153
	global_store_dwordx4 v[190:191], v[150:153], off
	s_nop 1
	v_cvt_pk_bf16_f32 v150, v128, v129
	v_lshlrev_b32_e32 v128, 16, v155
	v_and_b32_e32 v129, 0xffff0000, v155
	v_mul_f32_e32 v128, v176, v128
	v_mul_f32_e32 v129, v177, v129
	v_cvt_pk_bf16_f32 v151, v128, v129
	v_lshlrev_b32_e32 v128, 16, v156
	v_and_b32_e32 v129, 0xffff0000, v156
	v_mul_f32_e32 v128, v182, v128
	v_mul_f32_e32 v129, v183, v129
	v_cvt_pk_bf16_f32 v152, v128, v129
	v_lshlrev_b32_e32 v128, 16, v157
	v_and_b32_e32 v129, 0xffff0000, v157
	v_mul_f32_e32 v128, v180, v128
	v_mul_f32_e32 v129, v181, v129
	v_cvt_pk_bf16_f32 v153, v128, v129
	global_store_dwordx4 v[190:191], v[150:153], off offset:256
	v_lshlrev_b64 v[128:129], 11, v[184:185]
	s_nop 0
	v_pk_mul_f32 v[150:151], v[108:109], s[36:37] op_sel_hi:[1,0]
	v_pk_mul_f32 v[108:109], v[106:107], s[36:37] op_sel_hi:[1,0]
	v_lshlrev_b32_e32 v106, 16, v124
	v_and_b32_e32 v107, 0xffff0000, v124
	v_mul_f32_e32 v106, v110, v106
	v_mul_f32_e32 v107, v111, v107
	v_cvt_pk_bf16_f32 v106, v106, v107
	v_lshlrev_b32_e32 v107, 16, v125
	v_and_b32_e32 v110, 0xffff0000, v125
	v_mul_f32_e32 v107, v112, v107
	v_mul_f32_e32 v110, v113, v110
	v_cvt_pk_bf16_f32 v107, v107, v110
	v_lshlrev_b32_e32 v110, 16, v126
	v_mul_f32_e32 v108, v108, v110
	v_and_b32_e32 v110, 0xffff0000, v126
	v_mul_f32_e32 v109, v109, v110
	v_cvt_pk_bf16_f32 v108, v108, v109
	v_lshlrev_b32_e32 v109, 16, v127
	v_and_b32_e32 v110, 0xffff0000, v127
	v_mul_f32_e32 v109, v150, v109
	v_mul_f32_e32 v110, v151, v110
	v_cvt_pk_bf16_f32 v109, v109, v110
	v_lshl_add_u64 v[110:111], s[74:75], 0, v[128:129]
	v_lshl_add_u64 v[110:111], v[110:111], 0, v[194:195]
	global_store_dwordx4 v[110:111], v[106:109], off
	s_nop 1
	v_pk_mul_f32 v[106:107], v[100:101], s[36:37] op_sel_hi:[1,0]
	v_pk_mul_f32 v[100:101], v[98:99], s[36:37] op_sel_hi:[1,0]
	v_lshlrev_b32_e32 v98, 16, v158
	v_and_b32_e32 v99, 0xffff0000, v158
	v_mul_f32_e32 v98, v102, v98
	v_mul_f32_e32 v99, v103, v99
	v_cvt_pk_bf16_f32 v98, v98, v99
	v_lshlrev_b32_e32 v99, 16, v159
	v_and_b32_e32 v102, 0xffff0000, v159
	v_mul_f32_e32 v99, v104, v99
	v_mul_f32_e32 v102, v105, v102
	v_cvt_pk_bf16_f32 v99, v99, v102
	v_lshlrev_b32_e32 v102, 16, v160
	v_mul_f32_e32 v100, v100, v102
	v_and_b32_e32 v102, 0xffff0000, v160
	v_mul_f32_e32 v101, v101, v102
	v_cvt_pk_bf16_f32 v100, v100, v101
	v_lshlrev_b32_e32 v101, 16, v161
	v_mul_f32_e32 v101, v106, v101
	v_and_b32_e32 v102, 0xffff0000, v161
	v_mul_f32_e32 v102, v107, v102
	v_cvt_pk_bf16_f32 v101, v101, v102
	global_store_dwordx4 v[110:111], v[98:101], off offset:256
	s_nop 1
	v_pk_mul_f32 v[100:101], v[92:93], s[36:37] op_sel_hi:[1,0]
	v_pk_mul_f32 v[92:93], v[90:91], s[36:37] op_sel_hi:[1,0]
	v_lshlrev_b32_e32 v90, 16, v162
	v_and_b32_e32 v91, 0xffff0000, v162
	v_mul_f32_e32 v90, v94, v90
	v_mul_f32_e32 v91, v95, v91
	v_cvt_pk_bf16_f32 v90, v90, v91
	v_lshlrev_b32_e32 v91, 16, v163
	v_and_b32_e32 v94, 0xffff0000, v163
	v_mul_f32_e32 v91, v96, v91
	v_mul_f32_e32 v94, v97, v94
	v_cvt_pk_bf16_f32 v91, v91, v94
	v_lshlrev_b32_e32 v94, 16, v164
	v_mul_f32_e32 v92, v92, v94
	v_and_b32_e32 v94, 0xffff0000, v164
	v_mul_f32_e32 v93, v93, v94
	v_cvt_pk_bf16_f32 v92, v92, v93
	v_lshlrev_b32_e32 v93, 16, v165
	v_and_b32_e32 v94, 0xffff0000, v165
	v_lshlrev_b64 v[98:99], 11, v[186:187]
	v_mul_f32_e32 v93, v100, v93
	v_mul_f32_e32 v94, v101, v94
	v_cvt_pk_bf16_f32 v93, v93, v94
	v_lshl_add_u64 v[94:95], s[74:75], 0, v[98:99]
	v_lshl_add_u64 v[94:95], v[94:95], 0, v[194:195]
	global_store_dwordx4 v[94:95], v[90:93], off
	s_nop 1
	v_pk_mul_f32 v[90:91], v[84:85], s[36:37] op_sel_hi:[1,0]
	v_pk_mul_f32 v[84:85], v[82:83], s[36:37] op_sel_hi:[1,0]
	v_lshlrev_b32_e32 v82, 16, v166
	v_and_b32_e32 v83, 0xffff0000, v166
	v_mul_f32_e32 v82, v86, v82
	v_mul_f32_e32 v83, v87, v83
	v_cvt_pk_bf16_f32 v82, v82, v83
	v_lshlrev_b32_e32 v83, 16, v167
	v_and_b32_e32 v86, 0xffff0000, v167
	v_mul_f32_e32 v83, v88, v83
	v_mul_f32_e32 v86, v89, v86
	v_cvt_pk_bf16_f32 v83, v83, v86
	v_lshlrev_b32_e32 v86, 16, v168
	v_mul_f32_e32 v84, v84, v86
	v_and_b32_e32 v86, 0xffff0000, v168
	v_mul_f32_e32 v85, v85, v86
	v_cvt_pk_bf16_f32 v84, v84, v85
	v_lshlrev_b32_e32 v85, 16, v169
	v_mul_f32_e32 v85, v90, v85
	v_and_b32_e32 v86, 0xffff0000, v169
	v_mul_f32_e32 v86, v91, v86
	v_cvt_pk_bf16_f32 v85, v85, v86
	global_store_dwordx4 v[94:95], v[82:85], off offset:256
	s_nop 1
	v_pk_mul_f32 v[84:85], v[76:77], s[36:37] op_sel_hi:[1,0]
	v_pk_mul_f32 v[76:77], v[74:75], s[36:37] op_sel_hi:[1,0]
	v_lshlrev_b32_e32 v74, 16, v118
	v_and_b32_e32 v75, 0xffff0000, v118
	v_mul_f32_e32 v74, v78, v74
	v_mul_f32_e32 v75, v79, v75
	v_cvt_pk_bf16_f32 v74, v74, v75
	v_lshlrev_b32_e32 v75, 16, v119
	v_and_b32_e32 v78, 0xffff0000, v119
	v_mul_f32_e32 v75, v80, v75
	v_mul_f32_e32 v78, v81, v78
	v_cvt_pk_bf16_f32 v75, v75, v78
	v_lshlrev_b32_e32 v78, 16, v120
	v_mul_f32_e32 v76, v76, v78
	v_and_b32_e32 v78, 0xffff0000, v120
	v_mul_f32_e32 v77, v77, v78
	v_cvt_pk_bf16_f32 v76, v76, v77
	v_lshlrev_b32_e32 v77, 16, v121
	v_and_b32_e32 v78, 0xffff0000, v121
	v_lshlrev_b64 v[82:83], 11, v[122:123]
	v_mul_f32_e32 v77, v84, v77
	v_mul_f32_e32 v78, v85, v78
	v_cvt_pk_bf16_f32 v77, v77, v78
	v_lshl_add_u64 v[78:79], s[74:75], 0, v[82:83]
	v_lshl_add_u64 v[78:79], v[78:79], 0, v[194:195]
	global_store_dwordx4 v[78:79], v[74:77], off
	s_nop 1
	v_pk_mul_f32 v[74:75], v[68:69], s[36:37] op_sel_hi:[1,0]
	v_pk_mul_f32 v[68:69], v[66:67], s[36:37] op_sel_hi:[1,0]
	v_lshlrev_b32_e32 v66, 16, v114
	v_and_b32_e32 v67, 0xffff0000, v114
	v_mul_f32_e32 v66, v70, v66
	v_mul_f32_e32 v67, v71, v67
	v_cvt_pk_bf16_f32 v66, v66, v67
	v_lshlrev_b32_e32 v67, 16, v115
	v_and_b32_e32 v70, 0xffff0000, v115
	v_mul_f32_e32 v67, v72, v67
	v_mul_f32_e32 v70, v73, v70
	v_cvt_pk_bf16_f32 v67, v67, v70
	v_lshlrev_b32_e32 v70, 16, v116
	v_mul_f32_e32 v68, v68, v70
	v_and_b32_e32 v70, 0xffff0000, v116
	v_mul_f32_e32 v69, v69, v70
	v_cvt_pk_bf16_f32 v68, v68, v69
	v_lshlrev_b32_e32 v69, 16, v117
	v_mul_f32_e32 v69, v74, v69
	v_and_b32_e32 v70, 0xffff0000, v117
	v_mul_f32_e32 v70, v75, v70
	v_cvt_pk_bf16_f32 v69, v69, v70
	global_store_dwordx4 v[78:79], v[66:69], off offset:256
	v_add_u32_e32 v78, 0x80, v144
	s_nop 0
	v_mad_i64_i32 v[66:67], s[6:7], v78, s37, v[142:143]
	v_lshl_add_u64 v[66:67], v[66:67], 0, v[194:195]
	v_add_co_u32_e32 v68, vcc, s16, v66
	v_add_u32_e32 v86, 0x90, v144
	s_nop 0
	v_addc_co_u32_e32 v69, vcc, 0, v67, vcc
	global_load_dwordx4 v[70:73], v[68:69], off offset:2048
	v_lshl_add_u64 v[66:67], v[66:67], 0, s[84:85]
	global_load_dwordx4 v[74:77], v[66:67], off offset:256
	v_pk_mul_f32 v[96:97], v[56:57], s[36:37] op_sel_hi:[1,0]
	v_mad_i64_i32 v[56:57], s[6:7], v86, s37, v[142:143]
	v_lshl_add_u64 v[56:57], v[56:57], 0, v[194:195]
	v_pk_mul_f32 v[94:95], v[58:59], s[36:37] op_sel_hi:[1,0]
	v_add_co_u32_e32 v58, vcc, s16, v56
	v_pk_mul_f32 v[92:93], v[60:61], s[36:37] op_sel_hi:[1,0]
	s_nop 0
	v_addc_co_u32_e32 v59, vcc, 0, v57, vcc
	global_load_dwordx4 v[58:61], v[58:59], off offset:2048
	v_add_u32_e32 v68, 0xa0, v144
	v_pk_mul_f32 v[102:103], v[50:51], s[36:37] op_sel_hi:[1,0]
	v_mad_i64_i32 v[50:51], s[6:7], v68, s37, v[142:143]
	v_add_u32_e32 v66, 0xb0, v144
	v_lshl_add_u64 v[50:51], v[50:51], 0, v[194:195]
	v_pk_mul_f32 v[100:101], v[52:53], s[36:37] op_sel_hi:[1,0]
	v_mad_i64_i32 v[52:53], s[6:7], v66, s37, v[142:143]
	v_lshl_add_u64 v[82:83], v[50:51], 0, s[84:85]
	v_add_co_u32_e32 v50, vcc, s16, v50
	v_lshl_add_u64 v[52:53], v[52:53], 0, v[194:195]
	s_nop 0
	v_addc_co_u32_e32 v51, vcc, 0, v51, vcc
	v_ashrrev_i32_e32 v79, 31, v78
	v_lshl_add_u64 v[104:105], v[52:53], 0, s[84:85]
	v_add_co_u32_e32 v52, vcc, s16, v52
	v_pk_mul_f32 v[98:99], v[54:55], s[36:37] op_sel_hi:[1,0]
	v_lshlrev_b64 v[54:55], 11, v[78:79]
	v_lshl_add_u64 v[56:57], v[56:57], 0, s[84:85]
	v_addc_co_u32_e32 v53, vcc, 0, v53, vcc
	v_pk_mul_f32 v[88:89], v[64:65], s[36:37] op_sel_hi:[1,0]
	v_pk_mul_f32 v[90:91], v[62:63], s[36:37] op_sel_hi:[1,0]
	v_lshl_add_u64 v[106:107], s[74:75], 0, v[54:55]
	global_load_dwordx4 v[62:65], v[56:57], off offset:256
	global_load_dwordx4 v[78:81], v[50:51], off offset:2048
	s_nop 0
	global_load_dwordx4 v[82:85], v[82:83], off offset:256
	s_nop 0
	global_load_dwordx4 v[54:57], v[52:53], off offset:2048
	s_nop 0
	global_load_dwordx4 v[50:53], v[104:105], off offset:256
	v_lshl_add_u64 v[104:105], v[106:107], 0, v[194:195]
	v_pk_mul_f32 v[46:47], v[46:47], s[36:37] op_sel_hi:[1,0]
	v_pk_mul_f32 v[48:49], v[48:49], s[36:37] op_sel_hi:[1,0]
	v_ashrrev_i32_e32 v87, 31, v86
	v_pk_mul_f32 v[38:39], v[38:39], s[36:37] op_sel_hi:[1,0]
	v_pk_mul_f32 v[40:41], v[40:41], s[36:37] op_sel_hi:[1,0]
	v_pk_mul_f32 v[30:31], v[30:31], s[36:37] op_sel_hi:[1,0]
	v_pk_mul_f32 v[32:33], v[32:33], s[36:37] op_sel_hi:[1,0]
	v_ashrrev_i32_e32 v69, 31, v68
	v_pk_mul_f32 v[22:23], v[22:23], s[36:37] op_sel_hi:[1,0]
	v_pk_mul_f32 v[24:25], v[24:25], s[36:37] op_sel_hi:[1,0]
	v_pk_mul_f32 v[14:15], v[14:15], s[36:37] op_sel_hi:[1,0]
	v_pk_mul_f32 v[16:17], v[16:17], s[36:37] op_sel_hi:[1,0]
	v_ashrrev_i32_e32 v67, 31, v66
	v_pk_mul_f32 v[6:7], v[6:7], s[36:37] op_sel_hi:[1,0]
	v_pk_mul_f32 v[8:9], v[8:9], s[36:37] op_sel_hi:[1,0]
	s_waitcnt vmcnt(0)
	v_lshlrev_b32_e32 v106, 16, v70
	v_and_b32_e32 v70, 0xffff0000, v70
	v_lshlrev_b32_e32 v107, 16, v71
	v_and_b32_e32 v71, 0xffff0000, v71
	v_lshlrev_b32_e32 v108, 16, v72
	v_and_b32_e32 v72, 0xffff0000, v72
	v_lshlrev_b32_e32 v109, 16, v73
	v_and_b32_e32 v73, 0xffff0000, v73
	v_mul_f32_e32 v70, v91, v70
	v_mul_f32_e32 v71, v89, v71
	v_mul_f32_e32 v72, v95, v72
	v_mul_f32_e32 v73, v93, v73
	v_mul_f32_e32 v90, v90, v106
	v_mul_f32_e32 v88, v88, v107
	v_mul_f32_e32 v89, v94, v108
	v_mul_f32_e32 v91, v92, v109
	v_cvt_pk_bf16_f32 v70, v90, v70
	v_cvt_pk_bf16_f32 v71, v88, v71
	v_cvt_pk_bf16_f32 v72, v89, v72
	v_cvt_pk_bf16_f32 v73, v91, v73
	v_lshlrev_b32_e32 v111, 16, v75
	v_and_b32_e32 v75, 0xffff0000, v75
	global_store_dwordx4 v[104:105], v[70:73], off
	v_lshlrev_b32_e32 v110, 16, v74
	v_and_b32_e32 v74, 0xffff0000, v74
	v_lshlrev_b32_e32 v72, 16, v76
	v_and_b32_e32 v73, 0xffff0000, v76
	v_mul_f32_e32 v71, v97, v75
	v_mul_f32_e32 v72, v102, v72
	v_mul_f32_e32 v73, v103, v73
	v_mul_f32_e32 v92, v98, v110
	v_mul_f32_e32 v74, v99, v74
	v_mul_f32_e32 v93, v96, v111
	v_cvt_pk_bf16_f32 v70, v92, v74
	v_cvt_pk_bf16_f32 v71, v93, v71
	v_cvt_pk_bf16_f32 v72, v72, v73
	v_lshlrev_b32_e32 v73, 16, v77
	v_mul_f32_e32 v73, v100, v73
	v_and_b32_e32 v74, 0xffff0000, v77
	v_mul_f32_e32 v74, v101, v74
	v_cvt_pk_bf16_f32 v73, v73, v74
	global_store_dwordx4 v[104:105], v[70:73], off offset:256
	s_nop 1
	v_pk_mul_f32 v[72:73], v[44:45], s[36:37] op_sel_hi:[1,0]
	v_pk_mul_f32 v[44:45], v[42:43], s[36:37] op_sel_hi:[1,0]
	v_lshlrev_b32_e32 v42, 16, v58
	v_and_b32_e32 v43, 0xffff0000, v58
	v_mul_f32_e32 v42, v46, v42
	v_mul_f32_e32 v43, v47, v43
	v_cvt_pk_bf16_f32 v42, v42, v43
	v_lshlrev_b32_e32 v43, 16, v59
	v_and_b32_e32 v46, 0xffff0000, v59
	v_mul_f32_e32 v43, v48, v43
	v_mul_f32_e32 v46, v49, v46
	v_cvt_pk_bf16_f32 v43, v43, v46
	v_lshlrev_b32_e32 v46, 16, v60
	v_mul_f32_e32 v44, v44, v46
	v_and_b32_e32 v46, 0xffff0000, v60
	v_mul_f32_e32 v45, v45, v46
	v_cvt_pk_bf16_f32 v44, v44, v45
	v_lshlrev_b32_e32 v45, 16, v61
	v_and_b32_e32 v46, 0xffff0000, v61
	v_lshlrev_b64 v[70:71], 11, v[86:87]
	v_mul_f32_e32 v45, v72, v45
	v_mul_f32_e32 v46, v73, v46
	v_cvt_pk_bf16_f32 v45, v45, v46
	v_lshl_add_u64 v[46:47], s[74:75], 0, v[70:71]
	v_lshl_add_u64 v[46:47], v[46:47], 0, v[194:195]
	global_store_dwordx4 v[46:47], v[42:45], off
	s_nop 1
	v_pk_mul_f32 v[42:43], v[36:37], s[36:37] op_sel_hi:[1,0]
	v_pk_mul_f32 v[36:37], v[34:35], s[36:37] op_sel_hi:[1,0]
	v_lshlrev_b32_e32 v34, 16, v62
	v_and_b32_e32 v35, 0xffff0000, v62
	v_mul_f32_e32 v34, v38, v34
	v_mul_f32_e32 v35, v39, v35
	v_cvt_pk_bf16_f32 v34, v34, v35
	v_lshlrev_b32_e32 v35, 16, v63
	v_and_b32_e32 v38, 0xffff0000, v63
	v_mul_f32_e32 v35, v40, v35
	v_mul_f32_e32 v38, v41, v38
	v_cvt_pk_bf16_f32 v35, v35, v38
	v_lshlrev_b32_e32 v38, 16, v64
	v_mul_f32_e32 v36, v36, v38
	v_and_b32_e32 v38, 0xffff0000, v64
	v_mul_f32_e32 v37, v37, v38
	v_cvt_pk_bf16_f32 v36, v36, v37
	v_lshlrev_b32_e32 v37, 16, v65
	v_mul_f32_e32 v37, v42, v37
	v_and_b32_e32 v38, 0xffff0000, v65
	v_mul_f32_e32 v38, v43, v38
	v_cvt_pk_bf16_f32 v37, v37, v38
	global_store_dwordx4 v[46:47], v[34:37], off offset:256
	s_nop 1
	v_pk_mul_f32 v[36:37], v[28:29], s[36:37] op_sel_hi:[1,0]
	v_pk_mul_f32 v[28:29], v[26:27], s[36:37] op_sel_hi:[1,0]
	v_lshlrev_b32_e32 v26, 16, v78
	v_and_b32_e32 v27, 0xffff0000, v78
	v_mul_f32_e32 v26, v30, v26
	v_mul_f32_e32 v27, v31, v27
	v_cvt_pk_bf16_f32 v26, v26, v27
	v_lshlrev_b32_e32 v27, 16, v79
	v_and_b32_e32 v30, 0xffff0000, v79
	v_mul_f32_e32 v27, v32, v27
	v_mul_f32_e32 v30, v33, v30
	v_cvt_pk_bf16_f32 v27, v27, v30
	v_lshlrev_b32_e32 v30, 16, v80
	v_mul_f32_e32 v28, v28, v30
	v_and_b32_e32 v30, 0xffff0000, v80
	v_mul_f32_e32 v29, v29, v30
	v_cvt_pk_bf16_f32 v28, v28, v29
	v_lshlrev_b32_e32 v29, 16, v81
	v_and_b32_e32 v30, 0xffff0000, v81
	v_lshlrev_b64 v[34:35], 11, v[68:69]
	v_mul_f32_e32 v29, v36, v29
	v_mul_f32_e32 v30, v37, v30
	v_cvt_pk_bf16_f32 v29, v29, v30
	v_lshl_add_u64 v[30:31], s[74:75], 0, v[34:35]
	v_lshl_add_u64 v[30:31], v[30:31], 0, v[194:195]
	global_store_dwordx4 v[30:31], v[26:29], off
	s_nop 1
	v_pk_mul_f32 v[26:27], v[20:21], s[36:37] op_sel_hi:[1,0]
	v_pk_mul_f32 v[20:21], v[18:19], s[36:37] op_sel_hi:[1,0]
	v_lshlrev_b32_e32 v18, 16, v82
	v_and_b32_e32 v19, 0xffff0000, v82
	v_mul_f32_e32 v18, v22, v18
	v_mul_f32_e32 v19, v23, v19
	v_cvt_pk_bf16_f32 v18, v18, v19
	v_lshlrev_b32_e32 v19, 16, v83
	v_and_b32_e32 v22, 0xffff0000, v83
	v_mul_f32_e32 v19, v24, v19
	v_mul_f32_e32 v22, v25, v22
	v_cvt_pk_bf16_f32 v19, v19, v22
	v_lshlrev_b32_e32 v22, 16, v84
	v_mul_f32_e32 v20, v20, v22
	v_and_b32_e32 v22, 0xffff0000, v84
	v_mul_f32_e32 v21, v21, v22
	v_cvt_pk_bf16_f32 v20, v20, v21
	v_lshlrev_b32_e32 v21, 16, v85
	v_mul_f32_e32 v21, v26, v21
	v_and_b32_e32 v22, 0xffff0000, v85
	v_mul_f32_e32 v22, v27, v22
	v_cvt_pk_bf16_f32 v21, v21, v22
	global_store_dwordx4 v[30:31], v[18:21], off offset:256
	s_nop 1
	v_pk_mul_f32 v[20:21], v[12:13], s[36:37] op_sel_hi:[1,0]
	v_pk_mul_f32 v[12:13], v[10:11], s[36:37] op_sel_hi:[1,0]
	v_lshlrev_b32_e32 v10, 16, v54
	v_and_b32_e32 v11, 0xffff0000, v54
	v_mul_f32_e32 v10, v14, v10
	v_mul_f32_e32 v11, v15, v11
	v_cvt_pk_bf16_f32 v10, v10, v11
	v_lshlrev_b32_e32 v11, 16, v55
	v_and_b32_e32 v14, 0xffff0000, v55
	v_mul_f32_e32 v11, v16, v11
	v_mul_f32_e32 v14, v17, v14
	v_cvt_pk_bf16_f32 v11, v11, v14
	v_lshlrev_b32_e32 v14, 16, v56
	v_mul_f32_e32 v12, v12, v14
	v_and_b32_e32 v14, 0xffff0000, v56
	v_mul_f32_e32 v13, v13, v14
	v_cvt_pk_bf16_f32 v12, v12, v13
	v_lshlrev_b32_e32 v13, 16, v57
	v_and_b32_e32 v14, 0xffff0000, v57
	v_lshlrev_b64 v[18:19], 11, v[66:67]
	v_mul_f32_e32 v13, v20, v13
	v_mul_f32_e32 v14, v21, v14
	v_cvt_pk_bf16_f32 v13, v13, v14
	v_lshl_add_u64 v[14:15], s[74:75], 0, v[18:19]
	v_lshl_add_u64 v[14:15], v[14:15], 0, v[194:195]
	global_store_dwordx4 v[14:15], v[10:13], off
	s_nop 1
	v_pk_mul_f32 v[10:11], v[4:5], s[36:37] op_sel_hi:[1,0]
	v_pk_mul_f32 v[4:5], v[2:3], s[36:37] op_sel_hi:[1,0]
	v_lshlrev_b32_e32 v2, 16, v50
	v_and_b32_e32 v3, 0xffff0000, v50
	v_mul_f32_e32 v2, v6, v2
	v_mul_f32_e32 v3, v7, v3
	v_cvt_pk_bf16_f32 v2, v2, v3
	v_lshlrev_b32_e32 v3, 16, v51
	v_and_b32_e32 v6, 0xffff0000, v51
	v_mul_f32_e32 v3, v8, v3
	v_mul_f32_e32 v6, v9, v6
	v_cvt_pk_bf16_f32 v3, v3, v6
	v_lshlrev_b32_e32 v6, 16, v52
	v_mul_f32_e32 v4, v4, v6
	v_and_b32_e32 v6, 0xffff0000, v52
	v_mul_f32_e32 v5, v5, v6
	v_cvt_pk_bf16_f32 v4, v4, v5
	v_lshlrev_b32_e32 v5, 16, v53
	v_mul_f32_e32 v5, v10, v5
	v_and_b32_e32 v6, 0xffff0000, v53
	v_mul_f32_e32 v6, v11, v6
	v_cvt_pk_bf16_f32 v5, v5, v6
	global_store_dwordx4 v[14:15], v[2:5], off offset:256
	s_and_b64 vcc, exec, s[52:53]
	s_mov_b32 s28, s4
	s_cbranch_vccz .LBB0_265
	s_waitcnt vmcnt(0)
	v_readlane_b32 s28, v250, 12
	s_cmpk_gt_u32 s12, 0xff
	v_readlane_b32 s29, v250, 13
	s_mov_b32 s70, 0x800000
	s_cbranch_scc1 .LBB0_270
	s_barrier

.LBB0_368:
	v_add_u32_e32 v253, 0x10000, v201
	ds_read_b128 v[130:133], v253
	ds_read_b128 v[134:137], v253 offset:1024
	ds_read_b128 v[138:141], v253 offset:2048
	ds_read_b128 v[142:145], v253 offset:3072
	s_add_u32 s10, s8, 0xfffc0080
	s_addc_u32 s11, s9, -1
	s_cmp_eq_u32 s29, 12
	s_cselect_b32 s11, s81, s11
	s_cselect_b32 s10, s80, s10
	s_cselect_b32 s53, s83, s28
	s_cselect_b32 s52, s82, s7
	s_add_i32 m0, s34, 0xc000
	ds_read_b128 v[146:149], v199
	ds_read_b128 v[150:153], v199 offset:1024
	ds_read_b128 v[154:157], v199 offset:2048
	ds_read_b128 v[158:161], v199 offset:3072
	ds_read_b128 v[162:165], v199 offset:4096
	ds_read_b128 v[166:169], v199 offset:5120
	ds_read_b128 v[170:173], v199 offset:6144
	ds_read_b128 v[174:177], v199 offset:7168
	global_load_lds_dwordx4 v212, s[8:9]
	s_add_i32 m0, s34, 0xe000
	s_nop 0
	global_load_lds_dwordx4 v214, s[8:9]
	s_waitcnt lgkmcnt(8)
	s_setprio 1
	s_barrier
	s_waitcnt lgkmcnt(0)
	v_mfma_f32_16x16x32_bf16 v[126:129], v[130:133], v[146:149], v[126:129]
	v_mfma_f32_16x16x32_bf16 v[122:125], v[138:141], v[146:149], v[122:125]
	v_mfma_f32_16x16x32_bf16 v[118:121], v[130:133], v[154:157], v[118:121]
	v_mfma_f32_16x16x32_bf16 v[114:117], v[138:141], v[154:157], v[114:117]
	v_mfma_f32_16x16x32_bf16 v[110:113], v[130:133], v[162:165], v[110:113]
	v_mfma_f32_16x16x32_bf16 v[106:109], v[138:141], v[162:165], v[106:109]
	v_mfma_f32_16x16x32_bf16 v[102:105], v[130:133], v[170:173], v[102:105]
	v_mfma_f32_16x16x32_bf16 v[98:101], v[138:141], v[170:173], v[98:101]
	v_mfma_f32_16x16x32_bf16 v[126:129], v[134:137], v[150:153], v[126:129]
	v_mfma_f32_16x16x32_bf16 v[122:125], v[142:145], v[150:153], v[122:125]
	v_mfma_f32_16x16x32_bf16 v[118:121], v[134:137], v[158:161], v[118:121]
	v_mfma_f32_16x16x32_bf16 v[114:117], v[142:145], v[158:161], v[114:117]
	v_mfma_f32_16x16x32_bf16 v[110:113], v[134:137], v[166:169], v[110:113]
	v_mfma_f32_16x16x32_bf16 v[106:109], v[142:145], v[166:169], v[106:109]
	v_mfma_f32_16x16x32_bf16 v[102:105], v[134:137], v[174:177], v[102:105]
	v_mfma_f32_16x16x32_bf16 v[98:101], v[142:145], v[174:177], v[98:101]
	s_barrier
	s_setprio 0
	s_mov_b32 m0, s35
	v_lshl_add_u64 v[216:217], s[52:53], 0, v[194:195]
	ds_read_b128 v[178:181], v253 offset:16384
	ds_read_b128 v[182:185], v253 offset:17408
	ds_read_b128 v[186:189], v253 offset:18432
	ds_read_b128 v[190:193], v253 offset:19456
	global_load_lds_dwordx4 v[216:217], off
	v_lshl_add_u64 v[218:219], s[52:53], 0, v[210:211]
	s_mov_b32 m0, s42
	s_nop 0
	global_load_lds_dwordx4 v[218:219], off
	s_setprio 1
	s_barrier
	s_waitcnt lgkmcnt(0)
	v_mfma_f32_16x16x32_bf16 v[94:97], v[178:181], v[146:149], v[94:97]
	v_mfma_f32_16x16x32_bf16 v[90:93], v[186:189], v[146:149], v[90:93]
	v_mfma_f32_16x16x32_bf16 v[86:89], v[178:181], v[154:157], v[86:89]
	v_mfma_f32_16x16x32_bf16 v[82:85], v[186:189], v[154:157], v[82:85]
	v_mfma_f32_16x16x32_bf16 v[78:81], v[178:181], v[162:165], v[78:81]
	v_mfma_f32_16x16x32_bf16 v[74:77], v[186:189], v[162:165], v[74:77]
	v_mfma_f32_16x16x32_bf16 v[70:73], v[178:181], v[170:173], v[70:73]
	v_mfma_f32_16x16x32_bf16 v[66:69], v[186:189], v[170:173], v[66:69]
	v_mfma_f32_16x16x32_bf16 v[94:97], v[182:185], v[150:153], v[94:97]
	v_mfma_f32_16x16x32_bf16 v[90:93], v[190:193], v[150:153], v[90:93]
	v_mfma_f32_16x16x32_bf16 v[86:89], v[182:185], v[158:161], v[86:89]
	v_mfma_f32_16x16x32_bf16 v[82:85], v[190:193], v[158:161], v[82:85]
	v_mfma_f32_16x16x32_bf16 v[78:81], v[182:185], v[166:169], v[78:81]
	v_mfma_f32_16x16x32_bf16 v[74:77], v[190:193], v[166:169], v[74:77]
	s_mov_b32 m0, s34
	v_mfma_f32_16x16x32_bf16 v[70:73], v[182:185], v[174:177], v[70:73]
	v_lshl_add_u64 v[220:221], s[10:11], 0, v[206:207]
	v_mfma_f32_16x16x32_bf16 v[66:69], v[190:193], v[174:177], v[66:69]
	s_barrier
	s_setprio 0
	ds_read_b128 v[146:149], v199 offset:16384
	ds_read_b128 v[150:153], v199 offset:17408
	ds_read_b128 v[154:157], v199 offset:18432
	ds_read_b128 v[158:161], v199 offset:19456
	ds_read_b128 v[162:165], v199 offset:20480
	ds_read_b128 v[166:169], v199 offset:21504
	ds_read_b128 v[170:173], v199 offset:22528
	ds_read_b128 v[174:177], v199 offset:23552
	global_load_lds_dwordx4 v[220:221], off
	v_lshl_add_u64 v[222:223], s[10:11], 0, v[208:209]
	s_mov_b32 m0, s56
	s_nop 0
	global_load_lds_dwordx4 v[222:223], off
	s_setprio 1
	s_barrier
	s_waitcnt lgkmcnt(0)
	v_mfma_f32_16x16x32_bf16 v[62:65], v[130:133], v[146:149], v[62:65]
	v_mfma_f32_16x16x32_bf16 v[58:61], v[138:141], v[146:149], v[58:61]
	v_mfma_f32_16x16x32_bf16 v[54:57], v[130:133], v[154:157], v[54:57]
	v_mfma_f32_16x16x32_bf16 v[50:53], v[138:141], v[154:157], v[50:53]
	v_mfma_f32_16x16x32_bf16 v[46:49], v[130:133], v[162:165], v[46:49]
	v_mfma_f32_16x16x32_bf16 v[42:45], v[138:141], v[162:165], v[42:45]
	v_mfma_f32_16x16x32_bf16 v[38:41], v[130:133], v[170:173], v[38:41]
	v_mfma_f32_16x16x32_bf16 v[34:37], v[138:141], v[170:173], v[34:37]
	v_mfma_f32_16x16x32_bf16 v[62:65], v[134:137], v[150:153], v[62:65]
	v_mfma_f32_16x16x32_bf16 v[58:61], v[142:145], v[150:153], v[58:61]
	v_mfma_f32_16x16x32_bf16 v[54:57], v[134:137], v[158:161], v[54:57]
	v_mfma_f32_16x16x32_bf16 v[50:53], v[142:145], v[158:161], v[50:53]
	v_mfma_f32_16x16x32_bf16 v[46:49], v[134:137], v[166:169], v[46:49]
	v_mfma_f32_16x16x32_bf16 v[42:45], v[142:145], v[166:169], v[42:45]
	v_mfma_f32_16x16x32_bf16 v[38:41], v[134:137], v[174:177], v[38:41]
	v_mfma_f32_16x16x32_bf16 v[34:37], v[142:145], v[174:177], v[34:37]
	s_barrier
	s_setprio 0
	s_add_u32 s86, s52, 0x40000
	s_addc_u32 s87, s53, 0
	s_mov_b32 m0, s57
	s_nop 0
	global_load_lds_dwordx4 v194, s[86:87]
	s_mov_b32 m0, s67
	s_nop 0
	global_load_lds_dwordx4 v210, s[86:87]
	s_waitcnt vmcnt(6)
	s_setprio 1
	s_barrier
	v_mfma_f32_16x16x32_bf16 v[30:33], v[178:181], v[146:149], v[30:33]
	v_mfma_f32_16x16x32_bf16 v[26:29], v[186:189], v[146:149], v[26:29]
	v_mfma_f32_16x16x32_bf16 v[22:25], v[178:181], v[154:157], v[22:25]
	v_mfma_f32_16x16x32_bf16 v[18:21], v[186:189], v[154:157], v[18:21]
	v_mfma_f32_16x16x32_bf16 v[14:17], v[178:181], v[162:165], v[14:17]
	v_mfma_f32_16x16x32_bf16 v[10:13], v[186:189], v[162:165], v[10:13]
	v_mfma_f32_16x16x32_bf16 v[6:9], v[178:181], v[170:173], v[6:9]
	v_mfma_f32_16x16x32_bf16 v[2:5], v[186:189], v[170:173], v[2:5]
	v_mfma_f32_16x16x32_bf16 v[30:33], v[182:185], v[150:153], v[30:33]
	v_mfma_f32_16x16x32_bf16 v[26:29], v[190:193], v[150:153], v[26:29]
	v_mfma_f32_16x16x32_bf16 v[22:25], v[182:185], v[158:161], v[22:25]
	v_mfma_f32_16x16x32_bf16 v[18:21], v[190:193], v[158:161], v[18:21]
	v_mfma_f32_16x16x32_bf16 v[14:17], v[182:185], v[166:169], v[14:17]
	v_mfma_f32_16x16x32_bf16 v[10:13], v[190:193], v[166:169], v[10:13]
	v_mfma_f32_16x16x32_bf16 v[6:9], v[182:185], v[174:177], v[6:9]
	v_mfma_f32_16x16x32_bf16 v[2:5], v[190:193], v[174:177], v[2:5]
	s_barrier
	s_setprio 0
	ds_read_b128 v[130:133], v253 offset:32768
	ds_read_b128 v[134:137], v253 offset:33792
	ds_read_b128 v[138:141], v253 offset:34816
	ds_read_b128 v[142:145], v253 offset:35840
	s_add_u32 s10, s10, 0x40000
	s_addc_u32 s11, s11, 0
	s_mov_b32 m0, s70
	ds_read_b128 v[146:149], v199 offset:32768
	ds_read_b128 v[150:153], v199 offset:33792
	ds_read_b128 v[154:157], v199 offset:34816
	ds_read_b128 v[158:161], v199 offset:35840
	ds_read_b128 v[162:165], v199 offset:36864
	ds_read_b128 v[166:169], v199 offset:37888
	ds_read_b128 v[170:173], v199 offset:38912
	ds_read_b128 v[174:177], v199 offset:39936
	global_load_lds_dwordx4 v206, s[10:11]
	s_mov_b32 m0, s71
	s_nop 0
	global_load_lds_dwordx4 v208, s[10:11]
	s_waitcnt lgkmcnt(8)
	s_setprio 1
	s_barrier
	s_waitcnt lgkmcnt(0)
	v_mfma_f32_16x16x32_bf16 v[126:129], v[130:133], v[146:149], v[126:129]
	v_mfma_f32_16x16x32_bf16 v[122:125], v[138:141], v[146:149], v[122:125]
	v_mfma_f32_16x16x32_bf16 v[118:121], v[130:133], v[154:157], v[118:121]
	v_mfma_f32_16x16x32_bf16 v[114:117], v[138:141], v[154:157], v[114:117]
	v_mfma_f32_16x16x32_bf16 v[110:113], v[130:133], v[162:165], v[110:113]
	v_mfma_f32_16x16x32_bf16 v[106:109], v[138:141], v[162:165], v[106:109]
	v_mfma_f32_16x16x32_bf16 v[102:105], v[130:133], v[170:173], v[102:105]
	v_mfma_f32_16x16x32_bf16 v[98:101], v[138:141], v[170:173], v[98:101]
	v_mfma_f32_16x16x32_bf16 v[126:129], v[134:137], v[150:153], v[126:129]
	v_mfma_f32_16x16x32_bf16 v[122:125], v[142:145], v[150:153], v[122:125]
	v_mfma_f32_16x16x32_bf16 v[118:121], v[134:137], v[158:161], v[118:121]
	v_mfma_f32_16x16x32_bf16 v[114:117], v[142:145], v[158:161], v[114:117]
	v_mfma_f32_16x16x32_bf16 v[110:113], v[134:137], v[166:169], v[110:113]
	v_mfma_f32_16x16x32_bf16 v[106:109], v[142:145], v[166:169], v[106:109]
	v_mfma_f32_16x16x32_bf16 v[102:105], v[134:137], v[174:177], v[102:105]
	v_mfma_f32_16x16x32_bf16 v[98:101], v[142:145], v[174:177], v[98:101]
	s_barrier
	s_setprio 0
	s_mov_b32 m0, s78
	v_lshl_add_u64 v[216:217], v[216:217], 0, s[76:77]
	ds_read_b128 v[178:181], v253 offset:49152
	ds_read_b128 v[182:185], v253 offset:50176
	ds_read_b128 v[186:189], v253 offset:51200
	ds_read_b128 v[190:193], v253 offset:52224
	global_load_lds_dwordx4 v[216:217], off
	v_lshl_add_u64 v[216:217], v[218:219], 0, s[76:77]
	s_mov_b32 m0, s79
	s_nop 0
	global_load_lds_dwordx4 v[216:217], off
	s_setprio 1
	s_barrier
	s_waitcnt lgkmcnt(0)
	v_mfma_f32_16x16x32_bf16 v[94:97], v[178:181], v[146:149], v[94:97]
	v_mfma_f32_16x16x32_bf16 v[90:93], v[186:189], v[146:149], v[90:93]
	v_mfma_f32_16x16x32_bf16 v[86:89], v[178:181], v[154:157], v[86:89]
	v_mfma_f32_16x16x32_bf16 v[82:85], v[186:189], v[154:157], v[82:85]
	v_mfma_f32_16x16x32_bf16 v[78:81], v[178:181], v[162:165], v[78:81]
	v_mfma_f32_16x16x32_bf16 v[74:77], v[186:189], v[162:165], v[74:77]
	v_mfma_f32_16x16x32_bf16 v[70:73], v[178:181], v[170:173], v[70:73]
	v_mfma_f32_16x16x32_bf16 v[66:69], v[186:189], v[170:173], v[66:69]
	v_mfma_f32_16x16x32_bf16 v[94:97], v[182:185], v[150:153], v[94:97]
	v_mfma_f32_16x16x32_bf16 v[90:93], v[190:193], v[150:153], v[90:93]
	v_mfma_f32_16x16x32_bf16 v[86:89], v[182:185], v[158:161], v[86:89]
	v_mfma_f32_16x16x32_bf16 v[82:85], v[190:193], v[158:161], v[82:85]
	v_mfma_f32_16x16x32_bf16 v[78:81], v[182:185], v[166:169], v[78:81]
	v_mfma_f32_16x16x32_bf16 v[74:77], v[190:193], v[166:169], v[74:77]
	s_mov_b32 m0, s26
	v_mfma_f32_16x16x32_bf16 v[70:73], v[182:185], v[174:177], v[70:73]
	v_lshl_add_u64 v[216:217], v[220:221], 0, s[76:77]
	v_mfma_f32_16x16x32_bf16 v[66:69], v[190:193], v[174:177], v[66:69]
	s_barrier
	s_setprio 0
	ds_read_b128 v[146:149], v199 offset:49152
	ds_read_b128 v[150:153], v199 offset:50176
	ds_read_b128 v[154:157], v199 offset:51200
	ds_read_b128 v[158:161], v199 offset:52224
	ds_read_b128 v[162:165], v199 offset:53248
	ds_read_b128 v[166:169], v199 offset:54272
	ds_read_b128 v[170:173], v199 offset:55296
	ds_read_b128 v[174:177], v199 offset:56320
	global_load_lds_dwordx4 v[216:217], off
	v_lshl_add_u64 v[216:217], v[222:223], 0, s[76:77]
	s_mov_b32 m0, s4
	s_nop 0
	global_load_lds_dwordx4 v[216:217], off
	s_setprio 1
	s_barrier
	s_waitcnt lgkmcnt(0)
	v_mfma_f32_16x16x32_bf16 v[62:65], v[130:133], v[146:149], v[62:65]
	v_mfma_f32_16x16x32_bf16 v[58:61], v[138:141], v[146:149], v[58:61]
	v_mfma_f32_16x16x32_bf16 v[54:57], v[130:133], v[154:157], v[54:57]
	v_mfma_f32_16x16x32_bf16 v[50:53], v[138:141], v[154:157], v[50:53]
	v_mfma_f32_16x16x32_bf16 v[46:49], v[130:133], v[162:165], v[46:49]
	v_mfma_f32_16x16x32_bf16 v[42:45], v[138:141], v[162:165], v[42:45]
	v_mfma_f32_16x16x32_bf16 v[38:41], v[130:133], v[170:173], v[38:41]
	v_mfma_f32_16x16x32_bf16 v[34:37], v[138:141], v[170:173], v[34:37]
	v_mfma_f32_16x16x32_bf16 v[62:65], v[134:137], v[150:153], v[62:65]
	v_mfma_f32_16x16x32_bf16 v[58:61], v[142:145], v[150:153], v[58:61]
	v_mfma_f32_16x16x32_bf16 v[54:57], v[134:137], v[158:161], v[54:57]
	v_mfma_f32_16x16x32_bf16 v[50:53], v[142:145], v[158:161], v[50:53]
	v_mfma_f32_16x16x32_bf16 v[46:49], v[134:137], v[166:169], v[46:49]
	v_mfma_f32_16x16x32_bf16 v[42:45], v[142:145], v[166:169], v[42:45]
	v_mfma_f32_16x16x32_bf16 v[38:41], v[134:137], v[174:177], v[38:41]
	v_mfma_f32_16x16x32_bf16 v[34:37], v[142:145], v[174:177], v[34:37]
	s_barrier
	s_setprio 0
	s_add_u32 s10, s52, 0x40080
	s_addc_u32 s11, s53, 0
	s_mov_b32 m0, s5
	s_nop 0
	global_load_lds_dwordx4 v194, s[10:11]
	s_mov_b32 m0, s58
	s_nop 0
	global_load_lds_dwordx4 v210, s[10:11]
	s_waitcnt vmcnt(6)
	s_setprio 1
	s_barrier
	v_mfma_f32_16x16x32_bf16 v[30:33], v[178:181], v[146:149], v[30:33]
	v_mfma_f32_16x16x32_bf16 v[26:29], v[186:189], v[146:149], v[26:29]
	v_mfma_f32_16x16x32_bf16 v[22:25], v[178:181], v[154:157], v[22:25]
	v_mfma_f32_16x16x32_bf16 v[18:21], v[186:189], v[154:157], v[18:21]
	v_mfma_f32_16x16x32_bf16 v[14:17], v[178:181], v[162:165], v[14:17]
	v_mfma_f32_16x16x32_bf16 v[10:13], v[186:189], v[162:165], v[10:13]
	v_mfma_f32_16x16x32_bf16 v[6:9], v[178:181], v[170:173], v[6:9]
	v_mfma_f32_16x16x32_bf16 v[2:5], v[186:189], v[170:173], v[2:5]
	v_mfma_f32_16x16x32_bf16 v[30:33], v[182:185], v[150:153], v[30:33]
	v_mfma_f32_16x16x32_bf16 v[26:29], v[190:193], v[150:153], v[26:29]
	v_mfma_f32_16x16x32_bf16 v[22:25], v[182:185], v[158:161], v[22:25]
	v_mfma_f32_16x16x32_bf16 v[18:21], v[190:193], v[158:161], v[18:21]
	v_mfma_f32_16x16x32_bf16 v[14:17], v[182:185], v[166:169], v[14:17]
	v_mfma_f32_16x16x32_bf16 v[10:13], v[190:193], v[166:169], v[10:13]
	v_mfma_f32_16x16x32_bf16 v[6:9], v[182:185], v[174:177], v[6:9]
	v_mfma_f32_16x16x32_bf16 v[2:5], v[190:193], v[174:177], v[2:5]
	s_setprio 0
	s_add_i32 s29, s29, 2
	s_add_u32 s8, s8, 0x100
	s_addc_u32 s9, s9, 0
	s_add_u32 s7, s7, 0x100
	s_addc_u32 s28, s28, 0
	s_cmp_gt_u32 s29, 13
	s_barrier
	s_cbranch_scc0 .LBB0_368
	s_cmp_gt_i32 s95, 1
	s_cselect_b64 s[52:53], -1, 0
	s_mul_i32 s7, s6, 0x680000
	s_lshl_b32 s8, s95, 12
	s_lshl_b32 s9, s54, 9
	s_add_i32 s7, s7, s8
	s_add_i32 s7, s7, s9
	s_add_i32 s7, s7, 0x3800
	s_add_u32 s20, s50, s7
	s_addc_u32 s21, s51, 0
	s_lshl_b32 s7, s6, 20
	s_add_i32 s7, s7, s9
	s_add_u32 s10, s96, s7
	s_addc_u32 s11, s97, 0
	s_mov_b32 s86, 0xbfb8aa3b
	s_mov_b32 s87, 0xbfb8aa3b
	v_mul_u32_u24_e32 v253, 0x6800, v197
	v_lshlrev_b32_e32 v255, 12, v197
	v_lshl_add_u32 v253, v203, 1, v253
	v_lshl_add_u32 v255, v203, 1, v255
	v_add_u32_e32 v254, 0x1000, v253
	s_cmp_eq_u32 s95, 2
	s_cbranch_scc1 .Lem_br2
	global_load_dwordx4 v[130:133], v253, s[20:21]
	global_load_dwordx4 v[134:137], v254, s[20:21]
	global_load_dwordx4 v[138:141], v253, s[20:21] offset:256
	global_load_dwordx4 v[142:145], v254, s[20:21] offset:256
	s_add_u32 s28, s20, 0x68000
	s_addc_u32 s29, s21, 0
	global_load_dwordx4 v[146:149], v253, s[28:29]
	global_load_dwordx4 v[150:153], v254, s[28:29]
	global_load_dwordx4 v[154:157], v253, s[28:29] offset:256
	global_load_dwordx4 v[158:161], v254, s[28:29] offset:256
	s_add_u32 s28, s20, 0xd0000
	s_addc_u32 s29, s21, 0
	global_load_dwordx4 v[162:165], v253, s[28:29]
	global_load_dwordx4 v[166:169], v254, s[28:29]
	global_load_dwordx4 v[170:173], v253, s[28:29] offset:256
	global_load_dwordx4 v[174:177], v254, s[28:29] offset:256
	s_add_u32 s28, s20, 0x138000
	s_addc_u32 s29, s21, 0
	global_load_dwordx4 v[178:181], v253, s[28:29]
	global_load_dwordx4 v[182:185], v254, s[28:29]
	global_load_dwordx4 v[186:189], v253, s[28:29] offset:256
	global_load_dwordx4 v[190:193], v254, s[28:29] offset:256
	s_waitcnt vmcnt(12)
	v_lshlrev_b32_e32 v216, 16, v130
	v_and_b32_e32 v217, 0xffff0000, v130
	v_lshlrev_b32_e32 v218, 16, v131
	v_and_b32_e32 v219, 0xffff0000, v131
	v_lshlrev_b32_e32 v220, 16, v132
	v_and_b32_e32 v221, 0xffff0000, v132
	v_lshlrev_b32_e32 v222, 16, v133
	v_and_b32_e32 v223, 0xffff0000, v133
	v_pk_mul_f32 v[216:217], v[216:217], s[86:87] op_sel_hi:[1,0]
	v_pk_mul_f32 v[218:219], v[218:219], s[86:87] op_sel_hi:[1,0]
	v_pk_mul_f32 v[220:221], v[220:221], s[86:87] op_sel_hi:[1,0]
	v_pk_mul_f32 v[222:223], v[222:223], s[86:87] op_sel_hi:[1,0]
	v_exp_f32_e32 v216, v216
	v_exp_f32_e32 v217, v217
	v_exp_f32_e32 v218, v218
	v_exp_f32_e32 v219, v219
	v_exp_f32_e32 v220, v220
	v_exp_f32_e32 v221, v221
	v_exp_f32_e32 v222, v222
	v_exp_f32_e32 v223, v223
	v_pk_add_f32 v[216:217], v[216:217], 1.0 op_sel_hi:[1,0]
	v_pk_add_f32 v[218:219], v[218:219], 1.0 op_sel_hi:[1,0]
	v_pk_add_f32 v[220:221], v[220:221], 1.0 op_sel_hi:[1,0]
	v_pk_add_f32 v[222:223], v[222:223], 1.0 op_sel_hi:[1,0]
	v_rcp_f32_e32 v216, v216
	v_rcp_f32_e32 v217, v217
	v_rcp_f32_e32 v218, v218
	v_rcp_f32_e32 v219, v219
	v_rcp_f32_e32 v220, v220
	v_rcp_f32_e32 v221, v221
	v_rcp_f32_e32 v222, v222
	v_rcp_f32_e32 v223, v223
	v_lshlrev_b32_e32 v242, 16, v134
	v_and_b32_e32 v243, 0xffff0000, v134
	v_lshlrev_b32_e32 v244, 16, v135
	v_and_b32_e32 v245, 0xffff0000, v135
	v_lshlrev_b32_e32 v246, 16, v136
	v_and_b32_e32 v247, 0xffff0000, v136
	v_lshlrev_b32_e32 v248, 16, v137
	v_and_b32_e32 v249, 0xffff0000, v137
	v_pk_mul_f32 v[242:243], v[242:243], s[86:87] op_sel_hi:[1,0]
	v_pk_mul_f32 v[244:245], v[244:245], s[86:87] op_sel_hi:[1,0]
	v_pk_mul_f32 v[246:247], v[246:247], s[86:87] op_sel_hi:[1,0]
	v_pk_mul_f32 v[248:249], v[248:249], s[86:87] op_sel_hi:[1,0]
	v_exp_f32_e32 v242, v242
	v_exp_f32_e32 v243, v243
	v_exp_f32_e32 v244, v244
	v_exp_f32_e32 v245, v245
	v_exp_f32_e32 v246, v246
	v_exp_f32_e32 v247, v247
	v_exp_f32_e32 v248, v248
	v_exp_f32_e32 v249, v249
	v_pk_add_f32 v[242:243], v[242:243], 1.0 op_sel_hi:[1,0]
	v_pk_add_f32 v[244:245], v[244:245], 1.0 op_sel_hi:[1,0]
	v_pk_add_f32 v[246:247], v[246:247], 1.0 op_sel_hi:[1,0]
	v_pk_add_f32 v[248:249], v[248:249], 1.0 op_sel_hi:[1,0]
	v_pk_mul_f32 v[216:217], v[216:217], v[242:243]
	v_pk_mul_f32 v[218:219], v[218:219], v[244:245]
	v_pk_mul_f32 v[220:221], v[220:221], v[246:247]
	v_pk_mul_f32 v[222:223], v[222:223], v[248:249]
	v_pk_mul_f32 v[126:127], v[126:127], v[216:217]
	v_pk_mul_f32 v[128:129], v[128:129], v[218:219]
	v_pk_mul_f32 v[122:123], v[122:123], v[220:221]
	v_pk_mul_f32 v[124:125], v[124:125], v[222:223]
	v_lshlrev_b32_e32 v216, 16, v138
	v_and_b32_e32 v217, 0xffff0000, v138
	v_lshlrev_b32_e32 v218, 16, v139
	v_and_b32_e32 v219, 0xffff0000, v139
	v_lshlrev_b32_e32 v220, 16, v140
	v_and_b32_e32 v221, 0xffff0000, v140
	v_lshlrev_b32_e32 v222, 16, v141
	v_and_b32_e32 v223, 0xffff0000, v141
	v_pk_mul_f32 v[216:217], v[216:217], s[86:87] op_sel_hi:[1,0]
	v_pk_mul_f32 v[218:219], v[218:219], s[86:87] op_sel_hi:[1,0]
	v_pk_mul_f32 v[220:221], v[220:221], s[86:87] op_sel_hi:[1,0]
	v_pk_mul_f32 v[222:223], v[222:223], s[86:87] op_sel_hi:[1,0]
	v_exp_f32_e32 v216, v216
	v_exp_f32_e32 v217, v217
	v_exp_f32_e32 v218, v218
	v_exp_f32_e32 v219, v219
	v_exp_f32_e32 v220, v220
	v_exp_f32_e32 v221, v221
	v_exp_f32_e32 v222, v222
	v_exp_f32_e32 v223, v223
	v_pk_add_f32 v[216:217], v[216:217], 1.0 op_sel_hi:[1,0]
	v_pk_add_f32 v[218:219], v[218:219], 1.0 op_sel_hi:[1,0]
	v_pk_add_f32 v[220:221], v[220:221], 1.0 op_sel_hi:[1,0]
	v_pk_add_f32 v[222:223], v[222:223], 1.0 op_sel_hi:[1,0]
	v_rcp_f32_e32 v216, v216
	v_rcp_f32_e32 v217, v217
	v_rcp_f32_e32 v218, v218
	v_rcp_f32_e32 v219, v219
	v_rcp_f32_e32 v220, v220
	v_rcp_f32_e32 v221, v221
	v_rcp_f32_e32 v222, v222
	v_rcp_f32_e32 v223, v223
	v_lshlrev_b32_e32 v242, 16, v142
	v_and_b32_e32 v243, 0xffff0000, v142
	v_lshlrev_b32_e32 v244, 16, v143
	v_and_b32_e32 v245, 0xffff0000, v143
	v_lshlrev_b32_e32 v246, 16, v144
	v_and_b32_e32 v247, 0xffff0000, v144
	v_lshlrev_b32_e32 v248, 16, v145
	v_and_b32_e32 v249, 0xffff0000, v145
	v_pk_mul_f32 v[242:243], v[242:243], s[86:87] op_sel_hi:[1,0]
	v_pk_mul_f32 v[244:245], v[244:245], s[86:87] op_sel_hi:[1,0]
	v_pk_mul_f32 v[246:247], v[246:247], s[86:87] op_sel_hi:[1,0]
	v_pk_mul_f32 v[248:249], v[248:249], s[86:87] op_sel_hi:[1,0]
	v_exp_f32_e32 v242, v242
	v_exp_f32_e32 v243, v243
	v_exp_f32_e32 v244, v244
	v_exp_f32_e32 v245, v245
	v_exp_f32_e32 v246, v246
	v_exp_f32_e32 v247, v247
	v_exp_f32_e32 v248, v248
	v_exp_f32_e32 v249, v249
	v_pk_add_f32 v[242:243], v[242:243], 1.0 op_sel_hi:[1,0]
	v_pk_add_f32 v[244:245], v[244:245], 1.0 op_sel_hi:[1,0]
	v_pk_add_f32 v[246:247], v[246:247], 1.0 op_sel_hi:[1,0]
	v_pk_add_f32 v[248:249], v[248:249], 1.0 op_sel_hi:[1,0]
	v_pk_mul_f32 v[216:217], v[216:217], v[242:243]
	v_pk_mul_f32 v[218:219], v[218:219], v[244:245]
	v_pk_mul_f32 v[220:221], v[220:221], v[246:247]
	v_pk_mul_f32 v[222:223], v[222:223], v[248:249]
	v_pk_mul_f32 v[94:95], v[94:95], v[216:217]
	v_pk_mul_f32 v[96:97], v[96:97], v[218:219]
	v_pk_mul_f32 v[90:91], v[90:91], v[220:221]
	v_pk_mul_f32 v[92:93], v[92:93], v[222:223]
	s_add_u32 s28, s20, 0x340000
	s_addc_u32 s29, s21, 0
	global_load_dwordx4 v[130:133], v253, s[28:29]
	global_load_dwordx4 v[134:137], v254, s[28:29]
	global_load_dwordx4 v[138:141], v253, s[28:29] offset:256
	global_load_dwordx4 v[142:145], v254, s[28:29] offset:256
	s_waitcnt vmcnt(12)
	v_lshlrev_b32_e32 v216, 16, v146
	v_and_b32_e32 v217, 0xffff0000, v146
	v_lshlrev_b32_e32 v218, 16, v147
	v_and_b32_e32 v219, 0xffff0000, v147
	v_lshlrev_b32_e32 v220, 16, v148
	v_and_b32_e32 v221, 0xffff0000, v148
	v_lshlrev_b32_e32 v222, 16, v149
	v_and_b32_e32 v223, 0xffff0000, v149
	v_pk_mul_f32 v[216:217], v[216:217], s[86:87] op_sel_hi:[1,0]
	v_pk_mul_f32 v[218:219], v[218:219], s[86:87] op_sel_hi:[1,0]
	v_pk_mul_f32 v[220:221], v[220:221], s[86:87] op_sel_hi:[1,0]
	v_pk_mul_f32 v[222:223], v[222:223], s[86:87] op_sel_hi:[1,0]
	v_exp_f32_e32 v216, v216
	v_exp_f32_e32 v217, v217
	v_exp_f32_e32 v218, v218
	v_exp_f32_e32 v219, v219
	v_exp_f32_e32 v220, v220
	v_exp_f32_e32 v221, v221
	v_exp_f32_e32 v222, v222
	v_exp_f32_e32 v223, v223
	v_pk_add_f32 v[216:217], v[216:217], 1.0 op_sel_hi:[1,0]
	v_pk_add_f32 v[218:219], v[218:219], 1.0 op_sel_hi:[1,0]
	v_pk_add_f32 v[220:221], v[220:221], 1.0 op_sel_hi:[1,0]
	v_pk_add_f32 v[222:223], v[222:223], 1.0 op_sel_hi:[1,0]
	v_rcp_f32_e32 v216, v216
	v_rcp_f32_e32 v217, v217
	v_rcp_f32_e32 v218, v218
	v_rcp_f32_e32 v219, v219
	v_rcp_f32_e32 v220, v220
	v_rcp_f32_e32 v221, v221
	v_rcp_f32_e32 v222, v222
	v_rcp_f32_e32 v223, v223
	v_lshlrev_b32_e32 v242, 16, v150
	v_and_b32_e32 v243, 0xffff0000, v150
	v_lshlrev_b32_e32 v244, 16, v151
	v_and_b32_e32 v245, 0xffff0000, v151
	v_lshlrev_b32_e32 v246, 16, v152
	v_and_b32_e32 v247, 0xffff0000, v152
	v_lshlrev_b32_e32 v248, 16, v153
	v_and_b32_e32 v249, 0xffff0000, v153
	v_pk_mul_f32 v[242:243], v[242:243], s[86:87] op_sel_hi:[1,0]
	v_pk_mul_f32 v[244:245], v[244:245], s[86:87] op_sel_hi:[1,0]
	v_pk_mul_f32 v[246:247], v[246:247], s[86:87] op_sel_hi:[1,0]
	v_pk_mul_f32 v[248:249], v[248:249], s[86:87] op_sel_hi:[1,0]
	v_exp_f32_e32 v242, v242
	v_exp_f32_e32 v243, v243
	v_exp_f32_e32 v244, v244
	v_exp_f32_e32 v245, v245
	v_exp_f32_e32 v246, v246
	v_exp_f32_e32 v247, v247
	v_exp_f32_e32 v248, v248
	v_exp_f32_e32 v249, v249
	v_pk_add_f32 v[242:243], v[242:243], 1.0 op_sel_hi:[1,0]
	v_pk_add_f32 v[244:245], v[244:245], 1.0 op_sel_hi:[1,0]
	v_pk_add_f32 v[246:247], v[246:247], 1.0 op_sel_hi:[1,0]
	v_pk_add_f32 v[248:249], v[248:249], 1.0 op_sel_hi:[1,0]
	v_pk_mul_f32 v[216:217], v[216:217], v[242:243]
	v_pk_mul_f32 v[218:219], v[218:219], v[244:245]
	v_pk_mul_f32 v[220:221], v[220:221], v[246:247]
	v_pk_mul_f32 v[222:223], v[222:223], v[248:249]
	v_pk_mul_f32 v[118:119], v[118:119], v[216:217]
	v_pk_mul_f32 v[120:121], v[120:121], v[218:219]
	v_pk_mul_f32 v[114:115], v[114:115], v[220:221]
	v_pk_mul_f32 v[116:117], v[116:117], v[222:223]
	v_lshlrev_b32_e32 v216, 16, v154
	v_and_b32_e32 v217, 0xffff0000, v154
	v_lshlrev_b32_e32 v218, 16, v155
	v_and_b32_e32 v219, 0xffff0000, v155
	v_lshlrev_b32_e32 v220, 16, v156
	v_and_b32_e32 v221, 0xffff0000, v156
	v_lshlrev_b32_e32 v222, 16, v157
	v_and_b32_e32 v223, 0xffff0000, v157
	v_pk_mul_f32 v[216:217], v[216:217], s[86:87] op_sel_hi:[1,0]
	v_pk_mul_f32 v[218:219], v[218:219], s[86:87] op_sel_hi:[1,0]
	v_pk_mul_f32 v[220:221], v[220:221], s[86:87] op_sel_hi:[1,0]
	v_pk_mul_f32 v[222:223], v[222:223], s[86:87] op_sel_hi:[1,0]
	v_exp_f32_e32 v216, v216
	v_exp_f32_e32 v217, v217
	v_exp_f32_e32 v218, v218
	v_exp_f32_e32 v219, v219
	v_exp_f32_e32 v220, v220
	v_exp_f32_e32 v221, v221
	v_exp_f32_e32 v222, v222
	v_exp_f32_e32 v223, v223
	v_pk_add_f32 v[216:217], v[216:217], 1.0 op_sel_hi:[1,0]
	v_pk_add_f32 v[218:219], v[218:219], 1.0 op_sel_hi:[1,0]
	v_pk_add_f32 v[220:221], v[220:221], 1.0 op_sel_hi:[1,0]
	v_pk_add_f32 v[222:223], v[222:223], 1.0 op_sel_hi:[1,0]
	v_rcp_f32_e32 v216, v216
	v_rcp_f32_e32 v217, v217
	v_rcp_f32_e32 v218, v218
	v_rcp_f32_e32 v219, v219
	v_rcp_f32_e32 v220, v220
	v_rcp_f32_e32 v221, v221
	v_rcp_f32_e32 v222, v222
	v_rcp_f32_e32 v223, v223
	v_lshlrev_b32_e32 v242, 16, v158
	v_and_b32_e32 v243, 0xffff0000, v158
	v_lshlrev_b32_e32 v244, 16, v159
	v_and_b32_e32 v245, 0xffff0000, v159
	v_lshlrev_b32_e32 v246, 16, v160
	v_and_b32_e32 v247, 0xffff0000, v160
	v_lshlrev_b32_e32 v248, 16, v161
	v_and_b32_e32 v249, 0xffff0000, v161
	v_pk_mul_f32 v[242:243], v[242:243], s[86:87] op_sel_hi:[1,0]
	v_pk_mul_f32 v[244:245], v[244:245], s[86:87] op_sel_hi:[1,0]
	v_pk_mul_f32 v[246:247], v[246:247], s[86:87] op_sel_hi:[1,0]
	v_pk_mul_f32 v[248:249], v[248:249], s[86:87] op_sel_hi:[1,0]
	v_exp_f32_e32 v242, v242
	v_exp_f32_e32 v243, v243
	v_exp_f32_e32 v244, v244
	v_exp_f32_e32 v245, v245
	v_exp_f32_e32 v246, v246
	v_exp_f32_e32 v247, v247
	v_exp_f32_e32 v248, v248
	v_exp_f32_e32 v249, v249
	v_pk_add_f32 v[242:243], v[242:243], 1.0 op_sel_hi:[1,0]
	v_pk_add_f32 v[244:245], v[244:245], 1.0 op_sel_hi:[1,0]
	v_pk_add_f32 v[246:247], v[246:247], 1.0 op_sel_hi:[1,0]
	v_pk_add_f32 v[248:249], v[248:249], 1.0 op_sel_hi:[1,0]
	v_pk_mul_f32 v[216:217], v[216:217], v[242:243]
	v_pk_mul_f32 v[218:219], v[218:219], v[244:245]
	v_pk_mul_f32 v[220:221], v[220:221], v[246:247]
	v_pk_mul_f32 v[222:223], v[222:223], v[248:249]
	v_pk_mul_f32 v[86:87], v[86:87], v[216:217]
	v_pk_mul_f32 v[88:89], v[88:89], v[218:219]
	v_pk_mul_f32 v[82:83], v[82:83], v[220:221]
	v_pk_mul_f32 v[84:85], v[84:85], v[222:223]
	s_add_u32 s28, s20, 0x3a8000
	s_addc_u32 s29, s21, 0
	global_load_dwordx4 v[146:149], v253, s[28:29]
	global_load_dwordx4 v[150:153], v254, s[28:29]
	global_load_dwordx4 v[154:157], v253, s[28:29] offset:256
	global_load_dwordx4 v[158:161], v254, s[28:29] offset:256
	s_waitcnt vmcnt(12)
	v_lshlrev_b32_e32 v216, 16, v162
	v_and_b32_e32 v217, 0xffff0000, v162
	v_lshlrev_b32_e32 v218, 16, v163
	v_and_b32_e32 v219, 0xffff0000, v163
	v_lshlrev_b32_e32 v220, 16, v164
	v_and_b32_e32 v221, 0xffff0000, v164
	v_lshlrev_b32_e32 v222, 16, v165
	v_and_b32_e32 v223, 0xffff0000, v165
	v_pk_mul_f32 v[216:217], v[216:217], s[86:87] op_sel_hi:[1,0]
	v_pk_mul_f32 v[218:219], v[218:219], s[86:87] op_sel_hi:[1,0]
	v_pk_mul_f32 v[220:221], v[220:221], s[86:87] op_sel_hi:[1,0]
	v_pk_mul_f32 v[222:223], v[222:223], s[86:87] op_sel_hi:[1,0]
	v_exp_f32_e32 v216, v216
	v_exp_f32_e32 v217, v217
	v_exp_f32_e32 v218, v218
	v_exp_f32_e32 v219, v219
	v_exp_f32_e32 v220, v220
	v_exp_f32_e32 v221, v221
	v_exp_f32_e32 v222, v222
	v_exp_f32_e32 v223, v223
	v_pk_add_f32 v[216:217], v[216:217], 1.0 op_sel_hi:[1,0]
	v_pk_add_f32 v[218:219], v[218:219], 1.0 op_sel_hi:[1,0]
	v_pk_add_f32 v[220:221], v[220:221], 1.0 op_sel_hi:[1,0]
	v_pk_add_f32 v[222:223], v[222:223], 1.0 op_sel_hi:[1,0]
	v_rcp_f32_e32 v216, v216
	v_rcp_f32_e32 v217, v217
	v_rcp_f32_e32 v218, v218
	v_rcp_f32_e32 v219, v219
	v_rcp_f32_e32 v220, v220
	v_rcp_f32_e32 v221, v221
	v_rcp_f32_e32 v222, v222
	v_rcp_f32_e32 v223, v223
	v_lshlrev_b32_e32 v242, 16, v166
	v_and_b32_e32 v243, 0xffff0000, v166
	v_lshlrev_b32_e32 v244, 16, v167
	v_and_b32_e32 v245, 0xffff0000, v167
	v_lshlrev_b32_e32 v246, 16, v168
	v_and_b32_e32 v247, 0xffff0000, v168
	v_lshlrev_b32_e32 v248, 16, v169
	v_and_b32_e32 v249, 0xffff0000, v169
	v_pk_mul_f32 v[242:243], v[242:243], s[86:87] op_sel_hi:[1,0]
	v_pk_mul_f32 v[244:245], v[244:245], s[86:87] op_sel_hi:[1,0]
	v_pk_mul_f32 v[246:247], v[246:247], s[86:87] op_sel_hi:[1,0]
	v_pk_mul_f32 v[248:249], v[248:249], s[86:87] op_sel_hi:[1,0]
	v_exp_f32_e32 v242, v242
	v_exp_f32_e32 v243, v243
	v_exp_f32_e32 v244, v244
	v_exp_f32_e32 v245, v245
	v_exp_f32_e32 v246, v246
	v_exp_f32_e32 v247, v247
	v_exp_f32_e32 v248, v248
	v_exp_f32_e32 v249, v249
	v_pk_add_f32 v[242:243], v[242:243], 1.0 op_sel_hi:[1,0]
	v_pk_add_f32 v[244:245], v[244:245], 1.0 op_sel_hi:[1,0]
	v_pk_add_f32 v[246:247], v[246:247], 1.0 op_sel_hi:[1,0]
	v_pk_add_f32 v[248:249], v[248:249], 1.0 op_sel_hi:[1,0]
	v_pk_mul_f32 v[216:217], v[216:217], v[242:243]
	v_pk_mul_f32 v[218:219], v[218:219], v[244:245]
	v_pk_mul_f32 v[220:221], v[220:221], v[246:247]
	v_pk_mul_f32 v[222:223], v[222:223], v[248:249]
	v_pk_mul_f32 v[110:111], v[110:111], v[216:217]
	v_pk_mul_f32 v[112:113], v[112:113], v[218:219]
	v_pk_mul_f32 v[106:107], v[106:107], v[220:221]
	v_pk_mul_f32 v[108:109], v[108:109], v[222:223]
	v_lshlrev_b32_e32 v216, 16, v170
	v_and_b32_e32 v217, 0xffff0000, v170
	v_lshlrev_b32_e32 v218, 16, v171
	v_and_b32_e32 v219, 0xffff0000, v171
	v_lshlrev_b32_e32 v220, 16, v172
	v_and_b32_e32 v221, 0xffff0000, v172
	v_lshlrev_b32_e32 v222, 16, v173
	v_and_b32_e32 v223, 0xffff0000, v173
	v_pk_mul_f32 v[216:217], v[216:217], s[86:87] op_sel_hi:[1,0]
	v_pk_mul_f32 v[218:219], v[218:219], s[86:87] op_sel_hi:[1,0]
	v_pk_mul_f32 v[220:221], v[220:221], s[86:87] op_sel_hi:[1,0]
	v_pk_mul_f32 v[222:223], v[222:223], s[86:87] op_sel_hi:[1,0]
	v_exp_f32_e32 v216, v216
	v_exp_f32_e32 v217, v217
	v_exp_f32_e32 v218, v218
	v_exp_f32_e32 v219, v219
	v_exp_f32_e32 v220, v220
	v_exp_f32_e32 v221, v221
	v_exp_f32_e32 v222, v222
	v_exp_f32_e32 v223, v223
	v_pk_add_f32 v[216:217], v[216:217], 1.0 op_sel_hi:[1,0]
	v_pk_add_f32 v[218:219], v[218:219], 1.0 op_sel_hi:[1,0]
	v_pk_add_f32 v[220:221], v[220:221], 1.0 op_sel_hi:[1,0]
	v_pk_add_f32 v[222:223], v[222:223], 1.0 op_sel_hi:[1,0]
	v_rcp_f32_e32 v216, v216
	v_rcp_f32_e32 v217, v217
	v_rcp_f32_e32 v218, v218
	v_rcp_f32_e32 v219, v219
	v_rcp_f32_e32 v220, v220
	v_rcp_f32_e32 v221, v221
	v_rcp_f32_e32 v222, v222
	v_rcp_f32_e32 v223, v223
	v_lshlrev_b32_e32 v242, 16, v174
	v_and_b32_e32 v243, 0xffff0000, v174
	v_lshlrev_b32_e32 v244, 16, v175
	v_and_b32_e32 v245, 0xffff0000, v175
	v_lshlrev_b32_e32 v246, 16, v176
	v_and_b32_e32 v247, 0xffff0000, v176
	v_lshlrev_b32_e32 v248, 16, v177
	v_and_b32_e32 v249, 0xffff0000, v177
	v_pk_mul_f32 v[242:243], v[242:243], s[86:87] op_sel_hi:[1,0]
	v_pk_mul_f32 v[244:245], v[244:245], s[86:87] op_sel_hi:[1,0]
	v_pk_mul_f32 v[246:247], v[246:247], s[86:87] op_sel_hi:[1,0]
	v_pk_mul_f32 v[248:249], v[248:249], s[86:87] op_sel_hi:[1,0]
	v_exp_f32_e32 v242, v242
	v_exp_f32_e32 v243, v243
	v_exp_f32_e32 v244, v244
	v_exp_f32_e32 v245, v245
	v_exp_f32_e32 v246, v246
	v_exp_f32_e32 v247, v247
	v_exp_f32_e32 v248, v248
	v_exp_f32_e32 v249, v249
	v_pk_add_f32 v[242:243], v[242:243], 1.0 op_sel_hi:[1,0]
	v_pk_add_f32 v[244:245], v[244:245], 1.0 op_sel_hi:[1,0]
	v_pk_add_f32 v[246:247], v[246:247], 1.0 op_sel_hi:[1,0]
	v_pk_add_f32 v[248:249], v[248:249], 1.0 op_sel_hi:[1,0]
	v_pk_mul_f32 v[216:217], v[216:217], v[242:243]
	v_pk_mul_f32 v[218:219], v[218:219], v[244:245]
	v_pk_mul_f32 v[220:221], v[220:221], v[246:247]
	v_pk_mul_f32 v[222:223], v[222:223], v[248:249]
	v_pk_mul_f32 v[78:79], v[78:79], v[216:217]
	v_pk_mul_f32 v[80:81], v[80:81], v[218:219]
	v_pk_mul_f32 v[74:75], v[74:75], v[220:221]
	v_pk_mul_f32 v[76:77], v[76:77], v[222:223]
	s_add_u32 s28, s20, 0x410000
	s_addc_u32 s29, s21, 0
	global_load_dwordx4 v[162:165], v253, s[28:29]
	global_load_dwordx4 v[166:169], v254, s[28:29]
	global_load_dwordx4 v[170:173], v253, s[28:29] offset:256
	global_load_dwordx4 v[174:177], v254, s[28:29] offset:256
	s_waitcnt vmcnt(12)
	v_lshlrev_b32_e32 v216, 16, v178
	v_and_b32_e32 v217, 0xffff0000, v178
	v_lshlrev_b32_e32 v218, 16, v179
	v_and_b32_e32 v219, 0xffff0000, v179
	v_lshlrev_b32_e32 v220, 16, v180
	v_and_b32_e32 v221, 0xffff0000, v180
	v_lshlrev_b32_e32 v222, 16, v181
	v_and_b32_e32 v223, 0xffff0000, v181
	v_pk_mul_f32 v[216:217], v[216:217], s[86:87] op_sel_hi:[1,0]
	v_pk_mul_f32 v[218:219], v[218:219], s[86:87] op_sel_hi:[1,0]
	v_pk_mul_f32 v[220:221], v[220:221], s[86:87] op_sel_hi:[1,0]
	v_pk_mul_f32 v[222:223], v[222:223], s[86:87] op_sel_hi:[1,0]
	v_exp_f32_e32 v216, v216
	v_exp_f32_e32 v217, v217
	v_exp_f32_e32 v218, v218
	v_exp_f32_e32 v219, v219
	v_exp_f32_e32 v220, v220
	v_exp_f32_e32 v221, v221
	v_exp_f32_e32 v222, v222
	v_exp_f32_e32 v223, v223
	v_pk_add_f32 v[216:217], v[216:217], 1.0 op_sel_hi:[1,0]
	v_pk_add_f32 v[218:219], v[218:219], 1.0 op_sel_hi:[1,0]
	v_pk_add_f32 v[220:221], v[220:221], 1.0 op_sel_hi:[1,0]
	v_pk_add_f32 v[222:223], v[222:223], 1.0 op_sel_hi:[1,0]
	v_rcp_f32_e32 v216, v216
	v_rcp_f32_e32 v217, v217
	v_rcp_f32_e32 v218, v218
	v_rcp_f32_e32 v219, v219
	v_rcp_f32_e32 v220, v220
	v_rcp_f32_e32 v221, v221
	v_rcp_f32_e32 v222, v222
	v_rcp_f32_e32 v223, v223
	v_lshlrev_b32_e32 v242, 16, v182
	v_and_b32_e32 v243, 0xffff0000, v182
	v_lshlrev_b32_e32 v244, 16, v183
	v_and_b32_e32 v245, 0xffff0000, v183
	v_lshlrev_b32_e32 v246, 16, v184
	v_and_b32_e32 v247, 0xffff0000, v184
	v_lshlrev_b32_e32 v248, 16, v185
	v_and_b32_e32 v249, 0xffff0000, v185
	v_pk_mul_f32 v[242:243], v[242:243], s[86:87] op_sel_hi:[1,0]
	v_pk_mul_f32 v[244:245], v[244:245], s[86:87] op_sel_hi:[1,0]
	v_pk_mul_f32 v[246:247], v[246:247], s[86:87] op_sel_hi:[1,0]
	v_pk_mul_f32 v[248:249], v[248:249], s[86:87] op_sel_hi:[1,0]
	v_exp_f32_e32 v242, v242
	v_exp_f32_e32 v243, v243
	v_exp_f32_e32 v244, v244
	v_exp_f32_e32 v245, v245
	v_exp_f32_e32 v246, v246
	v_exp_f32_e32 v247, v247
	v_exp_f32_e32 v248, v248
	v_exp_f32_e32 v249, v249
	v_pk_add_f32 v[242:243], v[242:243], 1.0 op_sel_hi:[1,0]
	v_pk_add_f32 v[244:245], v[244:245], 1.0 op_sel_hi:[1,0]
	v_pk_add_f32 v[246:247], v[246:247], 1.0 op_sel_hi:[1,0]
	v_pk_add_f32 v[248:249], v[248:249], 1.0 op_sel_hi:[1,0]
	v_pk_mul_f32 v[216:217], v[216:217], v[242:243]
	v_pk_mul_f32 v[218:219], v[218:219], v[244:245]
	v_pk_mul_f32 v[220:221], v[220:221], v[246:247]
	v_pk_mul_f32 v[222:223], v[222:223], v[248:249]
	v_pk_mul_f32 v[102:103], v[102:103], v[216:217]
	v_pk_mul_f32 v[104:105], v[104:105], v[218:219]
	v_pk_mul_f32 v[98:99], v[98:99], v[220:221]
	v_pk_mul_f32 v[100:101], v[100:101], v[222:223]
	v_lshlrev_b32_e32 v216, 16, v186
	v_and_b32_e32 v217, 0xffff0000, v186
	v_lshlrev_b32_e32 v218, 16, v187
	v_and_b32_e32 v219, 0xffff0000, v187
	v_lshlrev_b32_e32 v220, 16, v188
	v_and_b32_e32 v221, 0xffff0000, v188
	v_lshlrev_b32_e32 v222, 16, v189
	v_and_b32_e32 v223, 0xffff0000, v189
	v_pk_mul_f32 v[216:217], v[216:217], s[86:87] op_sel_hi:[1,0]
	v_pk_mul_f32 v[218:219], v[218:219], s[86:87] op_sel_hi:[1,0]
	v_pk_mul_f32 v[220:221], v[220:221], s[86:87] op_sel_hi:[1,0]
	v_pk_mul_f32 v[222:223], v[222:223], s[86:87] op_sel_hi:[1,0]
	v_exp_f32_e32 v216, v216
	v_exp_f32_e32 v217, v217
	v_exp_f32_e32 v218, v218
	v_exp_f32_e32 v219, v219
	v_exp_f32_e32 v220, v220
	v_exp_f32_e32 v221, v221
	v_exp_f32_e32 v222, v222
	v_exp_f32_e32 v223, v223
	v_pk_add_f32 v[216:217], v[216:217], 1.0 op_sel_hi:[1,0]
	v_pk_add_f32 v[218:219], v[218:219], 1.0 op_sel_hi:[1,0]
	v_pk_add_f32 v[220:221], v[220:221], 1.0 op_sel_hi:[1,0]
	v_pk_add_f32 v[222:223], v[222:223], 1.0 op_sel_hi:[1,0]
	v_rcp_f32_e32 v216, v216
	v_rcp_f32_e32 v217, v217
	v_rcp_f32_e32 v218, v218
	v_rcp_f32_e32 v219, v219
	v_rcp_f32_e32 v220, v220
	v_rcp_f32_e32 v221, v221
	v_rcp_f32_e32 v222, v222
	v_rcp_f32_e32 v223, v223
	v_lshlrev_b32_e32 v242, 16, v190
	v_and_b32_e32 v243, 0xffff0000, v190
	v_lshlrev_b32_e32 v244, 16, v191
	v_and_b32_e32 v245, 0xffff0000, v191
	v_lshlrev_b32_e32 v246, 16, v192
	v_and_b32_e32 v247, 0xffff0000, v192
	v_lshlrev_b32_e32 v248, 16, v193
	v_and_b32_e32 v249, 0xffff0000, v193
	v_pk_mul_f32 v[242:243], v[242:243], s[86:87] op_sel_hi:[1,0]
	v_pk_mul_f32 v[244:245], v[244:245], s[86:87] op_sel_hi:[1,0]
	v_pk_mul_f32 v[246:247], v[246:247], s[86:87] op_sel_hi:[1,0]
	v_pk_mul_f32 v[248:249], v[248:249], s[86:87] op_sel_hi:[1,0]
	v_exp_f32_e32 v242, v242
	v_exp_f32_e32 v243, v243
	v_exp_f32_e32 v244, v244
	v_exp_f32_e32 v245, v245
	v_exp_f32_e32 v246, v246
	v_exp_f32_e32 v247, v247
	v_exp_f32_e32 v248, v248
	v_exp_f32_e32 v249, v249
	v_pk_add_f32 v[242:243], v[242:243], 1.0 op_sel_hi:[1,0]
	v_pk_add_f32 v[244:245], v[244:245], 1.0 op_sel_hi:[1,0]
	v_pk_add_f32 v[246:247], v[246:247], 1.0 op_sel_hi:[1,0]
	v_pk_add_f32 v[248:249], v[248:249], 1.0 op_sel_hi:[1,0]
	v_pk_mul_f32 v[216:217], v[216:217], v[242:243]
	v_pk_mul_f32 v[218:219], v[218:219], v[244:245]
	v_pk_mul_f32 v[220:221], v[220:221], v[246:247]
	v_pk_mul_f32 v[222:223], v[222:223], v[248:249]
	v_pk_mul_f32 v[70:71], v[70:71], v[216:217]
	v_pk_mul_f32 v[72:73], v[72:73], v[218:219]
	v_pk_mul_f32 v[66:67], v[66:67], v[220:221]
	v_pk_mul_f32 v[68:69], v[68:69], v[222:223]
	s_add_u32 s28, s20, 0x478000
	s_addc_u32 s29, s21, 0
	global_load_dwordx4 v[178:181], v253, s[28:29]
	global_load_dwordx4 v[182:185], v254, s[28:29]
	global_load_dwordx4 v[186:189], v253, s[28:29] offset:256
	global_load_dwordx4 v[190:193], v254, s[28:29] offset:256
	s_waitcnt vmcnt(12)
	v_lshlrev_b32_e32 v216, 16, v130
	v_and_b32_e32 v217, 0xffff0000, v130
	v_lshlrev_b32_e32 v218, 16, v131
	v_and_b32_e32 v219, 0xffff0000, v131
	v_lshlrev_b32_e32 v220, 16, v132
	v_and_b32_e32 v221, 0xffff0000, v132
	v_lshlrev_b32_e32 v222, 16, v133
	v_and_b32_e32 v223, 0xffff0000, v133
	v_pk_mul_f32 v[216:217], v[216:217], s[86:87] op_sel_hi:[1,0]
	v_pk_mul_f32 v[218:219], v[218:219], s[86:87] op_sel_hi:[1,0]
	v_pk_mul_f32 v[220:221], v[220:221], s[86:87] op_sel_hi:[1,0]
	v_pk_mul_f32 v[222:223], v[222:223], s[86:87] op_sel_hi:[1,0]
	v_exp_f32_e32 v216, v216
	v_exp_f32_e32 v217, v217
	v_exp_f32_e32 v218, v218
	v_exp_f32_e32 v219, v219
	v_exp_f32_e32 v220, v220
	v_exp_f32_e32 v221, v221
	v_exp_f32_e32 v222, v222
	v_exp_f32_e32 v223, v223
	v_pk_add_f32 v[216:217], v[216:217], 1.0 op_sel_hi:[1,0]
	v_pk_add_f32 v[218:219], v[218:219], 1.0 op_sel_hi:[1,0]
	v_pk_add_f32 v[220:221], v[220:221], 1.0 op_sel_hi:[1,0]
	v_pk_add_f32 v[222:223], v[222:223], 1.0 op_sel_hi:[1,0]
	v_rcp_f32_e32 v216, v216
	v_rcp_f32_e32 v217, v217
	v_rcp_f32_e32 v218, v218
	v_rcp_f32_e32 v219, v219
	v_rcp_f32_e32 v220, v220
	v_rcp_f32_e32 v221, v221
	v_rcp_f32_e32 v222, v222
	v_rcp_f32_e32 v223, v223
	v_lshlrev_b32_e32 v242, 16, v134
	v_and_b32_e32 v243, 0xffff0000, v134
	v_lshlrev_b32_e32 v244, 16, v135
	v_and_b32_e32 v245, 0xffff0000, v135
	v_lshlrev_b32_e32 v246, 16, v136
	v_and_b32_e32 v247, 0xffff0000, v136
	v_lshlrev_b32_e32 v248, 16, v137
	v_and_b32_e32 v249, 0xffff0000, v137
	v_pk_mul_f32 v[242:243], v[242:243], s[86:87] op_sel_hi:[1,0]
	v_pk_mul_f32 v[244:245], v[244:245], s[86:87] op_sel_hi:[1,0]
	v_pk_mul_f32 v[246:247], v[246:247], s[86:87] op_sel_hi:[1,0]
	v_pk_mul_f32 v[248:249], v[248:249], s[86:87] op_sel_hi:[1,0]
	v_exp_f32_e32 v242, v242
	v_exp_f32_e32 v243, v243
	v_exp_f32_e32 v244, v244
	v_exp_f32_e32 v245, v245
	v_exp_f32_e32 v246, v246
	v_exp_f32_e32 v247, v247
	v_exp_f32_e32 v248, v248
	v_exp_f32_e32 v249, v249
	v_pk_add_f32 v[242:243], v[242:243], 1.0 op_sel_hi:[1,0]
	v_pk_add_f32 v[244:245], v[244:245], 1.0 op_sel_hi:[1,0]
	v_pk_add_f32 v[246:247], v[246:247], 1.0 op_sel_hi:[1,0]
	v_pk_add_f32 v[248:249], v[248:249], 1.0 op_sel_hi:[1,0]
	v_pk_mul_f32 v[216:217], v[216:217], v[242:243]
	v_pk_mul_f32 v[218:219], v[218:219], v[244:245]
	v_pk_mul_f32 v[220:221], v[220:221], v[246:247]
	v_pk_mul_f32 v[222:223], v[222:223], v[248:249]
	v_pk_mul_f32 v[62:63], v[62:63], v[216:217]
	v_pk_mul_f32 v[64:65], v[64:65], v[218:219]
	v_pk_mul_f32 v[58:59], v[58:59], v[220:221]
	v_pk_mul_f32 v[60:61], v[60:61], v[222:223]
	v_lshlrev_b32_e32 v216, 16, v138
	v_and_b32_e32 v217, 0xffff0000, v138
	v_lshlrev_b32_e32 v218, 16, v139
	v_and_b32_e32 v219, 0xffff0000, v139
	v_lshlrev_b32_e32 v220, 16, v140
	v_and_b32_e32 v221, 0xffff0000, v140
	v_lshlrev_b32_e32 v222, 16, v141
	v_and_b32_e32 v223, 0xffff0000, v141
	v_pk_mul_f32 v[216:217], v[216:217], s[86:87] op_sel_hi:[1,0]
	v_pk_mul_f32 v[218:219], v[218:219], s[86:87] op_sel_hi:[1,0]
	v_pk_mul_f32 v[220:221], v[220:221], s[86:87] op_sel_hi:[1,0]
	v_pk_mul_f32 v[222:223], v[222:223], s[86:87] op_sel_hi:[1,0]
	v_exp_f32_e32 v216, v216
	v_exp_f32_e32 v217, v217
	v_exp_f32_e32 v218, v218
	v_exp_f32_e32 v219, v219
	v_exp_f32_e32 v220, v220
	v_exp_f32_e32 v221, v221
	v_exp_f32_e32 v222, v222
	v_exp_f32_e32 v223, v223
	v_pk_add_f32 v[216:217], v[216:217], 1.0 op_sel_hi:[1,0]
	v_pk_add_f32 v[218:219], v[218:219], 1.0 op_sel_hi:[1,0]
	v_pk_add_f32 v[220:221], v[220:221], 1.0 op_sel_hi:[1,0]
	v_pk_add_f32 v[222:223], v[222:223], 1.0 op_sel_hi:[1,0]
	v_rcp_f32_e32 v216, v216
	v_rcp_f32_e32 v217, v217
	v_rcp_f32_e32 v218, v218
	v_rcp_f32_e32 v219, v219
	v_rcp_f32_e32 v220, v220
	v_rcp_f32_e32 v221, v221
	v_rcp_f32_e32 v222, v222
	v_rcp_f32_e32 v223, v223
	v_lshlrev_b32_e32 v242, 16, v142
	v_and_b32_e32 v243, 0xffff0000, v142
	v_lshlrev_b32_e32 v244, 16, v143
	v_and_b32_e32 v245, 0xffff0000, v143
	v_lshlrev_b32_e32 v246, 16, v144
	v_and_b32_e32 v247, 0xffff0000, v144
	v_lshlrev_b32_e32 v248, 16, v145
	v_and_b32_e32 v249, 0xffff0000, v145
	v_pk_mul_f32 v[242:243], v[242:243], s[86:87] op_sel_hi:[1,0]
	v_pk_mul_f32 v[244:245], v[244:245], s[86:87] op_sel_hi:[1,0]
	v_pk_mul_f32 v[246:247], v[246:247], s[86:87] op_sel_hi:[1,0]
	v_pk_mul_f32 v[248:249], v[248:249], s[86:87] op_sel_hi:[1,0]
	v_exp_f32_e32 v242, v242
	v_exp_f32_e32 v243, v243
	v_exp_f32_e32 v244, v244
	v_exp_f32_e32 v245, v245
	v_exp_f32_e32 v246, v246
	v_exp_f32_e32 v247, v247
	v_exp_f32_e32 v248, v248
	v_exp_f32_e32 v249, v249
	v_pk_add_f32 v[242:243], v[242:243], 1.0 op_sel_hi:[1,0]
	v_pk_add_f32 v[244:245], v[244:245], 1.0 op_sel_hi:[1,0]
	v_pk_add_f32 v[246:247], v[246:247], 1.0 op_sel_hi:[1,0]
	v_pk_add_f32 v[248:249], v[248:249], 1.0 op_sel_hi:[1,0]
	v_pk_mul_f32 v[216:217], v[216:217], v[242:243]
	v_pk_mul_f32 v[218:219], v[218:219], v[244:245]
	v_pk_mul_f32 v[220:221], v[220:221], v[246:247]
	v_pk_mul_f32 v[222:223], v[222:223], v[248:249]
	v_pk_mul_f32 v[30:31], v[30:31], v[216:217]
	v_pk_mul_f32 v[32:33], v[32:33], v[218:219]
	v_pk_mul_f32 v[26:27], v[26:27], v[220:221]
	v_pk_mul_f32 v[28:29], v[28:29], v[222:223]
	s_waitcnt vmcnt(8)
	v_lshlrev_b32_e32 v216, 16, v146
	v_and_b32_e32 v217, 0xffff0000, v146
	v_lshlrev_b32_e32 v218, 16, v147
	v_and_b32_e32 v219, 0xffff0000, v147
	v_lshlrev_b32_e32 v220, 16, v148
	v_and_b32_e32 v221, 0xffff0000, v148
	v_lshlrev_b32_e32 v222, 16, v149
	v_and_b32_e32 v223, 0xffff0000, v149
	v_pk_mul_f32 v[216:217], v[216:217], s[86:87] op_sel_hi:[1,0]
	v_pk_mul_f32 v[218:219], v[218:219], s[86:87] op_sel_hi:[1,0]
	v_pk_mul_f32 v[220:221], v[220:221], s[86:87] op_sel_hi:[1,0]
	v_pk_mul_f32 v[222:223], v[222:223], s[86:87] op_sel_hi:[1,0]
	v_exp_f32_e32 v216, v216
	v_exp_f32_e32 v217, v217
	v_exp_f32_e32 v218, v218
	v_exp_f32_e32 v219, v219
	v_exp_f32_e32 v220, v220
	v_exp_f32_e32 v221, v221
	v_exp_f32_e32 v222, v222
	v_exp_f32_e32 v223, v223
	v_pk_add_f32 v[216:217], v[216:217], 1.0 op_sel_hi:[1,0]
	v_pk_add_f32 v[218:219], v[218:219], 1.0 op_sel_hi:[1,0]
	v_pk_add_f32 v[220:221], v[220:221], 1.0 op_sel_hi:[1,0]
	v_pk_add_f32 v[222:223], v[222:223], 1.0 op_sel_hi:[1,0]
	v_rcp_f32_e32 v216, v216
	v_rcp_f32_e32 v217, v217
	v_rcp_f32_e32 v218, v218
	v_rcp_f32_e32 v219, v219
	v_rcp_f32_e32 v220, v220
	v_rcp_f32_e32 v221, v221
	v_rcp_f32_e32 v222, v222
	v_rcp_f32_e32 v223, v223
	v_lshlrev_b32_e32 v242, 16, v150
	v_and_b32_e32 v243, 0xffff0000, v150
	v_lshlrev_b32_e32 v244, 16, v151
	v_and_b32_e32 v245, 0xffff0000, v151
	v_lshlrev_b32_e32 v246, 16, v152
	v_and_b32_e32 v247, 0xffff0000, v152
	v_lshlrev_b32_e32 v248, 16, v153
	v_and_b32_e32 v249, 0xffff0000, v153
	v_pk_mul_f32 v[242:243], v[242:243], s[86:87] op_sel_hi:[1,0]
	v_pk_mul_f32 v[244:245], v[244:245], s[86:87] op_sel_hi:[1,0]
	v_pk_mul_f32 v[246:247], v[246:247], s[86:87] op_sel_hi:[1,0]
	v_pk_mul_f32 v[248:249], v[248:249], s[86:87] op_sel_hi:[1,0]
	v_exp_f32_e32 v242, v242
	v_exp_f32_e32 v243, v243
	v_exp_f32_e32 v244, v244
	v_exp_f32_e32 v245, v245
	v_exp_f32_e32 v246, v246
	v_exp_f32_e32 v247, v247
	v_exp_f32_e32 v248, v248
	v_exp_f32_e32 v249, v249
	v_pk_add_f32 v[242:243], v[242:243], 1.0 op_sel_hi:[1,0]
	v_pk_add_f32 v[244:245], v[244:245], 1.0 op_sel_hi:[1,0]
	v_pk_add_f32 v[246:247], v[246:247], 1.0 op_sel_hi:[1,0]
	v_pk_add_f32 v[248:249], v[248:249], 1.0 op_sel_hi:[1,0]
	v_pk_mul_f32 v[216:217], v[216:217], v[242:243]
	v_pk_mul_f32 v[218:219], v[218:219], v[244:245]
	v_pk_mul_f32 v[220:221], v[220:221], v[246:247]
	v_pk_mul_f32 v[222:223], v[222:223], v[248:249]
	v_pk_mul_f32 v[54:55], v[54:55], v[216:217]
	v_pk_mul_f32 v[56:57], v[56:57], v[218:219]
	v_pk_mul_f32 v[50:51], v[50:51], v[220:221]
	v_pk_mul_f32 v[52:53], v[52:53], v[222:223]
	v_lshlrev_b32_e32 v216, 16, v154
	v_and_b32_e32 v217, 0xffff0000, v154
	v_lshlrev_b32_e32 v218, 16, v155
	v_and_b32_e32 v219, 0xffff0000, v155
	v_lshlrev_b32_e32 v220, 16, v156
	v_and_b32_e32 v221, 0xffff0000, v156
	v_lshlrev_b32_e32 v222, 16, v157
	v_and_b32_e32 v223, 0xffff0000, v157
	v_pk_mul_f32 v[216:217], v[216:217], s[86:87] op_sel_hi:[1,0]
	v_pk_mul_f32 v[218:219], v[218:219], s[86:87] op_sel_hi:[1,0]
	v_pk_mul_f32 v[220:221], v[220:221], s[86:87] op_sel_hi:[1,0]
	v_pk_mul_f32 v[222:223], v[222:223], s[86:87] op_sel_hi:[1,0]
	v_exp_f32_e32 v216, v216
	v_exp_f32_e32 v217, v217
	v_exp_f32_e32 v218, v218
	v_exp_f32_e32 v219, v219
	v_exp_f32_e32 v220, v220
	v_exp_f32_e32 v221, v221
	v_exp_f32_e32 v222, v222
	v_exp_f32_e32 v223, v223
	v_pk_add_f32 v[216:217], v[216:217], 1.0 op_sel_hi:[1,0]
	v_pk_add_f32 v[218:219], v[218:219], 1.0 op_sel_hi:[1,0]
	v_pk_add_f32 v[220:221], v[220:221], 1.0 op_sel_hi:[1,0]
	v_pk_add_f32 v[222:223], v[222:223], 1.0 op_sel_hi:[1,0]
	v_rcp_f32_e32 v216, v216
	v_rcp_f32_e32 v217, v217
	v_rcp_f32_e32 v218, v218
	v_rcp_f32_e32 v219, v219
	v_rcp_f32_e32 v220, v220
	v_rcp_f32_e32 v221, v221
	v_rcp_f32_e32 v222, v222
	v_rcp_f32_e32 v223, v223
	v_lshlrev_b32_e32 v242, 16, v158
	v_and_b32_e32 v243, 0xffff0000, v158
	v_lshlrev_b32_e32 v244, 16, v159
	v_and_b32_e32 v245, 0xffff0000, v159
	v_lshlrev_b32_e32 v246, 16, v160
	v_and_b32_e32 v247, 0xffff0000, v160
	v_lshlrev_b32_e32 v248, 16, v161
	v_and_b32_e32 v249, 0xffff0000, v161
	v_pk_mul_f32 v[242:243], v[242:243], s[86:87] op_sel_hi:[1,0]
	v_pk_mul_f32 v[244:245], v[244:245], s[86:87] op_sel_hi:[1,0]
	v_pk_mul_f32 v[246:247], v[246:247], s[86:87] op_sel_hi:[1,0]
	v_pk_mul_f32 v[248:249], v[248:249], s[86:87] op_sel_hi:[1,0]
	v_exp_f32_e32 v242, v242
	v_exp_f32_e32 v243, v243
	v_exp_f32_e32 v244, v244
	v_exp_f32_e32 v245, v245
	v_exp_f32_e32 v246, v246
	v_exp_f32_e32 v247, v247
	v_exp_f32_e32 v248, v248
	v_exp_f32_e32 v249, v249
	v_pk_add_f32 v[242:243], v[242:243], 1.0 op_sel_hi:[1,0]
	v_pk_add_f32 v[244:245], v[244:245], 1.0 op_sel_hi:[1,0]
	v_pk_add_f32 v[246:247], v[246:247], 1.0 op_sel_hi:[1,0]
	v_pk_add_f32 v[248:249], v[248:249], 1.0 op_sel_hi:[1,0]
	v_pk_mul_f32 v[216:217], v[216:217], v[242:243]
	v_pk_mul_f32 v[218:219], v[218:219], v[244:245]
	v_pk_mul_f32 v[220:221], v[220:221], v[246:247]
	v_pk_mul_f32 v[222:223], v[222:223], v[248:249]
	v_pk_mul_f32 v[22:23], v[22:23], v[216:217]
	v_pk_mul_f32 v[24:25], v[24:25], v[218:219]
	v_pk_mul_f32 v[18:19], v[18:19], v[220:221]
	v_pk_mul_f32 v[20:21], v[20:21], v[222:223]
	s_waitcnt vmcnt(4)
	v_lshlrev_b32_e32 v216, 16, v162
	v_and_b32_e32 v217, 0xffff0000, v162
	v_lshlrev_b32_e32 v218, 16, v163
	v_and_b32_e32 v219, 0xffff0000, v163
	v_lshlrev_b32_e32 v220, 16, v164
	v_and_b32_e32 v221, 0xffff0000, v164
	v_lshlrev_b32_e32 v222, 16, v165
	v_and_b32_e32 v223, 0xffff0000, v165
	v_pk_mul_f32 v[216:217], v[216:217], s[86:87] op_sel_hi:[1,0]
	v_pk_mul_f32 v[218:219], v[218:219], s[86:87] op_sel_hi:[1,0]
	v_pk_mul_f32 v[220:221], v[220:221], s[86:87] op_sel_hi:[1,0]
	v_pk_mul_f32 v[222:223], v[222:223], s[86:87] op_sel_hi:[1,0]
	v_exp_f32_e32 v216, v216
	v_exp_f32_e32 v217, v217
	v_exp_f32_e32 v218, v218
	v_exp_f32_e32 v219, v219
	v_exp_f32_e32 v220, v220
	v_exp_f32_e32 v221, v221
	v_exp_f32_e32 v222, v222
	v_exp_f32_e32 v223, v223
	v_pk_add_f32 v[216:217], v[216:217], 1.0 op_sel_hi:[1,0]
	v_pk_add_f32 v[218:219], v[218:219], 1.0 op_sel_hi:[1,0]
	v_pk_add_f32 v[220:221], v[220:221], 1.0 op_sel_hi:[1,0]
	v_pk_add_f32 v[222:223], v[222:223], 1.0 op_sel_hi:[1,0]
	v_rcp_f32_e32 v216, v216
	v_rcp_f32_e32 v217, v217
	v_rcp_f32_e32 v218, v218
	v_rcp_f32_e32 v219, v219
	v_rcp_f32_e32 v220, v220
	v_rcp_f32_e32 v221, v221
	v_rcp_f32_e32 v222, v222
	v_rcp_f32_e32 v223, v223
	v_lshlrev_b32_e32 v242, 16, v166
	v_and_b32_e32 v243, 0xffff0000, v166
	v_lshlrev_b32_e32 v244, 16, v167
	v_and_b32_e32 v245, 0xffff0000, v167
	v_lshlrev_b32_e32 v246, 16, v168
	v_and_b32_e32 v247, 0xffff0000, v168
	v_lshlrev_b32_e32 v248, 16, v169
	v_and_b32_e32 v249, 0xffff0000, v169
	v_pk_mul_f32 v[242:243], v[242:243], s[86:87] op_sel_hi:[1,0]
	v_pk_mul_f32 v[244:245], v[244:245], s[86:87] op_sel_hi:[1,0]
	v_pk_mul_f32 v[246:247], v[246:247], s[86:87] op_sel_hi:[1,0]
	v_pk_mul_f32 v[248:249], v[248:249], s[86:87] op_sel_hi:[1,0]
	v_exp_f32_e32 v242, v242
	v_exp_f32_e32 v243, v243
	v_exp_f32_e32 v244, v244
	v_exp_f32_e32 v245, v245
	v_exp_f32_e32 v246, v246
	v_exp_f32_e32 v247, v247
	v_exp_f32_e32 v248, v248
	v_exp_f32_e32 v249, v249
	v_pk_add_f32 v[242:243], v[242:243], 1.0 op_sel_hi:[1,0]
	v_pk_add_f32 v[244:245], v[244:245], 1.0 op_sel_hi:[1,0]
	v_pk_add_f32 v[246:247], v[246:247], 1.0 op_sel_hi:[1,0]
	v_pk_add_f32 v[248:249], v[248:249], 1.0 op_sel_hi:[1,0]
	v_pk_mul_f32 v[216:217], v[216:217], v[242:243]
	v_pk_mul_f32 v[218:219], v[218:219], v[244:245]
	v_pk_mul_f32 v[220:221], v[220:221], v[246:247]
	v_pk_mul_f32 v[222:223], v[222:223], v[248:249]
	v_pk_mul_f32 v[46:47], v[46:47], v[216:217]
	v_pk_mul_f32 v[48:49], v[48:49], v[218:219]
	v_pk_mul_f32 v[42:43], v[42:43], v[220:221]
	v_pk_mul_f32 v[44:45], v[44:45], v[222:223]
	v_lshlrev_b32_e32 v216, 16, v170
	v_and_b32_e32 v217, 0xffff0000, v170
	v_lshlrev_b32_e32 v218, 16, v171
	v_and_b32_e32 v219, 0xffff0000, v171
	v_lshlrev_b32_e32 v220, 16, v172
	v_and_b32_e32 v221, 0xffff0000, v172
	v_lshlrev_b32_e32 v222, 16, v173
	v_and_b32_e32 v223, 0xffff0000, v173
	v_pk_mul_f32 v[216:217], v[216:217], s[86:87] op_sel_hi:[1,0]
	v_pk_mul_f32 v[218:219], v[218:219], s[86:87] op_sel_hi:[1,0]
	v_pk_mul_f32 v[220:221], v[220:221], s[86:87] op_sel_hi:[1,0]
	v_pk_mul_f32 v[222:223], v[222:223], s[86:87] op_sel_hi:[1,0]
	v_exp_f32_e32 v216, v216
	v_exp_f32_e32 v217, v217
	v_exp_f32_e32 v218, v218
	v_exp_f32_e32 v219, v219
	v_exp_f32_e32 v220, v220
	v_exp_f32_e32 v221, v221
	v_exp_f32_e32 v222, v222
	v_exp_f32_e32 v223, v223
	v_pk_add_f32 v[216:217], v[216:217], 1.0 op_sel_hi:[1,0]
	v_pk_add_f32 v[218:219], v[218:219], 1.0 op_sel_hi:[1,0]
	v_pk_add_f32 v[220:221], v[220:221], 1.0 op_sel_hi:[1,0]
	v_pk_add_f32 v[222:223], v[222:223], 1.0 op_sel_hi:[1,0]
	v_rcp_f32_e32 v216, v216
	v_rcp_f32_e32 v217, v217
	v_rcp_f32_e32 v218, v218
	v_rcp_f32_e32 v219, v219
	v_rcp_f32_e32 v220, v220
	v_rcp_f32_e32 v221, v221
	v_rcp_f32_e32 v222, v222
	v_rcp_f32_e32 v223, v223
	v_lshlrev_b32_e32 v242, 16, v174
	v_and_b32_e32 v243, 0xffff0000, v174
	v_lshlrev_b32_e32 v244, 16, v175
	v_and_b32_e32 v245, 0xffff0000, v175
	v_lshlrev_b32_e32 v246, 16, v176
	v_and_b32_e32 v247, 0xffff0000, v176
	v_lshlrev_b32_e32 v248, 16, v177
	v_and_b32_e32 v249, 0xffff0000, v177
	v_pk_mul_f32 v[242:243], v[242:243], s[86:87] op_sel_hi:[1,0]
	v_pk_mul_f32 v[244:245], v[244:245], s[86:87] op_sel_hi:[1,0]
	v_pk_mul_f32 v[246:247], v[246:247], s[86:87] op_sel_hi:[1,0]
	v_pk_mul_f32 v[248:249], v[248:249], s[86:87] op_sel_hi:[1,0]
	v_exp_f32_e32 v242, v242
	v_exp_f32_e32 v243, v243
	v_exp_f32_e32 v244, v244
	v_exp_f32_e32 v245, v245
	v_exp_f32_e32 v246, v246
	v_exp_f32_e32 v247, v247
	v_exp_f32_e32 v248, v248
	v_exp_f32_e32 v249, v249
	v_pk_add_f32 v[242:243], v[242:243], 1.0 op_sel_hi:[1,0]
	v_pk_add_f32 v[244:245], v[244:245], 1.0 op_sel_hi:[1,0]
	v_pk_add_f32 v[246:247], v[246:247], 1.0 op_sel_hi:[1,0]
	v_pk_add_f32 v[248:249], v[248:249], 1.0 op_sel_hi:[1,0]
	v_pk_mul_f32 v[216:217], v[216:217], v[242:243]
	v_pk_mul_f32 v[218:219], v[218:219], v[244:245]
	v_pk_mul_f32 v[220:221], v[220:221], v[246:247]
	v_pk_mul_f32 v[222:223], v[222:223], v[248:249]
	v_pk_mul_f32 v[14:15], v[14:15], v[216:217]
	v_pk_mul_f32 v[16:17], v[16:17], v[218:219]
	v_pk_mul_f32 v[10:11], v[10:11], v[220:221]
	v_pk_mul_f32 v[12:13], v[12:13], v[222:223]
	s_waitcnt vmcnt(0)
	v_lshlrev_b32_e32 v216, 16, v178
	v_and_b32_e32 v217, 0xffff0000, v178
	v_lshlrev_b32_e32 v218, 16, v179
	v_and_b32_e32 v219, 0xffff0000, v179
	v_lshlrev_b32_e32 v220, 16, v180
	v_and_b32_e32 v221, 0xffff0000, v180
	v_lshlrev_b32_e32 v222, 16, v181
	v_and_b32_e32 v223, 0xffff0000, v181
	v_pk_mul_f32 v[216:217], v[216:217], s[86:87] op_sel_hi:[1,0]
	v_pk_mul_f32 v[218:219], v[218:219], s[86:87] op_sel_hi:[1,0]
	v_pk_mul_f32 v[220:221], v[220:221], s[86:87] op_sel_hi:[1,0]
	v_pk_mul_f32 v[222:223], v[222:223], s[86:87] op_sel_hi:[1,0]
	v_exp_f32_e32 v216, v216
	v_exp_f32_e32 v217, v217
	v_exp_f32_e32 v218, v218
	v_exp_f32_e32 v219, v219
	v_exp_f32_e32 v220, v220
	v_exp_f32_e32 v221, v221
	v_exp_f32_e32 v222, v222
	v_exp_f32_e32 v223, v223
	v_pk_add_f32 v[216:217], v[216:217], 1.0 op_sel_hi:[1,0]
	v_pk_add_f32 v[218:219], v[218:219], 1.0 op_sel_hi:[1,0]
	v_pk_add_f32 v[220:221], v[220:221], 1.0 op_sel_hi:[1,0]
	v_pk_add_f32 v[222:223], v[222:223], 1.0 op_sel_hi:[1,0]
	v_rcp_f32_e32 v216, v216
	v_rcp_f32_e32 v217, v217
	v_rcp_f32_e32 v218, v218
	v_rcp_f32_e32 v219, v219
	v_rcp_f32_e32 v220, v220
	v_rcp_f32_e32 v221, v221
	v_rcp_f32_e32 v222, v222
	v_rcp_f32_e32 v223, v223
	v_lshlrev_b32_e32 v242, 16, v182
	v_and_b32_e32 v243, 0xffff0000, v182
	v_lshlrev_b32_e32 v244, 16, v183
	v_and_b32_e32 v245, 0xffff0000, v183
	v_lshlrev_b32_e32 v246, 16, v184
	v_and_b32_e32 v247, 0xffff0000, v184
	v_lshlrev_b32_e32 v248, 16, v185
	v_and_b32_e32 v249, 0xffff0000, v185
	v_pk_mul_f32 v[242:243], v[242:243], s[86:87] op_sel_hi:[1,0]
	v_pk_mul_f32 v[244:245], v[244:245], s[86:87] op_sel_hi:[1,0]
	v_pk_mul_f32 v[246:247], v[246:247], s[86:87] op_sel_hi:[1,0]
	v_pk_mul_f32 v[248:249], v[248:249], s[86:87] op_sel_hi:[1,0]
	v_exp_f32_e32 v242, v242
	v_exp_f32_e32 v243, v243
	v_exp_f32_e32 v244, v244
	v_exp_f32_e32 v245, v245
	v_exp_f32_e32 v246, v246
	v_exp_f32_e32 v247, v247
	v_exp_f32_e32 v248, v248
	v_exp_f32_e32 v249, v249
	v_pk_add_f32 v[242:243], v[242:243], 1.0 op_sel_hi:[1,0]
	v_pk_add_f32 v[244:245], v[244:245], 1.0 op_sel_hi:[1,0]
	v_pk_add_f32 v[246:247], v[246:247], 1.0 op_sel_hi:[1,0]
	v_pk_add_f32 v[248:249], v[248:249], 1.0 op_sel_hi:[1,0]
	v_pk_mul_f32 v[216:217], v[216:217], v[242:243]
	v_pk_mul_f32 v[218:219], v[218:219], v[244:245]
	v_pk_mul_f32 v[220:221], v[220:221], v[246:247]
	v_pk_mul_f32 v[222:223], v[222:223], v[248:249]
	v_pk_mul_f32 v[38:39], v[38:39], v[216:217]
	v_pk_mul_f32 v[40:41], v[40:41], v[218:219]
	v_pk_mul_f32 v[34:35], v[34:35], v[220:221]
	v_pk_mul_f32 v[36:37], v[36:37], v[222:223]
	v_lshlrev_b32_e32 v216, 16, v186
	v_and_b32_e32 v217, 0xffff0000, v186
	v_lshlrev_b32_e32 v218, 16, v187
	v_and_b32_e32 v219, 0xffff0000, v187
	v_lshlrev_b32_e32 v220, 16, v188
	v_and_b32_e32 v221, 0xffff0000, v188
	v_lshlrev_b32_e32 v222, 16, v189
	v_and_b32_e32 v223, 0xffff0000, v189
	v_pk_mul_f32 v[216:217], v[216:217], s[86:87] op_sel_hi:[1,0]
	v_pk_mul_f32 v[218:219], v[218:219], s[86:87] op_sel_hi:[1,0]
	v_pk_mul_f32 v[220:221], v[220:221], s[86:87] op_sel_hi:[1,0]
	v_pk_mul_f32 v[222:223], v[222:223], s[86:87] op_sel_hi:[1,0]
	v_exp_f32_e32 v216, v216
	v_exp_f32_e32 v217, v217
	v_exp_f32_e32 v218, v218
	v_exp_f32_e32 v219, v219
	v_exp_f32_e32 v220, v220
	v_exp_f32_e32 v221, v221
	v_exp_f32_e32 v222, v222
	v_exp_f32_e32 v223, v223
	v_pk_add_f32 v[216:217], v[216:217], 1.0 op_sel_hi:[1,0]
	v_pk_add_f32 v[218:219], v[218:219], 1.0 op_sel_hi:[1,0]
	v_pk_add_f32 v[220:221], v[220:221], 1.0 op_sel_hi:[1,0]
	v_pk_add_f32 v[222:223], v[222:223], 1.0 op_sel_hi:[1,0]
	v_rcp_f32_e32 v216, v216
	v_rcp_f32_e32 v217, v217
	v_rcp_f32_e32 v218, v218
	v_rcp_f32_e32 v219, v219
	v_rcp_f32_e32 v220, v220
	v_rcp_f32_e32 v221, v221
	v_rcp_f32_e32 v222, v222
	v_rcp_f32_e32 v223, v223
	v_lshlrev_b32_e32 v242, 16, v190
	v_and_b32_e32 v243, 0xffff0000, v190
	v_lshlrev_b32_e32 v244, 16, v191
	v_and_b32_e32 v245, 0xffff0000, v191
	v_lshlrev_b32_e32 v246, 16, v192
	v_and_b32_e32 v247, 0xffff0000, v192
	v_lshlrev_b32_e32 v248, 16, v193
	v_and_b32_e32 v249, 0xffff0000, v193
	v_pk_mul_f32 v[242:243], v[242:243], s[86:87] op_sel_hi:[1,0]
	v_pk_mul_f32 v[244:245], v[244:245], s[86:87] op_sel_hi:[1,0]
	v_pk_mul_f32 v[246:247], v[246:247], s[86:87] op_sel_hi:[1,0]
	v_pk_mul_f32 v[248:249], v[248:249], s[86:87] op_sel_hi:[1,0]
	v_exp_f32_e32 v242, v242
	v_exp_f32_e32 v243, v243
	v_exp_f32_e32 v244, v244
	v_exp_f32_e32 v245, v245
	v_exp_f32_e32 v246, v246
	v_exp_f32_e32 v247, v247
	v_exp_f32_e32 v248, v248
	v_exp_f32_e32 v249, v249
	v_pk_add_f32 v[242:243], v[242:243], 1.0 op_sel_hi:[1,0]
	v_pk_add_f32 v[244:245], v[244:245], 1.0 op_sel_hi:[1,0]
	v_pk_add_f32 v[246:247], v[246:247], 1.0 op_sel_hi:[1,0]
	v_pk_add_f32 v[248:249], v[248:249], 1.0 op_sel_hi:[1,0]
	v_pk_mul_f32 v[216:217], v[216:217], v[242:243]
	v_pk_mul_f32 v[218:219], v[218:219], v[244:245]
	v_pk_mul_f32 v[220:221], v[220:221], v[246:247]
	v_pk_mul_f32 v[222:223], v[222:223], v[248:249]
	v_pk_mul_f32 v[6:7], v[6:7], v[216:217]
	v_pk_mul_f32 v[8:9], v[8:9], v[218:219]
	v_pk_mul_f32 v[2:3], v[2:3], v[220:221]
	v_pk_mul_f32 v[4:5], v[4:5], v[222:223]
	s_branch .Lem_done

.LBB0_504:
	v_add_u32_e32 v253, 0x10000, v163
	ds_read_b128 v[130:133], v253
	ds_read_b128 v[134:137], v253 offset:1024
	ds_read_b128 v[150:153], v253 offset:2048
	ds_read_b128 v[154:157], v253 offset:3072
	s_add_u32 s10, s52, 0xfff80080
	s_addc_u32 s11, s53, -1
	s_cmp_eq_u32 s29, 28
	s_cselect_b32 s11, s9, s11
	s_cselect_b32 s10, s8, s10
	s_cselect_b32 s55, s35, s7
	s_cselect_b32 s54, s34, s5
	s_add_i32 m0, s42, 0xc000
	ds_read_b128 v[158:161], v162
	ds_read_b128 v[166:169], v162 offset:1024
	ds_read_b128 v[170:173], v162 offset:2048
	ds_read_b128 v[174:177], v162 offset:3072
	ds_read_b128 v[178:181], v162 offset:4096
	ds_read_b128 v[182:185], v162 offset:5120
	ds_read_b128 v[186:189], v162 offset:6144
	ds_read_b128 v[190:193], v162 offset:7168
	global_load_lds_dwordx4 v146, s[52:53]
	s_add_i32 m0, s42, 0xe000
	s_nop 0
	global_load_lds_dwordx4 v148, s[52:53]
	s_waitcnt lgkmcnt(8)
	s_setprio 1
	s_barrier
	s_waitcnt lgkmcnt(0)
	v_mfma_f32_16x16x32_bf16 v[126:129], v[130:133], v[158:161], v[126:129]
	v_mfma_f32_16x16x32_bf16 v[122:125], v[150:153], v[158:161], v[122:125]
	v_mfma_f32_16x16x32_bf16 v[118:121], v[130:133], v[170:173], v[118:121]
	v_mfma_f32_16x16x32_bf16 v[114:117], v[150:153], v[170:173], v[114:117]
	v_mfma_f32_16x16x32_bf16 v[110:113], v[130:133], v[178:181], v[110:113]
	v_mfma_f32_16x16x32_bf16 v[106:109], v[150:153], v[178:181], v[106:109]
	v_mfma_f32_16x16x32_bf16 v[102:105], v[130:133], v[186:189], v[102:105]
	v_mfma_f32_16x16x32_bf16 v[98:101], v[150:153], v[186:189], v[98:101]
	v_mfma_f32_16x16x32_bf16 v[126:129], v[134:137], v[166:169], v[126:129]
	v_mfma_f32_16x16x32_bf16 v[122:125], v[154:157], v[166:169], v[122:125]
	v_mfma_f32_16x16x32_bf16 v[118:121], v[134:137], v[174:177], v[118:121]
	v_mfma_f32_16x16x32_bf16 v[114:117], v[154:157], v[174:177], v[114:117]
	v_mfma_f32_16x16x32_bf16 v[110:113], v[134:137], v[182:185], v[110:113]
	v_mfma_f32_16x16x32_bf16 v[106:109], v[154:157], v[182:185], v[106:109]
	v_mfma_f32_16x16x32_bf16 v[102:105], v[134:137], v[190:193], v[102:105]
	v_mfma_f32_16x16x32_bf16 v[98:101], v[154:157], v[190:193], v[98:101]
	s_barrier
	s_setprio 0
	s_mov_b32 m0, s41
	ds_read_b128 v[206:209], v253 offset:16384
	ds_read_b128 v[210:213], v253 offset:17408
	v_lshl_add_u64 v[222:223], s[54:55], 0, v[194:195]
	ds_read_b128 v[214:217], v253 offset:18432
	ds_read_b128 v[218:221], v253 offset:19456
	global_load_lds_dwordx4 v[222:223], off
	v_lshl_add_u64 v[224:225], s[54:55], 0, v[138:139]
	s_mov_b32 m0, s57
	s_nop 0
	global_load_lds_dwordx4 v[224:225], off
	s_setprio 1
	s_barrier
	s_waitcnt lgkmcnt(0)
	v_mfma_f32_16x16x32_bf16 v[62:65], v[206:209], v[158:161], v[62:65]
	v_mfma_f32_16x16x32_bf16 v[58:61], v[214:217], v[158:161], v[58:61]
	v_mfma_f32_16x16x32_bf16 v[54:57], v[206:209], v[170:173], v[54:57]
	v_mfma_f32_16x16x32_bf16 v[46:49], v[214:217], v[170:173], v[46:49]
	v_mfma_f32_16x16x32_bf16 v[50:53], v[206:209], v[178:181], v[50:53]
	v_mfma_f32_16x16x32_bf16 v[42:45], v[214:217], v[178:181], v[42:45]
	v_mfma_f32_16x16x32_bf16 v[38:41], v[206:209], v[186:189], v[38:41]
	v_mfma_f32_16x16x32_bf16 v[34:37], v[214:217], v[186:189], v[34:37]
	v_mfma_f32_16x16x32_bf16 v[62:65], v[210:213], v[166:169], v[62:65]
	v_mfma_f32_16x16x32_bf16 v[58:61], v[218:221], v[166:169], v[58:61]
	v_mfma_f32_16x16x32_bf16 v[54:57], v[210:213], v[174:177], v[54:57]
	v_mfma_f32_16x16x32_bf16 v[46:49], v[218:221], v[174:177], v[46:49]
	v_mfma_f32_16x16x32_bf16 v[50:53], v[210:213], v[182:185], v[50:53]
	v_mfma_f32_16x16x32_bf16 v[42:45], v[218:221], v[182:185], v[42:45]
	s_mov_b32 m0, s42
	v_mfma_f32_16x16x32_bf16 v[38:41], v[210:213], v[190:193], v[38:41]
	v_lshl_add_u64 v[226:227], s[10:11], 0, v[142:143]
	v_mfma_f32_16x16x32_bf16 v[34:37], v[218:221], v[190:193], v[34:37]
	s_barrier
	s_setprio 0
	ds_read_b128 v[158:161], v162 offset:16384
	ds_read_b128 v[166:169], v162 offset:17408
	ds_read_b128 v[170:173], v162 offset:18432
	ds_read_b128 v[174:177], v162 offset:19456
	ds_read_b128 v[178:181], v162 offset:20480
	ds_read_b128 v[182:185], v162 offset:21504
	ds_read_b128 v[186:189], v162 offset:22528
	ds_read_b128 v[190:193], v162 offset:23552
	global_load_lds_dwordx4 v[226:227], off
	v_lshl_add_u64 v[228:229], s[10:11], 0, v[140:141]
	s_mov_b32 m0, s58
	s_nop 0
	global_load_lds_dwordx4 v[228:229], off
	s_setprio 1
	s_barrier
	s_waitcnt lgkmcnt(0)
	v_mfma_f32_16x16x32_bf16 v[94:97], v[130:133], v[158:161], v[94:97]
	v_mfma_f32_16x16x32_bf16 v[90:93], v[150:153], v[158:161], v[90:93]
	v_mfma_f32_16x16x32_bf16 v[86:89], v[130:133], v[170:173], v[86:89]
	v_mfma_f32_16x16x32_bf16 v[82:85], v[150:153], v[170:173], v[82:85]
	v_mfma_f32_16x16x32_bf16 v[78:81], v[130:133], v[178:181], v[78:81]
	v_mfma_f32_16x16x32_bf16 v[74:77], v[150:153], v[178:181], v[74:77]
	v_mfma_f32_16x16x32_bf16 v[70:73], v[130:133], v[186:189], v[70:73]
	v_mfma_f32_16x16x32_bf16 v[66:69], v[150:153], v[186:189], v[66:69]
	v_mfma_f32_16x16x32_bf16 v[94:97], v[134:137], v[166:169], v[94:97]
	v_mfma_f32_16x16x32_bf16 v[90:93], v[154:157], v[166:169], v[90:93]
	v_mfma_f32_16x16x32_bf16 v[86:89], v[134:137], v[174:177], v[86:89]
	v_mfma_f32_16x16x32_bf16 v[82:85], v[154:157], v[174:177], v[82:85]
	v_mfma_f32_16x16x32_bf16 v[78:81], v[134:137], v[182:185], v[78:81]
	v_mfma_f32_16x16x32_bf16 v[74:77], v[154:157], v[182:185], v[74:77]
	v_mfma_f32_16x16x32_bf16 v[70:73], v[134:137], v[190:193], v[70:73]
	v_mfma_f32_16x16x32_bf16 v[66:69], v[154:157], v[190:193], v[66:69]
	s_barrier
	s_setprio 0
	s_add_u32 s86, s54, 0x80000
	s_addc_u32 s87, s55, 0
	s_mov_b32 m0, s59
	s_nop 0
	global_load_lds_dwordx4 v194, s[86:87]
	s_mov_b32 m0, s60
	s_nop 0
	global_load_lds_dwordx4 v138, s[86:87]
	s_waitcnt vmcnt(6)
	s_setprio 1
	s_barrier
	v_mfma_f32_16x16x32_bf16 v[30:33], v[206:209], v[158:161], v[30:33]
	v_mfma_f32_16x16x32_bf16 v[18:21], v[214:217], v[158:161], v[18:21]
	v_mfma_f32_16x16x32_bf16 v[26:29], v[206:209], v[170:173], v[26:29]
	v_mfma_f32_16x16x32_bf16 v[14:17], v[214:217], v[170:173], v[14:17]
	v_mfma_f32_16x16x32_bf16 v[22:25], v[206:209], v[178:181], v[22:25]
	v_mfma_f32_16x16x32_bf16 v[6:9], v[214:217], v[178:181], v[6:9]
	v_mfma_f32_16x16x32_bf16 v[10:13], v[206:209], v[186:189], v[10:13]
	v_mfma_f32_16x16x32_bf16 v[2:5], v[214:217], v[186:189], v[2:5]
	v_mfma_f32_16x16x32_bf16 v[30:33], v[210:213], v[166:169], v[30:33]
	v_mfma_f32_16x16x32_bf16 v[18:21], v[218:221], v[166:169], v[18:21]
	v_mfma_f32_16x16x32_bf16 v[26:29], v[210:213], v[174:177], v[26:29]
	v_mfma_f32_16x16x32_bf16 v[14:17], v[218:221], v[174:177], v[14:17]
	v_mfma_f32_16x16x32_bf16 v[22:25], v[210:213], v[182:185], v[22:25]
	v_mfma_f32_16x16x32_bf16 v[6:9], v[218:221], v[182:185], v[6:9]
	v_mfma_f32_16x16x32_bf16 v[10:13], v[210:213], v[190:193], v[10:13]
	v_mfma_f32_16x16x32_bf16 v[2:5], v[218:221], v[190:193], v[2:5]
	s_barrier
	s_setprio 0
	ds_read_b128 v[130:133], v253 offset:32768
	ds_read_b128 v[134:137], v253 offset:33792
	ds_read_b128 v[150:153], v253 offset:34816
	ds_read_b128 v[154:157], v253 offset:35840
	s_add_u32 s10, s10, 0x80000
	s_addc_u32 s11, s11, 0
	s_mov_b32 m0, s61
	ds_read_b128 v[158:161], v162 offset:32768
	ds_read_b128 v[166:169], v162 offset:33792
	ds_read_b128 v[170:173], v162 offset:34816
	ds_read_b128 v[174:177], v162 offset:35840
	ds_read_b128 v[178:181], v162 offset:36864
	ds_read_b128 v[182:185], v162 offset:37888
	ds_read_b128 v[186:189], v162 offset:38912
	ds_read_b128 v[190:193], v162 offset:39936
	global_load_lds_dwordx4 v142, s[10:11]
	s_mov_b32 m0, s62
	s_nop 0
	global_load_lds_dwordx4 v140, s[10:11]
	s_waitcnt lgkmcnt(8)
	s_setprio 1
	s_barrier
	s_waitcnt lgkmcnt(0)
	v_mfma_f32_16x16x32_bf16 v[126:129], v[130:133], v[158:161], v[126:129]
	v_mfma_f32_16x16x32_bf16 v[122:125], v[150:153], v[158:161], v[122:125]
	v_mfma_f32_16x16x32_bf16 v[118:121], v[130:133], v[170:173], v[118:121]
	v_mfma_f32_16x16x32_bf16 v[114:117], v[150:153], v[170:173], v[114:117]
	v_mfma_f32_16x16x32_bf16 v[110:113], v[130:133], v[178:181], v[110:113]
	v_mfma_f32_16x16x32_bf16 v[106:109], v[150:153], v[178:181], v[106:109]
	v_mfma_f32_16x16x32_bf16 v[102:105], v[130:133], v[186:189], v[102:105]
	v_mfma_f32_16x16x32_bf16 v[98:101], v[150:153], v[186:189], v[98:101]
	v_mfma_f32_16x16x32_bf16 v[126:129], v[134:137], v[166:169], v[126:129]
	v_mfma_f32_16x16x32_bf16 v[122:125], v[154:157], v[166:169], v[122:125]
	v_mfma_f32_16x16x32_bf16 v[118:121], v[134:137], v[174:177], v[118:121]
	v_mfma_f32_16x16x32_bf16 v[114:117], v[154:157], v[174:177], v[114:117]
	v_mfma_f32_16x16x32_bf16 v[110:113], v[134:137], v[182:185], v[110:113]
	v_mfma_f32_16x16x32_bf16 v[106:109], v[154:157], v[182:185], v[106:109]
	v_mfma_f32_16x16x32_bf16 v[102:105], v[134:137], v[190:193], v[102:105]
	v_mfma_f32_16x16x32_bf16 v[98:101], v[154:157], v[190:193], v[98:101]
	s_barrier
	s_setprio 0
	s_mov_b32 m0, s70
	ds_read_b128 v[206:209], v253 offset:49152
	ds_read_b128 v[210:213], v253 offset:50176
	v_lshl_add_u64 v[222:223], v[222:223], 0, s[76:77]
	ds_read_b128 v[214:217], v253 offset:51200
	ds_read_b128 v[218:221], v253 offset:52224
	global_load_lds_dwordx4 v[222:223], off
	v_lshl_add_u64 v[222:223], v[224:225], 0, s[76:77]
	s_mov_b32 m0, s71
	s_nop 0
	global_load_lds_dwordx4 v[222:223], off
	s_setprio 1
	s_barrier
	s_waitcnt lgkmcnt(0)
	v_mfma_f32_16x16x32_bf16 v[62:65], v[206:209], v[158:161], v[62:65]
	v_mfma_f32_16x16x32_bf16 v[58:61], v[214:217], v[158:161], v[58:61]
	v_mfma_f32_16x16x32_bf16 v[54:57], v[206:209], v[170:173], v[54:57]
	v_mfma_f32_16x16x32_bf16 v[46:49], v[214:217], v[170:173], v[46:49]
	v_mfma_f32_16x16x32_bf16 v[50:53], v[206:209], v[178:181], v[50:53]
	v_mfma_f32_16x16x32_bf16 v[42:45], v[214:217], v[178:181], v[42:45]
	v_mfma_f32_16x16x32_bf16 v[38:41], v[206:209], v[186:189], v[38:41]
	v_mfma_f32_16x16x32_bf16 v[34:37], v[214:217], v[186:189], v[34:37]
	v_mfma_f32_16x16x32_bf16 v[62:65], v[210:213], v[166:169], v[62:65]
	v_mfma_f32_16x16x32_bf16 v[58:61], v[218:221], v[166:169], v[58:61]
	v_mfma_f32_16x16x32_bf16 v[54:57], v[210:213], v[174:177], v[54:57]
	v_mfma_f32_16x16x32_bf16 v[46:49], v[218:221], v[174:177], v[46:49]
	v_mfma_f32_16x16x32_bf16 v[50:53], v[210:213], v[182:185], v[50:53]
	v_mfma_f32_16x16x32_bf16 v[42:45], v[218:221], v[182:185], v[42:45]
	s_mov_b32 m0, s78
	v_mfma_f32_16x16x32_bf16 v[38:41], v[210:213], v[190:193], v[38:41]
	v_lshl_add_u64 v[222:223], v[226:227], 0, s[76:77]
	v_mfma_f32_16x16x32_bf16 v[34:37], v[218:221], v[190:193], v[34:37]
	s_barrier
	s_setprio 0
	ds_read_b128 v[158:161], v162 offset:49152
	ds_read_b128 v[166:169], v162 offset:50176
	ds_read_b128 v[170:173], v162 offset:51200
	ds_read_b128 v[174:177], v162 offset:52224
	ds_read_b128 v[178:181], v162 offset:53248
	ds_read_b128 v[182:185], v162 offset:54272
	ds_read_b128 v[186:189], v162 offset:55296
	ds_read_b128 v[190:193], v162 offset:56320
	global_load_lds_dwordx4 v[222:223], off
	v_lshl_add_u64 v[222:223], v[228:229], 0, s[76:77]
	s_mov_b32 m0, s79
	s_nop 0
	global_load_lds_dwordx4 v[222:223], off
	s_setprio 1
	s_barrier
	s_waitcnt lgkmcnt(0)
	v_mfma_f32_16x16x32_bf16 v[94:97], v[130:133], v[158:161], v[94:97]
	v_mfma_f32_16x16x32_bf16 v[90:93], v[150:153], v[158:161], v[90:93]
	v_mfma_f32_16x16x32_bf16 v[86:89], v[130:133], v[170:173], v[86:89]
	v_mfma_f32_16x16x32_bf16 v[82:85], v[150:153], v[170:173], v[82:85]
	v_mfma_f32_16x16x32_bf16 v[78:81], v[130:133], v[178:181], v[78:81]
	v_mfma_f32_16x16x32_bf16 v[74:77], v[150:153], v[178:181], v[74:77]
	v_mfma_f32_16x16x32_bf16 v[70:73], v[130:133], v[186:189], v[70:73]
	v_mfma_f32_16x16x32_bf16 v[66:69], v[150:153], v[186:189], v[66:69]
	v_mfma_f32_16x16x32_bf16 v[94:97], v[134:137], v[166:169], v[94:97]
	v_mfma_f32_16x16x32_bf16 v[90:93], v[154:157], v[166:169], v[90:93]
	v_mfma_f32_16x16x32_bf16 v[86:89], v[134:137], v[174:177], v[86:89]
	v_mfma_f32_16x16x32_bf16 v[82:85], v[154:157], v[174:177], v[82:85]
	v_mfma_f32_16x16x32_bf16 v[78:81], v[134:137], v[182:185], v[78:81]
	v_mfma_f32_16x16x32_bf16 v[74:77], v[154:157], v[182:185], v[74:77]
	v_mfma_f32_16x16x32_bf16 v[70:73], v[134:137], v[190:193], v[70:73]
	v_mfma_f32_16x16x32_bf16 v[66:69], v[154:157], v[190:193], v[66:69]
	s_barrier
	s_setprio 0
	s_add_u32 s10, s54, 0x80080
	s_addc_u32 s11, s55, 0
	s_mov_b32 m0, s80
	s_nop 0
	global_load_lds_dwordx4 v194, s[10:11]
	s_mov_b32 m0, s81
	s_nop 0
	global_load_lds_dwordx4 v138, s[10:11]
	s_waitcnt vmcnt(6)
	s_setprio 1
	s_barrier
	v_mfma_f32_16x16x32_bf16 v[30:33], v[206:209], v[158:161], v[30:33]
	v_mfma_f32_16x16x32_bf16 v[18:21], v[214:217], v[158:161], v[18:21]
	v_mfma_f32_16x16x32_bf16 v[26:29], v[206:209], v[170:173], v[26:29]
	v_mfma_f32_16x16x32_bf16 v[14:17], v[214:217], v[170:173], v[14:17]
	v_mfma_f32_16x16x32_bf16 v[22:25], v[206:209], v[178:181], v[22:25]
	v_mfma_f32_16x16x32_bf16 v[6:9], v[214:217], v[178:181], v[6:9]
	v_mfma_f32_16x16x32_bf16 v[10:13], v[206:209], v[186:189], v[10:13]
	v_mfma_f32_16x16x32_bf16 v[2:5], v[214:217], v[186:189], v[2:5]
	v_mfma_f32_16x16x32_bf16 v[30:33], v[210:213], v[166:169], v[30:33]
	v_mfma_f32_16x16x32_bf16 v[18:21], v[218:221], v[166:169], v[18:21]
	v_mfma_f32_16x16x32_bf16 v[26:29], v[210:213], v[174:177], v[26:29]
	v_mfma_f32_16x16x32_bf16 v[14:17], v[218:221], v[174:177], v[14:17]
	v_mfma_f32_16x16x32_bf16 v[22:25], v[210:213], v[182:185], v[22:25]
	v_mfma_f32_16x16x32_bf16 v[6:9], v[218:221], v[182:185], v[6:9]
	v_mfma_f32_16x16x32_bf16 v[10:13], v[210:213], v[190:193], v[10:13]
	v_mfma_f32_16x16x32_bf16 v[2:5], v[218:221], v[190:193], v[2:5]
	s_setprio 0
	s_add_i32 s29, s29, 2
	s_add_u32 s52, s52, 0x100
	s_addc_u32 s53, s53, 0
	s_add_u32 s5, s5, 0x100
	s_addc_u32 s7, s7, 0
	s_cmp_gt_u32 s29, 29
	s_barrier
	s_cbranch_scc0 .LBB0_504
	v_readlane_b32 s10, v250, 21
	s_cmp_gt_i32 s40, 63
	v_readlane_b32 s11, v250, 22
	s_mov_b64 s[20:21], s[48:49]
	s_cselect_b32 s11, s21, s11
	s_cselect_b32 s10, s20, s10
	v_readlane_b32 s20, v252, 0
	v_readlane_b32 s26, v252, 6
	v_readlane_b32 s27, v252, 7
	s_cselect_b32 s53, s3, s27
	s_cselect_b32 s52, s2, s26
	s_sub_i32 s5, s40, 64
	s_cmp_gt_i32 s40, 63
	s_cselect_b32 s54, s5, s40
	s_lshr_b32 s5, s40, 3
	s_cmp_gt_i32 s40, 63
	s_mulk_i32 s5, 0x1800
	v_lshl_or_b32 v130, s28, 8, v164
	s_cselect_b32 s28, 0xc000, s5
	s_ashr_i32 s29, s28, 31
	s_lshl_b64 s[28:29], s[28:29], 2
	s_add_u32 s28, s63, s28
	v_ashrrev_i32_e32 v131, 31, v130
	s_addc_u32 s29, s67, s29
	v_lshlrev_b64 v[130:131], 2, v[130:131]
	v_lshl_add_u64 v[132:133], s[28:29], 0, v[130:131]
	s_mov_b64 s[28:29], 0x6484000
	s_ashr_i32 s55, s54, 31
	v_lshl_add_u64 v[154:155], v[132:133], 0, s[28:29]
	s_lshl_b64 s[28:29], s[54:55], 19
	v_lshl_add_u64 v[134:135], s[28:29], 0, v[144:145]
	v_lshlrev_b64 v[134:135], 2, v[134:135]
	v_lshl_add_u64 v[136:137], s[10:11], 0, v[134:135]
	v_lshl_add_u64 v[134:135], s[52:53], 0, v[134:135]
	s_mov_b32 s5, 0x6484000
	v_lshl_add_u64 v[150:151], v[136:137], 0, v[130:131]
	v_lshl_add_u64 v[152:153], v[134:135], 0, v[130:131]
	v_add_co_u32_e32 v130, vcc, s5, v132
	s_mov_b64 s[10:11], 0x20000
	s_nop 0
	v_addc_co_u32_e32 v131, vcc, 0, v133, vcc
	v_add_co_u32_e32 v156, vcc, s13, v150
	global_load_dwordx4 v[134:137], v[130:131], off
	s_nop 0
	global_load_dwordx4 v[130:133], v[154:155], off offset:16
	global_load_dwordx4 v[166:169], v[150:151], off offset:16
	global_load_dwordx4 v[170:173], v[150:151], off
	v_lshl_add_u64 v[158:159], v[150:151], 0, s[10:11]
	v_addc_co_u32_e32 v157, vcc, 0, v151, vcc
	s_mov_b32 s5, 0x40000
	global_load_dwordx4 v[174:177], v[156:157], off
	global_load_dwordx4 v[178:181], v[158:159], off offset:16
	s_mov_b64 s[10:11], 0x40000
	v_add_co_u32_e32 v158, vcc, s5, v150
	v_lshl_add_u64 v[160:161], v[150:151], 0, s[10:11]
	s_nop 0
	v_addc_co_u32_e32 v159, vcc, 0, v151, vcc
	s_mov_b32 s7, 0x60000
	global_load_dwordx4 v[182:185], v[158:159], off
	global_load_dwordx4 v[186:189], v[160:161], off offset:16
	s_mov_b64 s[10:11], 0x60000
	v_add_co_u32_e32 v160, vcc, s7, v150
	v_lshl_add_u64 v[206:207], v[150:151], 0, s[10:11]
	s_nop 0
	v_addc_co_u32_e32 v161, vcc, 0, v151, vcc
	global_load_dwordx4 v[190:193], v[160:161], off
	s_nop 0
	global_load_dwordx4 v[206:209], v[206:207], off offset:16
	v_readlane_b32 s21, v252, 1
	v_readlane_b32 s22, v252, 2
	v_readlane_b32 s23, v252, 3
	v_readlane_b32 s24, v252, 4
	v_readlane_b32 s25, v252, 5
	s_waitcnt vmcnt(0)
	v_pk_fma_f32 v[124:125], v[124:125], v[132:133], v[168:169]
	v_pk_fma_f32 v[122:123], v[122:123], v[130:131], v[166:167]
	global_store_dwordx4 v[152:153], v[122:125], off offset:16
	v_pk_fma_f32 v[128:129], v[128:129], v[136:137], v[172:173]
	v_pk_fma_f32 v[126:127], v[126:127], v[134:135], v[170:171]
	v_pk_fma_f32 v[122:123], v[120:121], v[136:137], v[176:177]
	v_pk_fma_f32 v[120:121], v[118:119], v[134:135], v[174:175]
	v_add_co_u32_e32 v118, vcc, s13, v152
	v_pk_fma_f32 v[116:117], v[116:117], v[132:133], v[180:181]
	s_nop 0
	v_addc_co_u32_e32 v119, vcc, 0, v153, vcc
	v_pk_fma_f32 v[114:115], v[114:115], v[130:131], v[178:179]
	global_store_dwordx4 v[118:119], v[114:117], off offset:16
	v_pk_fma_f32 v[108:109], v[108:109], v[132:133], v[188:189]
	v_pk_fma_f32 v[106:107], v[106:107], v[130:131], v[186:187]
	v_pk_fma_f32 v[114:115], v[112:113], v[136:137], v[184:185]
	v_pk_fma_f32 v[112:113], v[110:111], v[134:135], v[182:183]
	v_add_co_u32_e32 v110, vcc, s5, v152
	global_store_dwordx4 v[152:153], v[126:129], off
	s_nop 0
	v_addc_co_u32_e32 v111, vcc, 0, v153, vcc
	global_store_dwordx4 v[110:111], v[106:109], off offset:16
	v_pk_fma_f32 v[100:101], v[100:101], v[132:133], v[208:209]
	v_pk_fma_f32 v[98:99], v[98:99], v[130:131], v[206:207]
	v_pk_fma_f32 v[106:107], v[104:105], v[136:137], v[192:193]
	v_pk_fma_f32 v[104:105], v[102:103], v[134:135], v[190:191]
	v_add_co_u32_e32 v102, vcc, s7, v152
	global_store_dwordx4 v[118:119], v[120:123], off
	s_nop 0
	v_addc_co_u32_e32 v103, vcc, 0, v153, vcc
	global_store_dwordx4 v[110:111], v[112:115], off
	global_store_dwordx4 v[102:103], v[104:107], off
	global_store_dwordx4 v[102:103], v[98:101], off offset:16
	s_mov_b32 s5, 0x100000
	s_mov_b64 s[10:11], 0x100000
	v_add_co_u32_e32 v98, vcc, s5, v150
	v_lshl_add_u64 v[100:101], v[150:151], 0, s[10:11]
	s_nop 0
	v_addc_co_u32_e32 v99, vcc, 0, v151, vcc
	global_load_dwordx4 v[112:115], v[98:99], off
	global_load_dwordx4 v[120:123], v[100:101], off offset:16
	s_mov_b64 s[10:11], 0x120000
	v_add_co_u32_e32 v100, vcc, s45, v150
	v_lshl_add_u64 v[104:105], v[150:151], 0, s[10:11]
	s_nop 0
	v_addc_co_u32_e32 v101, vcc, 0, v151, vcc
	s_mov_b64 s[10:11], 0x140000
	s_mov_b32 s7, 0x140000
	global_load_dwordx4 v[124:127], v[100:101], off
	global_load_dwordx4 v[166:169], v[104:105], off offset:16
	v_lshl_add_u64 v[106:107], v[150:151], 0, s[10:11]
	v_add_co_u32_e32 v104, vcc, s7, v150
	s_mov_b64 s[10:11], 0x160000
	s_nop 0
	v_addc_co_u32_e32 v105, vcc, 0, v151, vcc
	v_lshl_add_u64 v[108:109], v[150:151], 0, s[10:11]
	s_mov_b32 s10, 0x160000
	global_load_dwordx4 v[170:173], v[104:105], off
	global_load_dwordx4 v[174:177], v[106:107], off offset:16
	v_add_co_u32_e32 v106, vcc, s10, v150
	s_waitcnt vmcnt(0)
	v_pk_fma_f32 v[112:113], v[94:95], v[134:135], v[112:113]
	v_addc_co_u32_e32 v107, vcc, 0, v151, vcc
	global_load_dwordx4 v[178:181], v[106:107], off
	global_load_dwordx4 v[182:185], v[108:109], off offset:16
	v_add_co_u32_e32 v94, vcc, s5, v152
	v_pk_fma_f32 v[92:93], v[92:93], v[132:133], v[122:123]
	s_nop 0
	v_addc_co_u32_e32 v95, vcc, 0, v153, vcc
	v_pk_fma_f32 v[90:91], v[90:91], v[130:131], v[120:121]
	global_store_dwordx4 v[94:95], v[90:93], off offset:16
	v_pk_fma_f32 v[84:85], v[84:85], v[132:133], v[168:169]
	v_pk_fma_f32 v[82:83], v[82:83], v[130:131], v[166:167]
	v_pk_fma_f32 v[90:91], v[88:89], v[136:137], v[126:127]
	v_pk_fma_f32 v[88:89], v[86:87], v[134:135], v[124:125]
	v_add_co_u32_e32 v86, vcc, s45, v152
	v_pk_fma_f32 v[114:115], v[96:97], v[136:137], v[114:115]
	s_nop 0
	v_addc_co_u32_e32 v87, vcc, 0, v153, vcc
	global_store_dwordx4 v[86:87], v[82:85], off offset:16
	v_pk_fma_f32 v[76:77], v[76:77], v[132:133], v[176:177]
	v_pk_fma_f32 v[74:75], v[74:75], v[130:131], v[174:175]
	v_pk_fma_f32 v[82:83], v[80:81], v[136:137], v[172:173]
	v_pk_fma_f32 v[80:81], v[78:79], v[134:135], v[170:171]
	v_add_co_u32_e32 v78, vcc, s7, v152
	global_store_dwordx4 v[94:95], v[112:115], off
	s_nop 0
	v_addc_co_u32_e32 v79, vcc, 0, v153, vcc
	global_store_dwordx4 v[78:79], v[74:77], off offset:16
	global_store_dwordx4 v[86:87], v[88:91], off
	global_store_dwordx4 v[78:79], v[80:83], off
	v_add_co_u32_e32 v74, vcc, s10, v152
	s_waitcnt vmcnt(0)
	v_pk_fma_f32 v[72:73], v[72:73], v[136:137], v[180:181]
	v_pk_fma_f32 v[70:71], v[70:71], v[134:135], v[178:179]
	v_addc_co_u32_e32 v75, vcc, 0, v153, vcc
	v_pk_fma_f32 v[68:69], v[68:69], v[132:133], v[184:185]
	v_pk_fma_f32 v[66:67], v[66:67], v[130:131], v[182:183]
	global_store_dwordx4 v[74:75], v[70:73], off
	global_store_dwordx4 v[74:75], v[66:69], off offset:16
	s_mov_b64 s[10:11], 0x20200
	v_lshl_add_u64 v[76:77], v[150:151], 0, s[10:11]
	s_mov_b64 s[10:11], 0x40200
	global_load_dwordx4 v[80:83], v[150:151], off offset:512
	global_load_dwordx4 v[70:73], v[154:155], off offset:512
	global_load_dwordx4 v[66:69], v[154:155], off offset:528
	global_load_dwordx4 v[88:91], v[150:151], off offset:528
	global_load_dwordx4 v[112:115], v[156:157], off offset:512
	global_load_dwordx4 v[120:123], v[158:159], off offset:512
	global_load_dwordx4 v[124:127], v[76:77], off offset:16
	v_lshl_add_u64 v[76:77], v[150:151], 0, s[10:11]
	s_mov_b64 s[10:11], 0x60200
	global_load_dwordx4 v[128:131], v[76:77], off offset:16
	global_load_dwordx4 v[132:135], v[160:161], off offset:512
	v_lshl_add_u64 v[76:77], v[150:151], 0, s[10:11]
	global_load_dwordx4 v[154:157], v[76:77], off offset:16
	s_waitcnt vmcnt(0)
	v_pk_fma_f32 v[64:65], v[64:65], v[72:73], v[82:83]
	v_pk_fma_f32 v[62:63], v[62:63], v[70:71], v[80:81]
	v_pk_fma_f32 v[60:61], v[60:61], v[68:69], v[90:91]
	v_pk_fma_f32 v[58:59], v[58:59], v[66:67], v[88:89]
	v_pk_fma_f32 v[52:53], v[52:53], v[72:73], v[122:123]
	v_pk_fma_f32 v[50:51], v[50:51], v[70:71], v[120:121]
	v_pk_fma_f32 v[48:49], v[48:49], v[68:69], v[126:127]
	v_pk_fma_f32 v[46:47], v[46:47], v[66:67], v[124:125]
	v_pk_fma_f32 v[56:57], v[56:57], v[72:73], v[114:115]
	v_pk_fma_f32 v[54:55], v[54:55], v[70:71], v[112:113]
	global_store_dwordx4 v[152:153], v[62:65], off offset:512
	global_store_dwordx4 v[152:153], v[58:61], off offset:528
	global_store_dwordx4 v[118:119], v[54:57], off offset:512
	global_store_dwordx4 v[110:111], v[50:53], off offset:512
	v_pk_fma_f32 v[44:45], v[44:45], v[68:69], v[130:131]
	v_pk_fma_f32 v[42:43], v[42:43], v[66:67], v[128:129]
	v_pk_fma_f32 v[40:41], v[40:41], v[72:73], v[134:135]
	v_pk_fma_f32 v[38:39], v[38:39], v[70:71], v[132:133]
	v_pk_fma_f32 v[36:37], v[36:37], v[68:69], v[156:157]
	v_pk_fma_f32 v[34:35], v[34:35], v[66:67], v[154:155]
	global_store_dwordx4 v[118:119], v[46:49], off offset:528
	global_store_dwordx4 v[110:111], v[42:45], off offset:528
	global_store_dwordx4 v[102:103], v[38:41], off offset:512
	global_store_dwordx4 v[102:103], v[34:37], off offset:528
	s_mov_b64 s[10:11], 0x100200
	v_lshl_add_u64 v[50:51], v[150:151], 0, s[10:11]
	s_mov_b64 s[10:11], 0x120200
	v_lshl_add_u64 v[54:55], v[150:151], 0, s[10:11]
	s_mov_b64 s[10:11], 0x140200
	v_lshl_add_u64 v[58:59], v[150:151], 0, s[10:11]
	s_mov_b64 s[10:11], 0x160200
	global_load_dwordx4 v[34:37], v[98:99], off offset:512
	global_load_dwordx4 v[38:41], v[100:101], off offset:512
	global_load_dwordx4 v[42:45], v[104:105], off offset:512
	global_load_dwordx4 v[46:49], v[106:107], off offset:512
	v_lshl_add_u64 v[62:63], v[150:151], 0, s[10:11]
	global_load_dwordx4 v[50:53], v[50:51], off offset:16
	s_waitcnt vmcnt(0)
	v_pk_fma_f32 v[32:33], v[32:33], v[72:73], v[36:37]
	global_load_dwordx4 v[54:57], v[54:55], off offset:16
	v_pk_fma_f32 v[30:31], v[30:31], v[70:71], v[34:35]
	global_load_dwordx4 v[58:61], v[58:59], off offset:16
	v_pk_fma_f32 v[28:29], v[28:29], v[72:73], v[40:41]
	global_load_dwordx4 v[62:65], v[62:63], off offset:16
	v_pk_fma_f32 v[26:27], v[26:27], v[70:71], v[38:39]
	v_pk_fma_f32 v[24:25], v[24:25], v[72:73], v[44:45]
	v_pk_fma_f32 v[22:23], v[22:23], v[70:71], v[42:43]
	v_pk_fma_f32 v[12:13], v[12:13], v[72:73], v[48:49]
	v_pk_fma_f32 v[10:11], v[10:11], v[70:71], v[46:47]
	v_pk_fma_f32 v[20:21], v[20:21], v[68:69], v[52:53]
	v_pk_fma_f32 v[18:19], v[18:19], v[66:67], v[50:51]
	global_store_dwordx4 v[94:95], v[30:33], off offset:512
	global_store_dwordx4 v[86:87], v[26:29], off offset:512
	global_store_dwordx4 v[78:79], v[22:25], off offset:512
	global_store_dwordx4 v[74:75], v[10:13], off offset:512
	s_waitcnt vmcnt(0)
	v_pk_fma_f32 v[16:17], v[16:17], v[68:69], v[56:57]
	v_pk_fma_f32 v[14:15], v[14:15], v[66:67], v[54:55]
	v_pk_fma_f32 v[8:9], v[8:9], v[68:69], v[60:61]
	v_pk_fma_f32 v[6:7], v[6:7], v[66:67], v[58:59]
	v_pk_fma_f32 v[4:5], v[4:5], v[68:69], v[64:65]
	v_pk_fma_f32 v[2:3], v[2:3], v[66:67], v[62:63]
	global_store_dwordx4 v[94:95], v[18:21], off offset:528
	global_store_dwordx4 v[86:87], v[14:17], off offset:528
	global_store_dwordx4 v[78:79], v[6:9], off offset:528
	global_store_dwordx4 v[74:75], v[2:5], off offset:528
	s_and_b64 vcc, exec, s[0:1]
	s_mov_b32 s40, s6
	s_mov_b32 s28, s4
	s_mov_b64 s[54:55], s[34:35]
	s_mov_b64 s[52:53], s[8:9]
	s_cbranch_vccz .LBB0_501
	s_waitcnt vmcnt(0)
	v_readlane_b32 s28, v250, 12
	v_readlane_b32 s26, v250, 15
	s_cmpk_gt_u32 s12, 0xff
	v_readlane_b32 s29, v250, 13
	v_readlane_b32 s27, v250, 16
	s_mov_b32 s70, 0x800000
	v_readlane_b32 s79, v250, 18
	s_cbranch_scc1 .LBB0_508
	s_barrier
